# hazard-slot trimming: removed hipcc's conservative s_nop 0 after each inline v_max3 in the attention stage loops (110 sites)
# speedup vs baseline: 1.0045x; 1.0011x over previous
.LBB0_379:
	s_andn2_b64 vcc, exec, s[4:5]
	s_mov_b64 s[4:5], -1
	s_cbranch_vccnz .LBB0_371
	s_cmpk_gt_i32 s45, 0xff
	s_barrier
	s_cbranch_scc0 .LBB0_449
	s_cmpk_gt_u32 s45, 0x10ff
	s_cbranch_scc0 .LBB0_398
	s_add_i32 s0, s45, 0xffffef00
	s_lshr_b32 s2, s0, 6
	s_lshl_b32 s0, s45, 6
	s_and_b32 s0, s0, 0xc0
	s_lshl_b32 s10, s2, 8
	s_or_b32 s5, s10, s0
	s_bitset1_b32 s5, 14
	s_mul_i32 s1, s5, 0x3900
	s_mul_hi_u32 s0, s5, 0x3900
	s_add_u32 s1, s82, s1
	s_addc_u32 s0, s83, s0
	s_lshl_b32 s4, s45, 4
	s_and_b32 s8, s4, 0x3c0
	s_lshl_b32 s4, s8, 1
	s_add_u32 s1, s1, s4
	s_addc_u32 s6, s0, 0
	s_waitcnt vmcnt(9)
	v_mov_b32_e32 v68, v175
	s_add_u32 s0, s1, 0x1c00
	s_waitcnt vmcnt(6)
	v_mov_b32_e32 v26, v175
	s_addc_u32 s1, s6, 0
	v_mov_b64_e32 v[2:3], s[0:1]
	v_ashrrev_i32_e32 v0, 2, v26
	v_bfi_b32 v0, -16, v0, v26
	v_mad_i64_i32 v[2:3], s[0:1], v0, s92, v[2:3]
	v_and_b32_e32 v0, 48, v26
	v_ashrrev_i32_e32 v24, 3, v26
	s_add_u32 s6, s82, s4
	v_lshl_add_u64 v[2:3], v[2:3], 0, v[0:1]
	v_lshrrev_b32_e32 v0, 1, v24
	s_addc_u32 s7, s83, 0
	s_lshl_b32 s2, s2, 10
	v_xor_b32_e32 v0, v0, v26
	s_or_b32 s2, s2, s8
	v_lshlrev_b32_e32 v0, 4, v0
	s_mul_i32 s42, s2, 0x1100
	v_and_b32_e32 v29, 0x70, v0
	s_waitcnt vmcnt(5)
	v_add_u32_e32 v35, s10, v24
	v_lshlrev_b32_e32 v0, 3, v26
	s_lshl_b64 s[8:9], s[42:43], 1
	v_add_u32_e32 v74, 0x4000, v35
	v_mov_b64_e32 v[14:15], s[6:7]
	v_and_b32_e32 v0, 56, v0
	s_add_u32 s8, s35, s8
	v_mad_i64_i32 v[10:11], s[0:1], v74, s92, v[14:15]
	v_lshlrev_b32_e32 v0, 1, v0
	v_add_u32_e32 v16, 0x4020, v35
	s_addc_u32 s9, s36, s9
	v_lshl_add_u64 v[10:11], v[10:11], 0, v[0:1]
	v_mad_i64_i32 v[14:15], s[0:1], v16, s92, v[14:15]
	global_load_dwordx4 v[6:9], v[2:3], off
	s_nop 0
	global_load_dwordx4 v[2:5], v[2:3], off offset:64
	v_lshl_add_u64 v[14:15], v[14:15], 0, v[0:1]
	global_load_dwordx4 v[10:13], v[10:11], off
	v_mov_b64_e32 v[22:23], s[8:9]
	global_load_dwordx4 v[14:17], v[14:15], off
	v_mad_i64_i32 v[60:61], s[0:1], v24, s74, v[22:23]
	v_lshlrev_b32_e32 v34, 7, v24
	s_waitcnt vmcnt(7)
	v_lshl_add_u64 v[18:19], v[60:61], 0, v[0:1]
	v_add_u32_e32 v24, 32, v24
	v_add_co_u32_e32 v30, vcc, s94, v18
	s_waitcnt vmcnt(4)
	v_mad_i64_i32 v[62:63], s[0:1], v24, s74, v[22:23]
	v_addc_co_u32_e32 v31, vcc, 0, v19, vcc
	v_lshl_add_u64 v[22:23], v[62:63], 0, v[0:1]
	v_add_co_u32_e32 v32, vcc, s94, v22
	global_load_dwordx4 v[18:21], v[30:31], off
	s_nop 0
	v_addc_co_u32_e32 v33, vcc, 0, v23, vcc
	global_load_dwordx4 v[22:25], v[32:33], off
	v_or_b32_e32 v36, v29, v34
	v_add_u32_e32 v72, 0, v36
	v_and_b32_e32 v27, 63, v26
	v_bfe_u32 v28, v26, 4, 2
	v_lshl_add_u64 v[64:65], s[6:7], 0, v[0:1]
	v_and_b32_e32 v42, 15, v26
	v_lshl_add_u32 v47, v42, 7, 0
	v_mov_b32_e32 v59, 0xf149f2ca
	s_waitcnt vmcnt(3)
	ds_write_b128 v72, v[10:13]
	s_waitcnt vmcnt(2)
	ds_write_b128 v72, v[14:17] offset:4096
	v_add_u32_e32 v10, 0, v29
	v_add_u32_e32 v73, v10, v34
	v_lshrrev_b32_e32 v10, 1, v26
	v_bfe_u32 v11, v26, 1, 3
	v_lshlrev_b32_e32 v12, 2, v27
	v_bitop3_b32 v10, v28, v10, 7 bitop3:0x78
	v_xor_b32_e32 v69, 0x80, v12
	v_lshlrev_b32_e32 v12, 4, v10
	v_bitop3_b32 v10, v28, v11, 4 bitop3:0x36
	v_lshlrev_b32_e32 v46, 4, v10
	v_add_u32_e32 v10, 0x4040, v35
	v_mad_i64_i32 v[10:11], s[0:1], v10, s92, v[64:65]
	s_waitcnt vmcnt(1)
	ds_write_b128 v73, v[18:21] offset:8192
	s_waitcnt vmcnt(0)
	ds_write_b128 v73, v[22:25] offset:12288
	s_waitcnt lgkmcnt(0)
	s_barrier
	global_load_dwordx4 v[18:21], v[10:11], off
	v_add_u32_e32 v10, 0x4060, v35
	v_mad_i64_i32 v[10:11], s[0:1], v10, s92, v[64:65]
	global_load_dwordx4 v[26:29], v[10:11], off
	global_load_dwordx4 v[34:37], v[30:31], off offset:128
	global_load_dwordx4 v[38:41], v[32:33], off offset:128
	v_add_u32_e32 v70, v47, v12
	ds_read_b128 v[22:25], v70 offset:4096
	ds_read_b128 v[30:33], v70 offset:6144
	ds_read_b128 v[10:13], v70
	ds_read_b128 v[14:17], v70 offset:2048
	v_add_u32_e32 v71, v47, v46
	s_waitcnt lgkmcnt(2)
	v_mfma_f32_16x16x32_bf16 v[42:45], v[30:33], v[6:9], 0
	ds_read_b128 v[30:33], v71
	s_waitcnt lgkmcnt(2)
	v_mfma_f32_16x16x32_bf16 v[10:13], v[10:13], v[6:9], 0
	s_waitcnt lgkmcnt(0)
	v_mfma_f32_16x16x32_bf16 v[30:33], v[30:33], v[2:5], v[10:13]
	s_nop 5
	ds_read_b128 v[10:13], v71 offset:2048
	v_mfma_f32_16x16x32_bf16 v[14:17], v[14:17], v[6:9], 0
	s_waitcnt lgkmcnt(0)
	v_mfma_f32_16x16x32_bf16 v[14:17], v[10:13], v[2:5], v[14:17]
	ds_read_b128 v[10:13], v71 offset:4096
	v_mfma_f32_16x16x32_bf16 v[22:25], v[22:25], v[6:9], 0
	s_waitcnt lgkmcnt(0)
	v_mfma_f32_16x16x32_bf16 v[10:13], v[10:13], v[2:5], v[22:25]
	s_nop 5
	ds_read_b128 v[22:25], v71 offset:6144
	s_waitcnt lgkmcnt(0)
	v_mfma_f32_16x16x32_bf16 v[22:25], v[22:25], v[2:5], v[42:45]
	v_max3_f32 v42, v30, v31, v32
	v_max3_f32 v42, v42, v33, v14
	v_max3_f32 v42, v42, v15, v16
	v_max3_f32 v42, v42, v17, v10
	v_max3_f32 v42, v42, v11, v12
	v_max3_f32 v42, v42, v13, v22
	v_max3_f32 v42, v42, v23, v24
	v_max3_f32 v42, v42, v25, v25
	v_mul_f32_e32 v42, 0x3e38aa3b, v42
	v_cmp_gt_f32_e32 vcc, v42, v59
	s_cbranch_vccz .LBB0_389
	ds_swizzle_b32 v43, v42 offset:swizzle(SWAP,16)
	v_max_f32_e32 v42, v42, v42
	s_mov_b32 s0, 0xf149f2ca
	s_waitcnt lgkmcnt(0)
	v_max_f32_e32 v43, v43, v43
	v_max_f32_e32 v42, v42, v43
	ds_bpermute_b32 v43, v69, v42
	s_waitcnt lgkmcnt(0)
	v_max3_f32 v59, v42, v43, s0
	v_sub_f32_e32 v42, 0xf149f2ca, v59
	v_exp_f32_e32 v42, v42
	s_nop 0
	v_mul_f32_e32 v58, 0, v42
	s_branch .LBB0_390

.LBB0_390:
	v_fma_f32 v30, v30, s72, -v59
	v_fma_f32 v31, v31, s72, -v59
	v_exp_f32_e32 v30, v30
	v_exp_f32_e32 v31, v31
	v_fma_f32 v32, v32, s72, -v59
	v_fma_f32 v33, v33, s72, -v59
	v_exp_f32_e32 v32, v32
	v_exp_f32_e32 v33, v33
	v_fma_f32 v14, v14, s72, -v59
	v_fma_f32 v15, v15, s72, -v59
	v_exp_f32_e32 v14, v14
	v_exp_f32_e32 v15, v15
	v_fma_f32 v16, v16, s72, -v59
	v_fma_f32 v17, v17, s72, -v59
	v_exp_f32_e32 v16, v16
	v_exp_f32_e32 v17, v17
	v_fma_f32 v10, v10, s72, -v59
	v_fma_f32 v11, v11, s72, -v59
	v_pk_add_f32 v[42:43], v[30:31], 0 op_sel_hi:[1,0]
	v_exp_f32_e32 v10, v10
	v_exp_f32_e32 v11, v11
	v_fma_f32 v12, v12, s72, -v59
	v_fma_f32 v13, v13, s72, -v59
	v_fma_f32 v22, v22, s72, -v59
	v_pk_add_f32 v[42:43], v[32:33], v[42:43]
	v_exp_f32_e32 v12, v12
	v_exp_f32_e32 v13, v13
	v_exp_f32_e32 v44, v22
	v_fma_f32 v22, v23, s72, -v59
	v_pk_add_f32 v[42:43], v[14:15], v[42:43]
	v_exp_f32_e32 v45, v22
	v_pk_add_f32 v[42:43], v[16:17], v[42:43]
	v_fma_f32 v22, v24, s72, -v59
	v_pk_add_f32 v[42:43], v[10:11], v[42:43]
	v_exp_f32_e32 v46, v22
	v_pk_add_f32 v[42:43], v[12:13], v[42:43]
	v_fma_f32 v22, v25, s72, -v59
	v_exp_f32_e32 v47, v22
	v_pk_add_f32 v[22:23], v[44:45], v[42:43]
	v_cvt_pk_bf16_f32 v42, v10, v11
	v_cvt_pk_bf16_f32 v43, v12, v13
	ds_read_b128 v[10:13], v70 offset:8192
	v_cvt_pk_bf16_f32 v24, v14, v15
	v_cvt_pk_bf16_f32 v25, v16, v17
	ds_read_b128 v[14:17], v71 offset:8192
	v_pk_add_f32 v[22:23], v[46:47], v[22:23]
	v_cvt_pk_bf16_f32 v44, v44, v45
	v_pk_add_f32 v[66:67], v[22:23], v[22:23] op_sel:[0,1] op_sel_hi:[1,0]
	v_cvt_pk_bf16_f32 v22, v30, v31
	v_cvt_pk_bf16_f32 v23, v32, v33
	v_cvt_pk_bf16_f32 v45, v46, v47
	v_mov_b32_e32 v46, v58
	v_mov_b32_e32 v47, v58
	v_mov_b32_e32 v48, v58
	v_mov_b32_e32 v49, v58
	ds_read_b128 v[50:53], v71 offset:12288
	s_waitcnt lgkmcnt(2)
	v_mfma_f32_16x16x32_bf16 v[10:13], v[10:13], v[22:25], v[46:49]
	s_waitcnt lgkmcnt(1)
	v_mfma_f32_16x16x32_bf16 v[30:33], v[14:17], v[42:45], v[10:13]
	ds_read_b128 v[14:17], v71 offset:10240
	s_nop 4
	ds_read_b128 v[10:13], v70 offset:10240
	s_waitcnt lgkmcnt(0)
	v_mfma_f32_16x16x32_bf16 v[10:13], v[10:13], v[22:25], v[46:49]
	v_mfma_f32_16x16x32_bf16 v[14:17], v[14:17], v[42:45], v[10:13]
	s_nop 6
	ds_read_b128 v[10:13], v70 offset:12288
	s_waitcnt lgkmcnt(0)
	v_mfma_f32_16x16x32_bf16 v[10:13], v[10:13], v[22:25], v[46:49]
	v_mfma_f32_16x16x32_bf16 v[10:13], v[50:53], v[42:45], v[10:13]
	ds_read_b128 v[50:53], v70 offset:14336
	s_waitcnt lgkmcnt(0)
	v_mfma_f32_16x16x32_bf16 v[22:25], v[50:53], v[22:25], v[46:49]
	s_nop 2
	ds_read_b128 v[46:49], v71 offset:14336
	s_waitcnt vmcnt(3)
	ds_write_b128 v72, v[18:21] offset:16384
	s_waitcnt vmcnt(2)
	ds_write_b128 v72, v[26:29] offset:20480
	s_waitcnt vmcnt(1)
	ds_write_b128 v73, v[34:37] offset:24576
	s_waitcnt vmcnt(0)
	ds_write_b128 v73, v[38:41] offset:28672
	v_lshl_add_u64 v[34:35], v[60:61], 0, v[0:1]
	v_add_co_u32_e32 v34, vcc, s94, v34
	v_lshl_add_u64 v[38:39], v[62:63], 0, v[0:1]
	s_nop 0
	v_addc_co_u32_e32 v35, vcc, 0, v35, vcc
	v_add_u32_e32 v18, 0x80, v74
	v_add_u32_e32 v26, 0xa0, v74
	v_add_co_u32_e32 v38, vcc, s94, v38
	v_mad_i64_i32 v[18:19], s[0:1], v18, s92, v[64:65]
	v_mad_i64_i32 v[26:27], s[0:1], v26, s92, v[64:65]
	v_addc_co_u32_e32 v39, vcc, 0, v39, vcc
	s_waitcnt lgkmcnt(0)
	s_barrier
	global_load_dwordx4 v[18:21], v[18:19], off
	ds_read_b128 v[50:53], v70 offset:20480
	global_load_dwordx4 v[26:29], v[26:27], off
	s_waitcnt lgkmcnt(0)
	v_mfma_f32_16x16x32_bf16 v[54:57], v[50:53], v[6:9], 0
	global_load_dwordx4 v[34:37], v[34:35], off offset:256
	ds_read_b128 v[50:53], v70 offset:22528
	global_load_dwordx4 v[38:41], v[38:39], off offset:256
	v_mfma_f32_16x16x32_bf16 v[22:25], v[46:49], v[42:45], v[22:25]
	ds_read_b128 v[42:45], v70 offset:16384
	ds_read_b128 v[46:49], v70 offset:18432
	s_waitcnt lgkmcnt(2)
	v_mfma_f32_16x16x32_bf16 v[76:79], v[50:53], v[6:9], 0
	ds_read_b128 v[50:53], v71 offset:16384
	s_waitcnt lgkmcnt(2)
	v_mfma_f32_16x16x32_bf16 v[42:45], v[42:45], v[6:9], 0
	s_waitcnt lgkmcnt(0)
	v_mfma_f32_16x16x32_bf16 v[50:53], v[50:53], v[2:5], v[42:45]
	v_max3_f32 v67, v50, v51, v52
	s_nop 5
	ds_read_b128 v[42:45], v71 offset:18432
	v_mfma_f32_16x16x32_bf16 v[46:49], v[46:49], v[6:9], 0
	s_waitcnt lgkmcnt(0)
	v_mfma_f32_16x16x32_bf16 v[46:49], v[42:45], v[2:5], v[46:49]
	ds_read_b128 v[42:45], v71 offset:20480
	v_max3_f32 v67, v67, v53, v46
	s_waitcnt lgkmcnt(0)
	v_mfma_f32_16x16x32_bf16 v[42:45], v[42:45], v[2:5], v[54:57]
	s_nop 2
	ds_read_b128 v[54:57], v71 offset:22528
	v_max3_f32 v67, v67, v47, v48
	v_max3_f32 v67, v67, v49, v42
	s_waitcnt lgkmcnt(0)
	v_mfma_f32_16x16x32_bf16 v[54:57], v[54:57], v[2:5], v[76:79]
	v_max3_f32 v67, v67, v43, v44
	v_max3_f32 v67, v67, v45, v54
	v_max3_f32 v67, v67, v55, v56
	v_max3_f32 v67, v67, v57, v57
	v_mul_f32_e32 v75, 0x3e38aa3b, v67
	v_mov_b32_e32 v67, v219
	v_pk_add_f32 v[66:67], v[58:59], v[66:67]
	s_nop 0
	v_cmp_gt_f32_e32 vcc, v75, v67
	s_cbranch_vccz .LBB0_392
	ds_swizzle_b32 v58, v75 offset:swizzle(SWAP,16)
	v_max_f32_e32 v75, v75, v75
	s_waitcnt lgkmcnt(0)
	v_max_f32_e32 v58, v58, v58
	v_max_f32_e32 v58, v75, v58
	ds_bpermute_b32 v75, v69, v58
	s_waitcnt lgkmcnt(0)
	v_max3_f32 v75, v59, v58, v75
	v_sub_f32_e32 v58, v59, v75
	v_exp_f32_e32 v76, v58
	v_xor_b32_e32 v58, 0x80000000, v75
	v_mov_b32_e32 v59, v75
	v_pk_mul_f32 v[66:67], v[66:67], v[76:77]
	v_pk_mul_f32 v[24:25], v[24:25], v[76:77] op_sel_hi:[1,0]
	v_pk_mul_f32 v[22:23], v[22:23], v[76:77] op_sel_hi:[1,0]
	v_pk_mul_f32 v[12:13], v[12:13], v[76:77] op_sel_hi:[1,0]
	v_pk_mul_f32 v[10:11], v[10:11], v[76:77] op_sel_hi:[1,0]
	v_pk_mul_f32 v[16:17], v[16:17], v[76:77] op_sel_hi:[1,0]
	v_pk_mul_f32 v[14:15], v[14:15], v[76:77] op_sel_hi:[1,0]
	v_pk_mul_f32 v[32:33], v[32:33], v[76:77] op_sel_hi:[1,0]
	v_pk_mul_f32 v[30:31], v[30:31], v[76:77] op_sel_hi:[1,0]
	v_add_f32_e32 v67, 0x41000000, v75
	s_branch .LBB0_393

.LBB0_393:
	v_fmamk_f32 v50, v50, 0x3e38aa3b, v58
	v_fmamk_f32 v51, v51, 0x3e38aa3b, v58
	v_exp_f32_e32 v50, v50
	v_exp_f32_e32 v51, v51
	v_fmamk_f32 v52, v52, 0x3e38aa3b, v58
	v_fmamk_f32 v53, v53, 0x3e38aa3b, v58
	v_exp_f32_e32 v52, v52
	v_exp_f32_e32 v53, v53
	v_fmamk_f32 v46, v46, 0x3e38aa3b, v58
	v_fmamk_f32 v47, v47, 0x3e38aa3b, v58
	v_exp_f32_e32 v46, v46
	v_exp_f32_e32 v47, v47
	v_fmamk_f32 v48, v48, 0x3e38aa3b, v58
	v_fmamk_f32 v49, v49, 0x3e38aa3b, v58
	v_exp_f32_e32 v48, v48
	v_exp_f32_e32 v49, v49
	v_fmamk_f32 v42, v42, 0x3e38aa3b, v58
	v_fmamk_f32 v43, v43, 0x3e38aa3b, v58
	v_fmamk_f32 v54, v54, 0x3e38aa3b, v58
	v_pk_add_f32 v[76:77], v[50:51], 0 op_sel_hi:[1,0]
	v_exp_f32_e32 v42, v42
	v_exp_f32_e32 v43, v43
	v_fmamk_f32 v44, v44, 0x3e38aa3b, v58
	v_fmamk_f32 v45, v45, 0x3e38aa3b, v58
	v_exp_f32_e32 v78, v54
	v_fmamk_f32 v54, v55, 0x3e38aa3b, v58
	v_pk_add_f32 v[76:77], v[52:53], v[76:77]
	v_exp_f32_e32 v44, v44
	v_exp_f32_e32 v45, v45
	v_exp_f32_e32 v79, v54
	v_fmamk_f32 v54, v56, 0x3e38aa3b, v58
	v_pk_add_f32 v[76:77], v[46:47], v[76:77]
	v_exp_f32_e32 v80, v54
	v_fmamk_f32 v54, v57, 0x3e38aa3b, v58
	v_pk_add_f32 v[76:77], v[48:49], v[76:77]
	v_exp_f32_e32 v81, v54
	v_pk_add_f32 v[76:77], v[42:43], v[76:77]
	v_cvt_pk_bf16_f32 v50, v50, v51
	v_pk_add_f32 v[76:77], v[44:45], v[76:77]
	v_cvt_pk_bf16_f32 v51, v52, v53
	v_pk_add_f32 v[54:55], v[78:79], v[76:77]
	v_cvt_pk_bf16_f32 v52, v46, v47
	v_pk_add_f32 v[54:55], v[80:81], v[54:55]
	v_cvt_pk_bf16_f32 v53, v48, v49
	v_add_f32_e32 v54, v54, v55
	v_add_f32_e32 v66, v66, v54
	v_cvt_pk_bf16_f32 v54, v42, v43
	v_cvt_pk_bf16_f32 v55, v44, v45
	ds_read_b128 v[42:45], v70 offset:24576
	s_waitcnt lgkmcnt(0)
	v_mfma_f32_16x16x32_bf16 v[30:33], v[42:45], v[50:53], v[30:33]
	ds_read_b128 v[42:45], v71 offset:24576
	v_cvt_pk_bf16_f32 v56, v78, v79
	v_cvt_pk_bf16_f32 v57, v80, v81
	s_waitcnt lgkmcnt(0)
	s_nop 0
	v_mfma_f32_16x16x32_bf16 v[46:49], v[42:45], v[54:57], v[30:33]
	s_nop 2
	ds_read_b128 v[30:33], v70 offset:26624
	s_waitcnt lgkmcnt(0)
	v_mfma_f32_16x16x32_bf16 v[14:17], v[30:33], v[50:53], v[14:17]
	ds_read_b128 v[30:33], v71 offset:26624
	s_waitcnt lgkmcnt(0)
	v_mfma_f32_16x16x32_bf16 v[42:45], v[30:33], v[54:57], v[14:17]
	s_nop 4
	ds_read_b128 v[14:17], v70 offset:28672
	s_waitcnt lgkmcnt(0)
	v_mfma_f32_16x16x32_bf16 v[10:13], v[14:17], v[50:53], v[10:13]
	ds_read_b128 v[14:17], v71 offset:28672
	s_waitcnt lgkmcnt(0)
	v_mfma_f32_16x16x32_bf16 v[14:17], v[14:17], v[54:57], v[10:13]
	s_nop 4
	ds_read_b128 v[10:13], v70 offset:30720
	s_waitcnt lgkmcnt(0)
	v_mfma_f32_16x16x32_bf16 v[10:13], v[10:13], v[50:53], v[22:25]
	s_nop 2
	ds_read_b128 v[22:25], v71 offset:30720
	s_waitcnt vmcnt(3)
	ds_write_b128 v72, v[18:21]
	s_waitcnt vmcnt(2)
	ds_write_b128 v72, v[26:29] offset:4096
	s_waitcnt vmcnt(1)
	ds_write_b128 v73, v[34:37] offset:8192
	s_waitcnt vmcnt(0)
	ds_write_b128 v73, v[38:41] offset:12288
	s_waitcnt lgkmcnt(0)
	v_mfma_f32_16x16x32_bf16 v[30:33], v[22:25], v[54:57], v[10:13]
	s_nop 2
	v_add_u32_e32 v10, 0xc0, v74
	v_mad_i64_i32 v[10:11], s[0:1], v10, s92, v[64:65]
	s_barrier
	global_load_dwordx4 v[26:29], v[10:11], off
	v_add_u32_e32 v10, 0xe0, v74
	v_mad_i64_i32 v[10:11], s[0:1], v10, s92, v[64:65]
	global_load_dwordx4 v[34:37], v[10:11], off
	v_lshl_add_u64 v[10:11], v[60:61], 0, v[0:1]
	v_add_co_u32_e32 v10, vcc, s94, v10
	ds_read_b128 v[22:25], v70 offset:4096
	s_nop 0
	v_addc_co_u32_e32 v11, vcc, 0, v11, vcc
	global_load_dwordx4 v[38:41], v[10:11], off offset:384
	v_lshl_add_u64 v[10:11], v[62:63], 0, v[0:1]
	v_add_co_u32_e32 v10, vcc, s94, v10
	s_waitcnt lgkmcnt(0)
	v_mfma_f32_16x16x32_bf16 v[54:57], v[22:25], v[6:9], 0
	v_addc_co_u32_e32 v11, vcc, 0, v11, vcc
	global_load_dwordx4 v[50:53], v[10:11], off offset:384
	ds_read_b128 v[22:25], v70 offset:6144
	ds_read_b128 v[10:13], v70
	ds_read_b128 v[18:21], v70 offset:2048
	s_waitcnt lgkmcnt(2)
	v_mfma_f32_16x16x32_bf16 v[60:63], v[22:25], v[6:9], 0
	ds_read_b128 v[22:25], v71
	s_waitcnt lgkmcnt(2)
	v_mfma_f32_16x16x32_bf16 v[10:13], v[10:13], v[6:9], 0
	s_waitcnt lgkmcnt(0)
	v_mfma_f32_16x16x32_bf16 v[22:25], v[22:25], v[2:5], v[10:13]
	v_max3_f32 v0, v22, v23, v24
	s_nop 5
	ds_read_b128 v[10:13], v71 offset:2048
	v_mfma_f32_16x16x32_bf16 v[18:21], v[18:21], v[6:9], 0
	s_waitcnt lgkmcnt(0)
	v_mfma_f32_16x16x32_bf16 v[10:13], v[10:13], v[2:5], v[18:21]
	s_nop 5
	ds_read_b128 v[18:21], v71 offset:4096
	v_max3_f32 v0, v0, v25, v10
	s_waitcnt lgkmcnt(0)
	v_mfma_f32_16x16x32_bf16 v[18:21], v[18:21], v[2:5], v[54:57]
	s_nop 2
	ds_read_b128 v[54:57], v71 offset:6144
	v_max3_f32 v0, v0, v11, v12
	v_max3_f32 v0, v0, v13, v18
	s_waitcnt lgkmcnt(0)
	v_mfma_f32_16x16x32_bf16 v[54:57], v[54:57], v[2:5], v[60:63]
	v_max3_f32 v0, v0, v19, v20
	v_max3_f32 v0, v0, v21, v54
	v_max3_f32 v0, v0, v55, v56
	v_max3_f32 v0, v0, v57, v57
	v_mul_f32_e32 v0, 0x3e38aa3b, v0
	v_cmp_gt_f32_e32 vcc, v0, v67
	s_cbranch_vccz .LBB0_395
	ds_swizzle_b32 v58, v0 offset:swizzle(SWAP,16)
	v_max_f32_e32 v0, v0, v0
	s_waitcnt lgkmcnt(0)
	v_max_f32_e32 v58, v58, v58
	v_max_f32_e32 v0, v0, v58
	ds_bpermute_b32 v58, v69, v0
	s_waitcnt lgkmcnt(0)
	v_max3_f32 v60, v59, v0, v58
	v_sub_f32_e32 v0, v59, v60
	v_exp_f32_e32 v0, v0
	v_xor_b32_e32 v58, 0x80000000, v60
	v_add_f32_e32 v67, 0x41000000, v60
	v_mov_b32_e32 v59, v60
	v_mul_f32_e32 v66, v66, v0
	v_pk_mul_f32 v[32:33], v[32:33], v[0:1] op_sel_hi:[1,0]
	v_pk_mul_f32 v[30:31], v[30:31], v[0:1] op_sel_hi:[1,0]
	v_pk_mul_f32 v[16:17], v[16:17], v[0:1] op_sel_hi:[1,0]
	v_pk_mul_f32 v[14:15], v[14:15], v[0:1] op_sel_hi:[1,0]
	v_pk_mul_f32 v[44:45], v[44:45], v[0:1] op_sel_hi:[1,0]
	v_pk_mul_f32 v[42:43], v[42:43], v[0:1] op_sel_hi:[1,0]
	v_pk_mul_f32 v[48:49], v[48:49], v[0:1] op_sel_hi:[1,0]
	v_pk_mul_f32 v[46:47], v[46:47], v[0:1] op_sel_hi:[1,0]
.LBB0_395:
	v_fmamk_f32 v0, v22, 0x3e38aa3b, v58
	v_exp_f32_e32 v22, v0
	v_fmamk_f32 v0, v23, 0x3e38aa3b, v58
	v_exp_f32_e32 v23, v0
	v_fmamk_f32 v0, v24, 0x3e38aa3b, v58
	v_exp_f32_e32 v24, v0
	v_fmamk_f32 v0, v25, 0x3e38aa3b, v58
	v_exp_f32_e32 v25, v0
	v_fmamk_f32 v0, v10, 0x3e38aa3b, v58
	v_exp_f32_e32 v10, v0
	v_fmamk_f32 v0, v11, 0x3e38aa3b, v58
	v_exp_f32_e32 v11, v0
	v_fmamk_f32 v0, v12, 0x3e38aa3b, v58
	v_exp_f32_e32 v12, v0
	v_fmamk_f32 v0, v13, 0x3e38aa3b, v58
	v_exp_f32_e32 v13, v0
	v_fmamk_f32 v0, v18, 0x3e38aa3b, v58
	v_exp_f32_e32 v62, v0
	v_fmamk_f32 v0, v19, 0x3e38aa3b, v58
	v_pk_add_f32 v[60:61], v[22:23], 0 op_sel_hi:[1,0]
	v_exp_f32_e32 v63, v0
	v_pk_add_f32 v[60:61], v[24:25], v[60:61]
	v_fmamk_f32 v0, v20, 0x3e38aa3b, v58
	v_pk_add_f32 v[60:61], v[10:11], v[60:61]
	v_exp_f32_e32 v64, v0
	v_fmamk_f32 v0, v21, 0x3e38aa3b, v58
	v_pk_add_f32 v[60:61], v[12:13], v[60:61]
	v_exp_f32_e32 v65, v0
	v_fmamk_f32 v0, v54, 0x3e38aa3b, v58
	v_pk_add_f32 v[18:19], v[62:63], v[60:61]
	v_exp_f32_e32 v60, v0
	v_fmamk_f32 v0, v55, 0x3e38aa3b, v58
	v_exp_f32_e32 v61, v0
	v_fmamk_f32 v0, v56, 0x3e38aa3b, v58
	v_exp_f32_e32 v74, v0
	v_fmamk_f32 v0, v57, 0x3e38aa3b, v58
	v_exp_f32_e32 v75, v0
	v_cvt_pk_bf16_f32 v20, v10, v11
	v_cvt_pk_bf16_f32 v21, v12, v13
	ds_read_b128 v[10:13], v70 offset:8192
	v_pk_add_f32 v[18:19], v[64:65], v[18:19]
	v_cvt_pk_bf16_f32 v54, v62, v63
	v_pk_add_f32 v[18:19], v[60:61], v[18:19]
	v_cvt_pk_bf16_f32 v55, v64, v65
	v_pk_add_f32 v[18:19], v[74:75], v[18:19]
	v_cvt_pk_bf16_f32 v56, v60, v61
	v_add_f32_e32 v0, v18, v19
	v_cvt_pk_bf16_f32 v18, v22, v23
	v_cvt_pk_bf16_f32 v19, v24, v25
	ds_read_b128 v[22:25], v71 offset:8192
	v_cvt_pk_bf16_f32 v57, v74, v75
	s_waitcnt lgkmcnt(1)
	v_mfma_f32_16x16x32_bf16 v[10:13], v[10:13], v[18:21], v[46:49]
	v_add_f32_e32 v0, v66, v0
	s_waitcnt lgkmcnt(0)
	v_mfma_f32_16x16x32_bf16 v[10:13], v[22:25], v[54:57], v[10:13]
	ds_read_b128 v[22:25], v70 offset:10240
	s_waitcnt lgkmcnt(0)
	v_mfma_f32_16x16x32_bf16 v[22:25], v[22:25], v[18:21], v[42:45]
	s_nop 2
	ds_read_b128 v[42:45], v71 offset:10240
	s_waitcnt lgkmcnt(0)
	v_mfma_f32_16x16x32_bf16 v[22:25], v[42:45], v[54:57], v[22:25]
	ds_read_b128 v[42:45], v70 offset:12288
	s_waitcnt lgkmcnt(0)
	v_mfma_f32_16x16x32_bf16 v[14:17], v[42:45], v[18:21], v[14:17]
	ds_read_b128 v[42:45], v71 offset:12288
	s_waitcnt lgkmcnt(0)
	v_mfma_f32_16x16x32_bf16 v[14:17], v[42:45], v[54:57], v[14:17]
	ds_read_b128 v[42:45], v70 offset:14336
	s_waitcnt lgkmcnt(0)
	v_mfma_f32_16x16x32_bf16 v[18:21], v[42:45], v[18:21], v[30:33]
	s_nop 2
	ds_read_b128 v[30:33], v71 offset:14336
	s_waitcnt vmcnt(3)
	ds_write_b128 v72, v[26:29] offset:16384
	s_waitcnt vmcnt(2)
	ds_write_b128 v72, v[34:37] offset:20480
	s_waitcnt vmcnt(1)
	ds_write_b128 v73, v[38:41] offset:24576
	s_waitcnt vmcnt(0)
	ds_write_b128 v73, v[50:53] offset:28672
	s_waitcnt lgkmcnt(0)
	v_mfma_f32_16x16x32_bf16 v[18:21], v[30:33], v[54:57], v[18:21]
	s_barrier
	ds_read_b128 v[26:29], v70 offset:16384
	ds_read_b128 v[30:33], v70 offset:18432
	ds_read_b128 v[34:37], v70 offset:20480
	ds_read_b128 v[38:41], v70 offset:22528
	s_waitcnt lgkmcnt(3)
	v_mfma_f32_16x16x32_bf16 v[26:29], v[26:29], v[6:9], 0
	s_waitcnt lgkmcnt(2)
	v_mfma_f32_16x16x32_bf16 v[30:33], v[30:33], v[6:9], 0
	s_waitcnt lgkmcnt(1)
	v_mfma_f32_16x16x32_bf16 v[34:37], v[34:37], v[6:9], 0
	s_waitcnt lgkmcnt(0)
	v_mfma_f32_16x16x32_bf16 v[38:41], v[38:41], v[6:9], 0
	ds_read_b128 v[6:9], v71 offset:16384
	s_waitcnt lgkmcnt(0)
	v_mfma_f32_16x16x32_bf16 v[6:9], v[6:9], v[2:5], v[26:29]
	s_nop 2
	ds_read_b128 v[26:29], v71 offset:18432
	s_waitcnt lgkmcnt(0)
	v_mfma_f32_16x16x32_bf16 v[26:29], v[26:29], v[2:5], v[30:33]
	s_nop 2
	ds_read_b128 v[30:33], v71 offset:20480
	s_waitcnt lgkmcnt(0)
	v_mfma_f32_16x16x32_bf16 v[30:33], v[30:33], v[2:5], v[34:37]
	s_nop 2
	ds_read_b128 v[34:37], v71 offset:22528
	s_waitcnt lgkmcnt(0)
	v_mfma_f32_16x16x32_bf16 v[2:5], v[34:37], v[2:5], v[38:41]
	v_max3_f32 v34, v6, v7, v8
	v_max3_f32 v34, v34, v9, v26
	v_max3_f32 v34, v34, v27, v28
	v_max3_f32 v34, v34, v29, v30
	v_max3_f32 v34, v34, v31, v32
	v_max3_f32 v34, v34, v33, v2
	v_max3_f32 v34, v34, v3, v4
	v_max3_f32 v34, v34, v5, v5
	v_mul_f32_e32 v34, 0x3e38aa3b, v34
	v_cmp_gt_f32_e32 vcc, v34, v67
	s_cbranch_vccz .LBB0_397
	ds_swizzle_b32 v35, v34 offset:swizzle(SWAP,16)
	v_max_f32_e32 v34, v34, v34
	s_waitcnt lgkmcnt(0)
	v_max_f32_e32 v35, v35, v35
	v_max_f32_e32 v34, v34, v35
	ds_bpermute_b32 v35, v69, v34
	s_waitcnt lgkmcnt(0)
	v_min3_f32 v58, -v59, -v34, -v35
	v_add_f32_e32 v34, v59, v58
	v_exp_f32_e32 v34, v34
	s_nop 0
	v_mul_f32_e32 v0, v0, v34
	v_pk_mul_f32 v[20:21], v[20:21], v[34:35] op_sel_hi:[1,0]
	v_pk_mul_f32 v[18:19], v[18:19], v[34:35] op_sel_hi:[1,0]
	v_pk_mul_f32 v[16:17], v[16:17], v[34:35] op_sel_hi:[1,0]
	v_pk_mul_f32 v[14:15], v[14:15], v[34:35] op_sel_hi:[1,0]
	v_pk_mul_f32 v[24:25], v[24:25], v[34:35] op_sel_hi:[1,0]
	v_pk_mul_f32 v[22:23], v[22:23], v[34:35] op_sel_hi:[1,0]
	v_pk_mul_f32 v[12:13], v[12:13], v[34:35] op_sel_hi:[1,0]
	v_pk_mul_f32 v[10:11], v[10:11], v[34:35] op_sel_hi:[1,0]

.LBB0_430:
	v_max3_f32 v94, v54, v55, v56
	v_add_f32_e32 v95, 0x41000000, v71
	v_max3_f32 v94, v94, v57, v50
	v_max3_f32 v94, v94, v51, v52
	v_max3_f32 v94, v94, v53, v46
	v_max3_f32 v94, v94, v47, v48
	v_max3_f32 v94, v94, v49, v42
	v_max3_f32 v94, v94, v43, v44
	v_max3_f32 v94, v94, v45, v45
	v_cmp_gt_f32_e32 vcc, v94, v95
	s_cbranch_vccz .LBB0_432
	ds_swizzle_b32 v95, v94 offset:swizzle(SWAP,16)
	v_max_f32_e32 v94, v94, v94
	s_waitcnt lgkmcnt(0)
	v_max_f32_e32 v95, v95, v95
	v_max_f32_e32 v94, v94, v95
	ds_bpermute_b32 v95, v59, v94
	s_waitcnt lgkmcnt(0)
	v_max3_f32 v95, v71, v94, v95
	v_sub_f32_e32 v71, v71, v95
	v_exp_f32_e32 v94, v71
	v_mov_b32_e32 v71, v95
	v_mul_f32_e32 v68, v68, v94
	v_pk_mul_f32 v[16:17], v[16:17], v[94:95] op_sel_hi:[1,0]
	v_pk_mul_f32 v[14:15], v[14:15], v[94:95] op_sel_hi:[1,0]
	v_pk_mul_f32 v[12:13], v[12:13], v[94:95] op_sel_hi:[1,0]
	v_pk_mul_f32 v[10:11], v[10:11], v[94:95] op_sel_hi:[1,0]
	v_pk_mul_f32 v[8:9], v[8:9], v[94:95] op_sel_hi:[1,0]
	v_pk_mul_f32 v[6:7], v[6:7], v[94:95] op_sel_hi:[1,0]
	v_pk_mul_f32 v[4:5], v[4:5], v[94:95] op_sel_hi:[1,0]
	v_pk_mul_f32 v[2:3], v[2:3], v[94:95] op_sel_hi:[1,0]

.LBB0_490:
	v_add_u32_e32 v0, v76, v73
	s_waitcnt lgkmcnt(0)
	s_barrier
	ds_read_b128 v[26:29], v0 offset:16384
	ds_read_b128 v[30:33], v0 offset:18432
	ds_read_b128 v[36:39], v0 offset:20480
	ds_read_b128 v[40:43], v0 offset:22528
	v_readlane_b32 s89, v255, 12
	v_readlane_b32 s34, v255, 15
	s_waitcnt lgkmcnt(2)
	v_mfma_f32_16x16x32_bf16 v[32:35], v[30:33], v[22:25], 0
	v_add_u32_e32 v30, v76, v70
	v_readlane_b32 s88, v255, 35
	s_mov_b32 s38, s86
	v_mfma_f32_16x16x32_bf16 v[26:29], v[26:29], v[22:25], 0
	s_waitcnt lgkmcnt(1)
	v_mfma_f32_16x16x32_bf16 v[36:39], v[36:39], v[22:25], 0
	s_waitcnt lgkmcnt(0)
	v_mfma_f32_16x16x32_bf16 v[22:25], v[40:43], v[22:25], 0
	ds_read_b128 v[40:43], v30 offset:16384
	s_waitcnt lgkmcnt(0)
	v_mfma_f32_16x16x32_bf16 v[40:43], v[40:43], v[18:21], v[26:29]
	s_nop 2
	ds_read_b128 v[26:29], v30 offset:18432
	s_waitcnt lgkmcnt(0)
	v_mfma_f32_16x16x32_bf16 v[44:47], v[26:29], v[18:21], v[32:35]
	ds_read_b128 v[26:29], v30 offset:20480
	s_nop 1
	v_mul_f32_e32 v33, 0x3e38aa3b, v41
	s_nop 3
	v_mul_f32_e32 v31, 0x3e38aa3b, v44
	s_waitcnt lgkmcnt(0)
	v_mfma_f32_16x16x32_bf16 v[36:39], v[26:29], v[18:21], v[36:39]
	ds_read_b128 v[26:29], v30 offset:22528
	v_mul_f32_e32 v34, 0x3e38aa3b, v47
	s_nop 5
	v_mul_f32_e32 v32, 0x3e38aa3b, v38
	s_waitcnt lgkmcnt(0)
	v_mfma_f32_16x16x32_bf16 v[48:51], v[26:29], v[18:21], v[22:25]
	s_nop 2
	v_mul_f32_e32 v23, 0x3e38aa3b, v40
	v_mul_f32_e32 v29, 0x3e38aa3b, v42
	v_max3_f32 v35, v23, v33, v29
	v_mul_f32_e32 v26, 0x3e38aa3b, v43
	v_max3_f32 v35, v35, v26, v31
	v_mul_f32_e32 v27, 0x3e38aa3b, v45
	v_mul_f32_e32 v24, 0x3e38aa3b, v46
	v_max3_f32 v35, v35, v27, v24
	v_mul_f32_e32 v25, 0x3e38aa3b, v36
	v_max3_f32 v35, v35, v34, v25
	v_mul_f32_e32 v22, 0x3e38aa3b, v37
	v_max3_f32 v35, v35, v22, v32
	v_mul_f32_e32 v28, 0x3e38aa3b, v39
	v_mul_f32_e32 v21, 0x3e38aa3b, v48
	v_max3_f32 v35, v35, v28, v21
	v_mul_f32_e32 v20, 0x3e38aa3b, v49
	v_mul_f32_e32 v19, 0x3e38aa3b, v50
	v_max3_f32 v35, v35, v20, v19
	v_add_f32_e32 v36, 0x41000000, v71
	v_mul_f32_e32 v18, 0x3e38aa3b, v51
	v_max3_f32 v35, v35, v18, v18
	v_cmp_gt_f32_e32 vcc, v35, v36
	s_cbranch_vccz .LBB0_492
	ds_swizzle_b32 v36, v35 offset:swizzle(SWAP,16)
	v_max_f32_e32 v35, v35, v35
	s_waitcnt lgkmcnt(0)
	v_max_f32_e32 v36, v36, v36
	v_max_f32_e32 v35, v35, v36
	ds_bpermute_b32 v36, v59, v35
	s_waitcnt lgkmcnt(0)
	v_max3_f32 v35, v71, v35, v36
	v_sub_f32_e32 v36, v71, v35
	v_exp_f32_e32 v36, v36
	v_mov_b32_e32 v71, v35
	v_mul_f32_e32 v68, v68, v36
	v_pk_mul_f32 v[16:17], v[16:17], v[36:37] op_sel_hi:[1,0]
	v_pk_mul_f32 v[14:15], v[14:15], v[36:37] op_sel_hi:[1,0]
	v_pk_mul_f32 v[12:13], v[12:13], v[36:37] op_sel_hi:[1,0]
	v_pk_mul_f32 v[10:11], v[10:11], v[36:37] op_sel_hi:[1,0]
	v_pk_mul_f32 v[8:9], v[8:9], v[36:37] op_sel_hi:[1,0]
	v_pk_mul_f32 v[6:7], v[6:7], v[36:37] op_sel_hi:[1,0]
	v_pk_mul_f32 v[4:5], v[4:5], v[36:37] op_sel_hi:[1,0]
	v_pk_mul_f32 v[2:3], v[2:3], v[36:37] op_sel_hi:[1,0]

.LBB0_534:
	s_bitcmp1_b32 s19, 0
	s_cselect_b32 s0, 0x6000, 0
	s_add_i32 s0, s0, 0
	v_add3_u32 v108, s0, v153, v154
	s_waitcnt lgkmcnt(0)
	s_barrier
	ds_read_b128 v[84:87], v108
	ds_read_b128 v[88:91], v108 offset:2048
	v_add3_u32 v114, s0, v151, v154
	s_waitcnt vmcnt(3) lgkmcnt(1)
	v_mfma_f32_16x16x32_bf16 v[92:95], v[84:87], v[12:15], 0
	ds_read_b128 v[100:103], v114
	ds_read_b128 v[104:107], v114 offset:2048
	v_subrev_u32_e32 v2, 32, v144
	v_ashrrev_i32_e32 v3, 31, v2
	s_waitcnt vmcnt(1)
	v_mfma_f32_16x16x32_bf16 v[84:87], v[84:87], v[16:19], 0
	v_ashrrev_i32_e32 v145, 31, v144
	v_lshlrev_b64 v[2:3], 14, v[2:3]
	v_lshl_add_u64 v[2:3], v[140:141], 0, v[2:3]
	s_waitcnt lgkmcnt(2)
	v_mfma_f32_16x16x32_bf16 v[96:99], v[88:91], v[12:15], 0
	v_mfma_f32_16x16x32_bf16 v[88:91], v[88:91], v[16:19], 0
	s_waitcnt lgkmcnt(1)
	v_mfma_f32_16x16x32_bf16 v[136:139], v[100:103], v[4:7], v[92:95]
	s_nop 2
	ds_read_b128 v[92:95], v108 offset:4096
	s_waitcnt vmcnt(0)
	v_mfma_f32_16x16x32_bf16 v[124:127], v[100:103], v[8:11], v[84:87]
	s_nop 2
	v_lshlrev_b64 v[84:85], 14, v[144:145]
	s_waitcnt lgkmcnt(1)
	v_mfma_f32_16x16x32_bf16 v[128:131], v[104:107], v[8:11], v[88:91]
	s_nop 2
	v_lshl_add_u64 v[88:89], v[140:141], 0, v[84:85]
	v_mfma_f32_16x16x32_bf16 v[132:135], v[104:107], v[4:7], v[96:99]
	s_nop 2
	ds_read_b128 v[96:99], v108 offset:6144
	global_load_dwordx4 v[84:87], v[2:3], off
	s_nop 0
	global_load_dwordx4 v[88:91], v[88:89], off
	ds_read_b128 v[108:111], v114 offset:4096
	v_lshl_add_u64 v[2:3], v[142:143], 0, s[26:27]
	s_waitcnt lgkmcnt(2)
	v_mfma_f32_16x16x32_bf16 v[100:103], v[92:95], v[12:15], 0
	v_mfma_f32_16x16x32_bf16 v[104:107], v[92:95], v[16:19], 0
	v_add_co_u32_e32 v92, vcc, s64, v2
	s_nop 1
	v_addc_co_u32_e32 v93, vcc, 0, v3, vcc
	v_add_co_u32_e32 v112, vcc, s65, v2
	s_waitcnt lgkmcnt(0)
	v_mfma_f32_16x16x32_bf16 v[120:123], v[108:111], v[4:7], v[100:103]
	v_addc_co_u32_e32 v113, vcc, 0, v3, vcc
	s_nop 1
	v_add_co_u32_e32 v100, vcc, s67, v2
	v_mfma_f32_16x16x32_bf16 v[116:119], v[96:99], v[12:15], 0
	s_nop 0
	v_addc_co_u32_e32 v101, vcc, 0, v3, vcc
	v_add_co_u32_e32 v2, vcc, s68, v2
	v_mfma_f32_16x16x32_bf16 v[158:161], v[96:99], v[16:19], 0
	global_load_dwordx4 v[92:95], v[92:93], off offset:128
	s_nop 0
	global_load_dwordx4 v[96:99], v[112:113], off offset:128
	ds_read_b128 v[162:165], v114 offset:6144
	v_addc_co_u32_e32 v3, vcc, 0, v3, vcc
	v_mfma_f32_16x16x32_bf16 v[112:115], v[108:111], v[8:11], v[104:107]
	global_load_dwordx4 v[100:103], v[100:101], off offset:128
	s_nop 1
	global_load_dwordx4 v[104:107], v[2:3], off offset:128
	v_max3_f32 v2, v136, v137, v138
	v_add_f32_e32 v3, 0x41000000, v146
	v_max3_f32 v2, v2, v139, v132
	s_waitcnt lgkmcnt(0)
	v_mfma_f32_16x16x32_bf16 v[116:119], v[162:165], v[4:7], v[116:119]
	v_max3_f32 v2, v2, v133, v134
	v_max3_f32 v2, v2, v135, v135
	v_mfma_f32_16x16x32_bf16 v[108:111], v[162:165], v[8:11], v[158:161]
	v_mul_f32_e32 v2, 0x3e38aa3b, v2
	v_cmp_gt_f32_e32 vcc, v2, v3
	s_cbranch_vccz .LBB0_536
	ds_swizzle_b32 v3, v2 offset:swizzle(SWAP,16)
	v_max_f32_e32 v2, v2, v2
	s_waitcnt lgkmcnt(0)
	v_max_f32_e32 v3, v3, v3
	v_max_f32_e32 v2, v2, v3
	ds_bpermute_b32 v3, v150, v2
	s_waitcnt lgkmcnt(0)
	v_max3_f32 v2, v146, v2, v3
	v_sub_f32_e32 v3, v146, v2
	v_exp_f32_e32 v146, v3
	v_mov_b32_e32 v3, v147
	v_mul_f32_e32 v0, v0, v146
	v_pk_mul_f32 v[82:83], v[82:83], v[146:147] op_sel_hi:[1,0]
	v_pk_mul_f32 v[80:81], v[80:81], v[146:147] op_sel_hi:[1,0]
	v_pk_mul_f32 v[74:75], v[74:75], v[146:147] op_sel_hi:[1,0]
	v_pk_mul_f32 v[72:73], v[72:73], v[146:147] op_sel_hi:[1,0]
	v_pk_mul_f32 v[66:67], v[66:67], v[146:147] op_sel_hi:[1,0]
	v_pk_mul_f32 v[64:65], v[64:65], v[146:147] op_sel_hi:[1,0]
	v_pk_mul_f32 v[58:59], v[58:59], v[146:147] op_sel_hi:[1,0]
	v_pk_mul_f32 v[56:57], v[56:57], v[146:147] op_sel_hi:[1,0]
	v_pk_mul_f32 v[50:51], v[50:51], v[146:147] op_sel_hi:[1,0]
	v_pk_mul_f32 v[48:49], v[48:49], v[146:147] op_sel_hi:[1,0]
	v_pk_mul_f32 v[38:39], v[38:39], v[146:147] op_sel_hi:[1,0]
	v_pk_mul_f32 v[36:37], v[36:37], v[146:147] op_sel_hi:[1,0]
	v_pk_mul_f32 v[34:35], v[34:35], v[146:147] op_sel_hi:[1,0]
	v_pk_mul_f32 v[32:33], v[32:33], v[146:147] op_sel_hi:[1,0]
	v_pk_mul_f32 v[42:43], v[42:43], v[146:147] op_sel_hi:[1,0]
	v_pk_mul_f32 v[40:41], v[40:41], v[146:147] op_sel_hi:[1,0]
	v_mov_b32_e32 v146, v2
	s_branch .LBB0_537

.LBB0_537:
	v_max3_f32 v145, v124, v125, v126
	v_add_f32_e32 v147, 0x41000000, v3
	v_max3_f32 v145, v145, v127, v128
	v_max3_f32 v145, v145, v129, v130
	v_max3_f32 v145, v145, v131, v131
	v_mul_f32_e32 v145, 0x3e38aa3b, v145
	v_cmp_gt_f32_e32 vcc, v145, v147
	s_cbranch_vccz .LBB0_539
	ds_swizzle_b32 v147, v145 offset:swizzle(SWAP,16)
	v_max_f32_e32 v145, v145, v145
	s_waitcnt lgkmcnt(0)
	v_max_f32_e32 v147, v147, v147
	v_max_f32_e32 v145, v145, v147
	ds_bpermute_b32 v147, v150, v145
	s_waitcnt lgkmcnt(0)
	v_max3_f32 v147, v3, v145, v147
	v_sub_f32_e32 v3, v3, v147
	v_exp_f32_e32 v148, v3
	v_mov_b32_e32 v3, v147
	v_mov_b32_e32 v145, v2
	v_mul_f32_e32 v152, v152, v148
	v_pk_mul_f32 v[78:79], v[78:79], v[148:149] op_sel_hi:[1,0]
	v_pk_mul_f32 v[76:77], v[76:77], v[148:149] op_sel_hi:[1,0]
	v_pk_mul_f32 v[70:71], v[70:71], v[148:149] op_sel_hi:[1,0]
	v_pk_mul_f32 v[68:69], v[68:69], v[148:149] op_sel_hi:[1,0]
	v_pk_mul_f32 v[62:63], v[62:63], v[148:149] op_sel_hi:[1,0]
	v_pk_mul_f32 v[60:61], v[60:61], v[148:149] op_sel_hi:[1,0]
	v_pk_mul_f32 v[54:55], v[54:55], v[148:149] op_sel_hi:[1,0]
	v_pk_mul_f32 v[52:53], v[52:53], v[148:149] op_sel_hi:[1,0]
	v_pk_mul_f32 v[46:47], v[46:47], v[148:149] op_sel_hi:[1,0]
	v_pk_mul_f32 v[44:45], v[44:45], v[148:149] op_sel_hi:[1,0]
	v_pk_mul_f32 v[30:31], v[30:31], v[148:149] op_sel_hi:[1,0]
	v_pk_mul_f32 v[28:29], v[28:29], v[148:149] op_sel_hi:[1,0]
	v_pk_mul_f32 v[26:27], v[26:27], v[148:149] op_sel_hi:[1,0]
	v_pk_mul_f32 v[24:25], v[24:25], v[148:149] op_sel_hi:[1,0]
	v_pk_mul_f32 v[22:23], v[22:23], v[148:149] op_sel_hi:[1,0]
	v_pk_mul_f32 v[20:21], v[20:21], v[148:149] op_sel_hi:[1,0]
	s_branch .LBB0_540

.LBB0_540:
	v_mov_b64_e32 v[148:149], v[2:3]
	v_fma_f32 v2, v136, s72, -v146
	v_exp_f32_e32 v136, v2
	v_fma_f32 v2, v137, s72, -v146
	v_exp_f32_e32 v137, v2
	v_fma_f32 v2, v138, s72, -v146
	v_exp_f32_e32 v138, v2
	v_fma_f32 v2, v139, s72, -v146
	v_exp_f32_e32 v139, v2
	v_fma_f32 v2, v132, s72, -v146
	v_exp_f32_e32 v160, v2
	v_fma_f32 v2, v133, s72, -v146
	v_exp_f32_e32 v161, v2
	v_fma_f32 v2, v134, s72, -v146
	v_exp_f32_e32 v162, v2
	v_fma_f32 v2, v135, s72, -v146
	v_exp_f32_e32 v163, v2
	v_pk_add_f32 v[158:159], v[136:137], 0 op_sel_hi:[1,0]
	v_cvt_pk_bf16_f32 v134, v160, v161
	v_pk_add_f32 v[158:159], v[138:139], v[158:159]
	v_fma_f32 v124, v124, s72, -v3
	v_pk_add_f32 v[132:133], v[160:161], v[158:159]
	v_fma_f32 v125, v125, s72, -v3
	v_pk_add_f32 v[132:133], v[162:163], v[132:133]
	v_fma_f32 v126, v126, s72, -v3
	v_add_f32_e32 v2, v132, v133
	v_add_f32_e32 v0, v0, v2
	v_add_u32_e32 v2, s0, v154
	v_add_u32_e32 v146, v2, v153
	ds_read_b128 v[158:161], v146 offset:8192
	v_fma_f32 v127, v127, s72, -v3
	v_fma_f32 v128, v128, s72, -v3
	v_fma_f32 v129, v129, s72, -v3
	v_fma_f32 v130, v130, s72, -v3
	v_fma_f32 v131, v131, s72, -v3
	v_exp_f32_e32 v124, v124
	v_exp_f32_e32 v125, v125
	v_exp_f32_e32 v126, v126
	v_exp_f32_e32 v127, v127
	v_exp_f32_e32 v128, v128
	v_exp_f32_e32 v129, v129
	v_exp_f32_e32 v130, v130
	v_exp_f32_e32 v131, v131
	v_cvt_pk_bf16_f32 v132, v136, v137
	v_cvt_pk_bf16_f32 v133, v138, v139
	v_cvt_pk_bf16_f32 v135, v162, v163
	v_cvt_pk_bf16_f32 v136, v124, v125
	v_cvt_pk_bf16_f32 v137, v126, v127
	v_cvt_pk_bf16_f32 v138, v128, v129
	v_cvt_pk_bf16_f32 v139, v130, v131
	s_waitcnt lgkmcnt(0)
	v_mfma_f32_16x16x32_bf16 v[80:83], v[158:161], v[132:135], v[80:83]
	v_mfma_f32_16x16x32_bf16 v[76:79], v[158:161], v[136:139], v[76:79]
	ds_read_b128 v[158:161], v146 offset:10240
	s_waitcnt lgkmcnt(0)
	v_mfma_f32_16x16x32_bf16 v[72:75], v[158:161], v[132:135], v[72:75]
	v_mfma_f32_16x16x32_bf16 v[68:71], v[158:161], v[136:139], v[68:71]
	ds_read_b128 v[158:161], v146 offset:12288
	s_waitcnt lgkmcnt(0)
	v_mfma_f32_16x16x32_bf16 v[64:67], v[158:161], v[132:135], v[64:67]
	v_mfma_f32_16x16x32_bf16 v[60:63], v[158:161], v[136:139], v[60:63]
	ds_read_b128 v[158:161], v146 offset:14336
	s_waitcnt lgkmcnt(0)
	v_mfma_f32_16x16x32_bf16 v[56:59], v[158:161], v[132:135], v[56:59]
	v_mfma_f32_16x16x32_bf16 v[52:55], v[158:161], v[136:139], v[52:55]
	ds_read_b128 v[158:161], v146 offset:16384
	s_waitcnt lgkmcnt(0)
	v_mfma_f32_16x16x32_bf16 v[48:51], v[158:161], v[132:135], v[48:51]
	v_mfma_f32_16x16x32_bf16 v[44:47], v[158:161], v[136:139], v[44:47]
	ds_read_b128 v[158:161], v146 offset:18432
	s_waitcnt lgkmcnt(0)
	v_mfma_f32_16x16x32_bf16 v[36:39], v[158:161], v[132:135], v[36:39]
	v_mfma_f32_16x16x32_bf16 v[28:31], v[158:161], v[136:139], v[28:31]
	ds_read_b128 v[158:161], v146 offset:20480
	s_waitcnt lgkmcnt(0)
	v_mfma_f32_16x16x32_bf16 v[32:35], v[158:161], v[132:135], v[32:35]
	v_mfma_f32_16x16x32_bf16 v[24:27], v[158:161], v[136:139], v[24:27]
	ds_read_b128 v[158:161], v146 offset:22528
	s_waitcnt lgkmcnt(0)
	v_mfma_f32_16x16x32_bf16 v[40:43], v[158:161], v[132:135], v[40:43]
	v_max3_f32 v132, v120, v121, v122
	v_add_f32_e32 v133, 0x41000000, v145
	v_max3_f32 v132, v132, v123, v116
	v_mfma_f32_16x16x32_bf16 v[20:23], v[158:161], v[136:139], v[20:23]
	v_max3_f32 v132, v132, v117, v118
	v_max3_f32 v132, v132, v119, v119
	v_mul_f32_e32 v132, 0x3e38aa3b, v132
	v_cmp_gt_f32_e32 vcc, v132, v133
	s_cbranch_vccz .LBB0_542
	ds_swizzle_b32 v3, v132 offset:swizzle(SWAP,16)
	v_max_f32_e32 v132, v132, v132
	s_waitcnt lgkmcnt(0)
	v_max_f32_e32 v3, v3, v3
	v_max_f32_e32 v3, v132, v3
	ds_bpermute_b32 v132, v150, v3
	s_waitcnt lgkmcnt(0)
	v_max3_f32 v148, v145, v3, v132
	v_sub_f32_e32 v3, v145, v148
	v_exp_f32_e32 v132, v3
	v_mov_b32_e32 v3, v149
	v_mov_b32_e32 v145, v148
	v_mul_f32_e32 v0, v0, v132
	v_pk_mul_f32 v[82:83], v[82:83], v[132:133] op_sel_hi:[1,0]
	v_pk_mul_f32 v[80:81], v[80:81], v[132:133] op_sel_hi:[1,0]
	v_pk_mul_f32 v[74:75], v[74:75], v[132:133] op_sel_hi:[1,0]
	v_pk_mul_f32 v[72:73], v[72:73], v[132:133] op_sel_hi:[1,0]
	v_pk_mul_f32 v[66:67], v[66:67], v[132:133] op_sel_hi:[1,0]
	v_pk_mul_f32 v[64:65], v[64:65], v[132:133] op_sel_hi:[1,0]
	v_pk_mul_f32 v[58:59], v[58:59], v[132:133] op_sel_hi:[1,0]
	v_pk_mul_f32 v[56:57], v[56:57], v[132:133] op_sel_hi:[1,0]
	v_pk_mul_f32 v[50:51], v[50:51], v[132:133] op_sel_hi:[1,0]
	v_pk_mul_f32 v[48:49], v[48:49], v[132:133] op_sel_hi:[1,0]
	v_pk_mul_f32 v[38:39], v[38:39], v[132:133] op_sel_hi:[1,0]
	v_pk_mul_f32 v[36:37], v[36:37], v[132:133] op_sel_hi:[1,0]
	v_pk_mul_f32 v[34:35], v[34:35], v[132:133] op_sel_hi:[1,0]
	v_pk_mul_f32 v[32:33], v[32:33], v[132:133] op_sel_hi:[1,0]
	v_pk_mul_f32 v[42:43], v[42:43], v[132:133] op_sel_hi:[1,0]
	v_pk_mul_f32 v[40:41], v[40:41], v[132:133] op_sel_hi:[1,0]
.LBB0_542:
	v_pk_add_f32 v[124:125], v[124:125], 0 op_sel_hi:[1,0]
	s_nop 0
	v_pk_add_f32 v[124:125], v[126:127], v[124:125]
	v_add_f32_e32 v126, 0x41000000, v3
	v_pk_add_f32 v[124:125], v[128:129], v[124:125]
	s_nop 0
	v_pk_add_f32 v[124:125], v[130:131], v[124:125]
	s_nop 0
	v_add_f32_e32 v124, v124, v125
	v_max3_f32 v125, v112, v113, v114
	v_add_f32_e32 v124, v152, v124
	v_max3_f32 v125, v125, v115, v108
	v_max3_f32 v125, v125, v109, v110
	v_max3_f32 v125, v125, v111, v111
	v_mul_f32_e32 v125, 0x3e38aa3b, v125
	v_cmp_gt_f32_e32 vcc, v125, v126
	s_cbranch_vccz .LBB0_533
	ds_swizzle_b32 v126, v125 offset:swizzle(SWAP,16)
	v_max_f32_e32 v125, v125, v125
	s_waitcnt lgkmcnt(0)
	v_max_f32_e32 v126, v126, v126
	v_max_f32_e32 v125, v125, v126
	ds_bpermute_b32 v126, v150, v125
	s_waitcnt lgkmcnt(0)
	v_max3_f32 v149, v3, v125, v126
	v_sub_f32_e32 v3, v3, v149
	v_exp_f32_e32 v126, v3
	v_mov_b32_e32 v3, v149
	v_mul_f32_e32 v124, v124, v126
	v_pk_mul_f32 v[78:79], v[78:79], v[126:127] op_sel_hi:[1,0]
	v_pk_mul_f32 v[76:77], v[76:77], v[126:127] op_sel_hi:[1,0]
	v_pk_mul_f32 v[70:71], v[70:71], v[126:127] op_sel_hi:[1,0]
	v_pk_mul_f32 v[68:69], v[68:69], v[126:127] op_sel_hi:[1,0]
	v_pk_mul_f32 v[62:63], v[62:63], v[126:127] op_sel_hi:[1,0]
	v_pk_mul_f32 v[60:61], v[60:61], v[126:127] op_sel_hi:[1,0]
	v_pk_mul_f32 v[54:55], v[54:55], v[126:127] op_sel_hi:[1,0]
	v_pk_mul_f32 v[52:53], v[52:53], v[126:127] op_sel_hi:[1,0]
	v_pk_mul_f32 v[46:47], v[46:47], v[126:127] op_sel_hi:[1,0]
	v_pk_mul_f32 v[44:45], v[44:45], v[126:127] op_sel_hi:[1,0]
	v_pk_mul_f32 v[30:31], v[30:31], v[126:127] op_sel_hi:[1,0]
	v_pk_mul_f32 v[28:29], v[28:29], v[126:127] op_sel_hi:[1,0]
	v_pk_mul_f32 v[26:27], v[26:27], v[126:127] op_sel_hi:[1,0]
	v_pk_mul_f32 v[24:25], v[24:25], v[126:127] op_sel_hi:[1,0]
	v_pk_mul_f32 v[22:23], v[22:23], v[126:127] op_sel_hi:[1,0]
	v_pk_mul_f32 v[20:21], v[20:21], v[126:127] op_sel_hi:[1,0]
	s_branch .LBB0_533
.LBB0_544:
	v_add3_u32 v2, s0, v153, v154
	s_waitcnt lgkmcnt(0)
	s_barrier
	ds_read_b128 v[84:87], v2
	ds_read_b128 v[92:95], v2 offset:2048
	v_add3_u32 v116, s0, v151, v154
	ds_read_b128 v[100:103], v116
	s_waitcnt lgkmcnt(2)
	v_mfma_f32_16x16x32_bf16 v[88:91], v[84:87], v[12:15], 0
	v_mfma_f32_16x16x32_bf16 v[84:87], v[84:87], v[16:19], 0
	s_waitcnt lgkmcnt(0)
	v_mfma_f32_16x16x32_bf16 v[112:115], v[100:103], v[4:7], v[88:91]
	v_mfma_f32_16x16x32_bf16 v[100:103], v[100:103], v[8:11], v[84:87]
	s_nop 4
	ds_read_b128 v[84:87], v116 offset:2048
	v_mfma_f32_16x16x32_bf16 v[96:99], v[92:95], v[12:15], 0
	v_mfma_f32_16x16x32_bf16 v[92:95], v[92:95], v[16:19], 0
	s_waitcnt lgkmcnt(0)
	v_mfma_f32_16x16x32_bf16 v[108:111], v[84:87], v[4:7], v[96:99]
	v_mfma_f32_16x16x32_bf16 v[104:107], v[84:87], v[8:11], v[92:95]
	ds_read_b128 v[84:87], v2 offset:4096
	s_nop 3
	ds_read_b128 v[92:95], v2 offset:6144
	s_waitcnt lgkmcnt(1)
	v_mfma_f32_16x16x32_bf16 v[88:91], v[84:87], v[12:15], 0
	v_max3_f32 v2, v112, v113, v114
	v_max3_f32 v2, v2, v115, v108
	v_mfma_f32_16x16x32_bf16 v[84:87], v[84:87], v[16:19], 0
	v_max3_f32 v2, v2, v109, v110
	v_max3_f32 v2, v2, v111, v111
	s_waitcnt lgkmcnt(0)
	v_mfma_f32_16x16x32_bf16 v[12:15], v[92:95], v[12:15], 0
	v_mul_f32_e32 v2, 0x3e38aa3b, v2
	v_mfma_f32_16x16x32_bf16 v[16:19], v[92:95], v[16:19], 0
	ds_read_b128 v[92:95], v116 offset:4096
	s_waitcnt lgkmcnt(0)
	v_mfma_f32_16x16x32_bf16 v[96:99], v[92:95], v[4:7], v[88:91]
	v_mfma_f32_16x16x32_bf16 v[88:91], v[92:95], v[8:11], v[84:87]
	s_nop 2
	ds_read_b128 v[84:87], v116 offset:6144
	s_waitcnt lgkmcnt(0)
	v_mfma_f32_16x16x32_bf16 v[92:95], v[84:87], v[4:7], v[12:15]
	v_add_f32_e32 v4, 0x41000000, v146
	v_cmp_gt_f32_e32 vcc, v2, v4
	v_mfma_f32_16x16x32_bf16 v[84:87], v[84:87], v[8:11], v[16:19]
	s_cbranch_vccz .LBB0_546
	ds_swizzle_b32 v3, v2 offset:swizzle(SWAP,16)
	v_max_f32_e32 v2, v2, v2
	v_mov_b32_e32 v117, v147
	s_waitcnt lgkmcnt(0)
	v_max_f32_e32 v3, v3, v3
	v_max_f32_e32 v2, v2, v3
	ds_bpermute_b32 v3, v150, v2
	s_waitcnt lgkmcnt(0)
	v_max3_f32 v116, v146, v2, v3
	v_sub_f32_e32 v2, v146, v116
	v_exp_f32_e32 v2, v2
	v_mov_b32_e32 v146, v116
	v_mul_f32_e32 v0, v0, v2
	v_pk_mul_f32 v[82:83], v[82:83], v[2:3] op_sel_hi:[1,0]
	v_pk_mul_f32 v[80:81], v[80:81], v[2:3] op_sel_hi:[1,0]
	v_pk_mul_f32 v[74:75], v[74:75], v[2:3] op_sel_hi:[1,0]
	v_pk_mul_f32 v[72:73], v[72:73], v[2:3] op_sel_hi:[1,0]
	v_pk_mul_f32 v[66:67], v[66:67], v[2:3] op_sel_hi:[1,0]
	v_pk_mul_f32 v[64:65], v[64:65], v[2:3] op_sel_hi:[1,0]
	v_pk_mul_f32 v[58:59], v[58:59], v[2:3] op_sel_hi:[1,0]
	v_pk_mul_f32 v[56:57], v[56:57], v[2:3] op_sel_hi:[1,0]
	v_pk_mul_f32 v[50:51], v[50:51], v[2:3] op_sel_hi:[1,0]
	v_pk_mul_f32 v[48:49], v[48:49], v[2:3] op_sel_hi:[1,0]
	v_pk_mul_f32 v[38:39], v[38:39], v[2:3] op_sel_hi:[1,0]
	v_pk_mul_f32 v[36:37], v[36:37], v[2:3] op_sel_hi:[1,0]
	v_pk_mul_f32 v[34:35], v[34:35], v[2:3] op_sel_hi:[1,0]
	v_pk_mul_f32 v[32:33], v[32:33], v[2:3] op_sel_hi:[1,0]
	v_pk_mul_f32 v[42:43], v[42:43], v[2:3] op_sel_hi:[1,0]
	v_pk_mul_f32 v[40:41], v[40:41], v[2:3] op_sel_hi:[1,0]
	v_mov_b32_e32 v3, v147
	s_branch .LBB0_547

.LBB0_547:
	v_max3_f32 v2, v100, v101, v102
	v_add_f32_e32 v4, 0x41000000, v3
	v_max3_f32 v2, v2, v103, v104
	v_max3_f32 v2, v2, v105, v106
	v_max3_f32 v2, v2, v107, v107
	v_mul_f32_e32 v2, 0x3e38aa3b, v2
	v_cmp_gt_f32_e32 vcc, v2, v4
	s_cbranch_vccz .LBB0_549
	ds_swizzle_b32 v4, v2 offset:swizzle(SWAP,16)
	v_max_f32_e32 v2, v2, v2
	s_waitcnt lgkmcnt(0)
	v_max_f32_e32 v4, v4, v4
	v_max_f32_e32 v2, v2, v4
	ds_bpermute_b32 v4, v150, v2
	s_waitcnt lgkmcnt(0)
	v_max3_f32 v117, v3, v2, v4
	v_sub_f32_e32 v2, v3, v117
	v_exp_f32_e32 v2, v2
	s_nop 0
	v_mul_f32_e32 v152, v152, v2
	v_pk_mul_f32 v[78:79], v[78:79], v[2:3] op_sel_hi:[1,0]
	v_pk_mul_f32 v[76:77], v[76:77], v[2:3] op_sel_hi:[1,0]
	v_pk_mul_f32 v[70:71], v[70:71], v[2:3] op_sel_hi:[1,0]
	v_pk_mul_f32 v[68:69], v[68:69], v[2:3] op_sel_hi:[1,0]
	v_pk_mul_f32 v[62:63], v[62:63], v[2:3] op_sel_hi:[1,0]
	v_pk_mul_f32 v[60:61], v[60:61], v[2:3] op_sel_hi:[1,0]
	v_pk_mul_f32 v[54:55], v[54:55], v[2:3] op_sel_hi:[1,0]
	v_pk_mul_f32 v[52:53], v[52:53], v[2:3] op_sel_hi:[1,0]
	v_pk_mul_f32 v[46:47], v[46:47], v[2:3] op_sel_hi:[1,0]
	v_pk_mul_f32 v[44:45], v[44:45], v[2:3] op_sel_hi:[1,0]
	v_pk_mul_f32 v[30:31], v[30:31], v[2:3] op_sel_hi:[1,0]
	v_pk_mul_f32 v[28:29], v[28:29], v[2:3] op_sel_hi:[1,0]
	v_pk_mul_f32 v[26:27], v[26:27], v[2:3] op_sel_hi:[1,0]
	v_pk_mul_f32 v[24:25], v[24:25], v[2:3] op_sel_hi:[1,0]
	v_pk_mul_f32 v[22:23], v[22:23], v[2:3] op_sel_hi:[1,0]
	v_pk_mul_f32 v[20:21], v[20:21], v[2:3] op_sel_hi:[1,0]
	v_mov_b32_e32 v3, v117
	s_branch .LBB0_550

.LBB0_550:
	v_fma_f32 v2, v112, s72, -v146
	v_exp_f32_e32 v4, v2
	v_fma_f32 v2, v113, s72, -v146
	v_exp_f32_e32 v5, v2
	v_fma_f32 v2, v114, s72, -v146
	v_exp_f32_e32 v6, v2
	v_fma_f32 v2, v115, s72, -v146
	v_exp_f32_e32 v7, v2
	v_fma_f32 v2, v108, s72, -v146
	v_exp_f32_e32 v10, v2
	v_fma_f32 v2, v109, s72, -v146
	v_exp_f32_e32 v11, v2
	v_fma_f32 v2, v110, s72, -v146
	v_exp_f32_e32 v16, v2
	v_fma_f32 v2, v111, s72, -v146
	v_pk_add_f32 v[8:9], v[4:5], 0 op_sel_hi:[1,0]
	v_exp_f32_e32 v17, v2
	v_cvt_pk_bf16_f32 v12, v4, v5
	v_fma_f32 v4, v100, s72, -v3
	v_exp_f32_e32 v108, v4
	v_fma_f32 v4, v101, s72, -v3
	v_pk_add_f32 v[8:9], v[6:7], v[8:9]
	v_exp_f32_e32 v109, v4
	v_fma_f32 v4, v102, s72, -v3
	v_pk_add_f32 v[8:9], v[10:11], v[8:9]
	v_exp_f32_e32 v110, v4
	v_fma_f32 v4, v103, s72, -v3
	v_pk_add_f32 v[8:9], v[16:17], v[8:9]
	v_exp_f32_e32 v111, v4
	v_fma_f32 v4, v104, s72, -v3
	v_add_f32_e32 v2, v8, v9
	v_exp_f32_e32 v104, v4
	v_fma_f32 v4, v105, s72, -v3
	v_add_f32_e32 v2, v0, v2
	v_add_u32_e32 v0, s0, v154
	v_exp_f32_e32 v105, v4
	v_fma_f32 v4, v106, s72, -v3
	v_exp_f32_e32 v106, v4
	v_fma_f32 v4, v107, s72, -v3
	v_add_u32_e32 v112, v0, v153
	v_cvt_pk_bf16_f32 v13, v6, v7
	v_exp_f32_e32 v107, v4
	ds_read_b128 v[4:7], v112 offset:8192
	v_cvt_pk_bf16_f32 v14, v10, v11
	v_cvt_pk_bf16_f32 v15, v16, v17
	v_cvt_pk_bf16_f32 v16, v108, v109
	v_cvt_pk_bf16_f32 v17, v110, v111
	v_cvt_pk_bf16_f32 v18, v104, v105
	v_cvt_pk_bf16_f32 v19, v106, v107
	s_waitcnt lgkmcnt(0)
	v_mfma_f32_16x16x32_bf16 v[80:83], v[4:7], v[12:15], v[80:83]
	v_mfma_f32_16x16x32_bf16 v[76:79], v[4:7], v[16:19], v[76:79]
	ds_read_b128 v[4:7], v112 offset:10240
	s_waitcnt lgkmcnt(0)
	v_mfma_f32_16x16x32_bf16 v[72:75], v[4:7], v[12:15], v[72:75]
	v_mfma_f32_16x16x32_bf16 v[68:71], v[4:7], v[16:19], v[68:71]
	ds_read_b128 v[4:7], v112 offset:12288
	s_waitcnt lgkmcnt(0)
	v_mfma_f32_16x16x32_bf16 v[64:67], v[4:7], v[12:15], v[64:67]
	v_mfma_f32_16x16x32_bf16 v[60:63], v[4:7], v[16:19], v[60:63]
	ds_read_b128 v[4:7], v112 offset:14336
	s_waitcnt lgkmcnt(0)
	v_mfma_f32_16x16x32_bf16 v[56:59], v[4:7], v[12:15], v[56:59]
	v_mfma_f32_16x16x32_bf16 v[100:103], v[4:7], v[16:19], v[52:55]
	ds_read_b128 v[4:7], v112 offset:16384
	s_waitcnt lgkmcnt(0)
	v_mfma_f32_16x16x32_bf16 v[48:51], v[4:7], v[12:15], v[48:51]
	v_mfma_f32_16x16x32_bf16 v[52:55], v[4:7], v[16:19], v[44:47]
	ds_read_b128 v[4:7], v112 offset:18432
	s_waitcnt lgkmcnt(0)
	v_mfma_f32_16x16x32_bf16 v[36:39], v[4:7], v[12:15], v[36:39]
	v_mfma_f32_16x16x32_bf16 v[44:47], v[4:7], v[16:19], v[28:31]
	ds_read_b128 v[4:7], v112 offset:20480
	s_waitcnt lgkmcnt(0)
	v_mfma_f32_16x16x32_bf16 v[8:11], v[4:7], v[12:15], v[32:35]
	v_mfma_f32_16x16x32_bf16 v[4:7], v[4:7], v[16:19], v[24:27]
	s_nop 2
	ds_read_b128 v[24:27], v112 offset:22528
	s_waitcnt lgkmcnt(0)
	v_mfma_f32_16x16x32_bf16 v[16:19], v[24:27], v[16:19], v[20:23]
	v_max3_f32 v20, v96, v97, v98
	s_nop 2
	v_add_f32_e32 v21, 0x41000000, v116
	v_max3_f32 v20, v20, v99, v92
	v_mfma_f32_16x16x32_bf16 v[12:15], v[24:27], v[12:15], v[40:43]
	v_max3_f32 v20, v20, v93, v94
	v_max3_f32 v20, v20, v95, v95
	v_mul_f32_e32 v20, 0x3e38aa3b, v20
	v_cmp_gt_f32_e32 vcc, v20, v21
	s_cbranch_vccz .LBB0_552
	ds_swizzle_b32 v3, v20 offset:swizzle(SWAP,16)
	v_max_f32_e32 v20, v20, v20
	s_waitcnt lgkmcnt(0)
	v_max_f32_e32 v3, v3, v3
	v_max_f32_e32 v3, v20, v3
	ds_bpermute_b32 v20, v150, v3
	s_waitcnt lgkmcnt(0)
	v_max3_f32 v21, v116, v3, v20
	v_sub_f32_e32 v3, v116, v21
	v_exp_f32_e32 v20, v3
	v_mov_b32_e32 v3, v117
	v_mov_b32_e32 v116, v21
	v_mul_f32_e32 v2, v2, v20
	v_pk_mul_f32 v[82:83], v[82:83], v[20:21] op_sel_hi:[1,0]
	v_pk_mul_f32 v[80:81], v[80:81], v[20:21] op_sel_hi:[1,0]
	v_pk_mul_f32 v[74:75], v[74:75], v[20:21] op_sel_hi:[1,0]
	v_pk_mul_f32 v[72:73], v[72:73], v[20:21] op_sel_hi:[1,0]
	v_pk_mul_f32 v[66:67], v[66:67], v[20:21] op_sel_hi:[1,0]
	v_pk_mul_f32 v[64:65], v[64:65], v[20:21] op_sel_hi:[1,0]
	v_pk_mul_f32 v[58:59], v[58:59], v[20:21] op_sel_hi:[1,0]
	v_pk_mul_f32 v[56:57], v[56:57], v[20:21] op_sel_hi:[1,0]
	v_pk_mul_f32 v[50:51], v[50:51], v[20:21] op_sel_hi:[1,0]
	v_pk_mul_f32 v[48:49], v[48:49], v[20:21] op_sel_hi:[1,0]
	v_pk_mul_f32 v[38:39], v[38:39], v[20:21] op_sel_hi:[1,0]
	v_pk_mul_f32 v[36:37], v[36:37], v[20:21] op_sel_hi:[1,0]
	v_pk_mul_f32 v[10:11], v[10:11], v[20:21] op_sel_hi:[1,0]
	v_pk_mul_f32 v[8:9], v[8:9], v[20:21] op_sel_hi:[1,0]
	v_pk_mul_f32 v[14:15], v[14:15], v[20:21] op_sel_hi:[1,0]
	v_pk_mul_f32 v[12:13], v[12:13], v[20:21] op_sel_hi:[1,0]
.LBB0_552:
	v_pk_add_f32 v[20:21], v[108:109], 0 op_sel_hi:[1,0]
	s_nop 0
	v_pk_add_f32 v[20:21], v[110:111], v[20:21]
	s_nop 0
	v_pk_add_f32 v[20:21], v[104:105], v[20:21]
	s_nop 0
	v_pk_add_f32 v[20:21], v[106:107], v[20:21]
	s_nop 0
	v_add_f32_e32 v20, v20, v21
	v_add_f32_e32 v24, v152, v20
	v_max3_f32 v20, v88, v89, v90
	v_add_f32_e32 v21, 0x41000000, v3
	v_max3_f32 v20, v20, v91, v84
	v_max3_f32 v20, v20, v85, v86
	v_max3_f32 v20, v20, v87, v87
	v_mul_f32_e32 v20, 0x3e38aa3b, v20
	v_cmp_gt_f32_e32 vcc, v20, v21
	s_cbranch_vccz .LBB0_554
	ds_swizzle_b32 v21, v20 offset:swizzle(SWAP,16)
	v_max_f32_e32 v20, v20, v20
	s_waitcnt lgkmcnt(0)
	v_max_f32_e32 v21, v21, v21
	v_max_f32_e32 v20, v20, v21
	ds_bpermute_b32 v21, v150, v20
	s_waitcnt lgkmcnt(0)
	v_max3_f32 v21, v3, v20, v21
	v_sub_f32_e32 v3, v3, v21
	v_exp_f32_e32 v20, v3
	v_mov_b32_e32 v3, v21
	v_mul_f32_e32 v24, v24, v20
	v_pk_mul_f32 v[78:79], v[78:79], v[20:21] op_sel_hi:[1,0]
	v_pk_mul_f32 v[76:77], v[76:77], v[20:21] op_sel_hi:[1,0]
	v_pk_mul_f32 v[70:71], v[70:71], v[20:21] op_sel_hi:[1,0]
	v_pk_mul_f32 v[68:69], v[68:69], v[20:21] op_sel_hi:[1,0]
	v_pk_mul_f32 v[62:63], v[62:63], v[20:21] op_sel_hi:[1,0]
	v_pk_mul_f32 v[60:61], v[60:61], v[20:21] op_sel_hi:[1,0]
	v_pk_mul_f32 v[102:103], v[102:103], v[20:21] op_sel_hi:[1,0]
	v_pk_mul_f32 v[100:101], v[100:101], v[20:21] op_sel_hi:[1,0]
	v_pk_mul_f32 v[54:55], v[54:55], v[20:21] op_sel_hi:[1,0]
	v_pk_mul_f32 v[52:53], v[52:53], v[20:21] op_sel_hi:[1,0]
	v_pk_mul_f32 v[46:47], v[46:47], v[20:21] op_sel_hi:[1,0]
	v_pk_mul_f32 v[44:45], v[44:45], v[20:21] op_sel_hi:[1,0]
	v_pk_mul_f32 v[6:7], v[6:7], v[20:21] op_sel_hi:[1,0]
	v_pk_mul_f32 v[4:5], v[4:5], v[20:21] op_sel_hi:[1,0]
	v_pk_mul_f32 v[18:19], v[18:19], v[20:21] op_sel_hi:[1,0]
	v_pk_mul_f32 v[16:17], v[16:17], v[20:21] op_sel_hi:[1,0]

.LBB0_556:
	s_bitcmp1_b32 s2, 0
	s_cselect_b32 s0, 0x6000, 0
	s_add_i32 s0, s0, 0
	v_add3_u32 v142, s0, v199, v200
	s_waitcnt lgkmcnt(0)
	s_barrier
	ds_read_b128 v[118:121], v142
	ds_read_b128 v[122:125], v142 offset:2048
	v_add3_u32 v148, s0, v197, v200
	s_waitcnt lgkmcnt(1)
	v_mfma_f32_16x16x32_bf16 v[126:129], v[118:121], v[46:49], 0
	ds_read_b128 v[134:137], v148
	ds_read_b128 v[138:141], v148 offset:2048
	v_subrev_u32_e32 v2, 32, v188
	v_ashrrev_i32_e32 v3, 31, v2
	v_mfma_f32_16x16x32_bf16 v[118:121], v[118:121], v[50:53], 0
	v_ashrrev_i32_e32 v189, 31, v188
	v_lshlrev_b64 v[2:3], 14, v[2:3]
	v_lshl_add_u64 v[2:3], v[24:25], 0, v[2:3]
	s_waitcnt lgkmcnt(2)
	v_mfma_f32_16x16x32_bf16 v[130:133], v[122:125], v[46:49], 0
	v_mfma_f32_16x16x32_bf16 v[122:125], v[122:125], v[50:53], 0
	s_waitcnt lgkmcnt(1)
	v_mfma_f32_16x16x32_bf16 v[170:173], v[134:137], v[38:41], v[126:129]
	s_nop 2
	ds_read_b128 v[126:129], v142 offset:4096
	v_mfma_f32_16x16x32_bf16 v[158:161], v[134:137], v[42:45], v[118:121]
	s_nop 2
	v_lshlrev_b64 v[118:119], 14, v[188:189]
	s_waitcnt lgkmcnt(1)
	v_mfma_f32_16x16x32_bf16 v[162:165], v[138:141], v[42:45], v[122:125]
	s_nop 2
	v_lshl_add_u64 v[122:123], v[24:25], 0, v[118:119]
	v_mfma_f32_16x16x32_bf16 v[166:169], v[138:141], v[38:41], v[130:133]
	s_nop 2
	ds_read_b128 v[130:133], v142 offset:6144
	global_load_dwordx4 v[118:121], v[2:3], off offset:128
	s_nop 0
	global_load_dwordx4 v[122:125], v[122:123], off offset:128
	ds_read_b128 v[142:145], v148 offset:4096
	v_lshl_add_u64 v[2:3], v[186:187], 0, s[20:21]
	s_waitcnt lgkmcnt(2)
	v_mfma_f32_16x16x32_bf16 v[134:137], v[126:129], v[46:49], 0
	v_mfma_f32_16x16x32_bf16 v[138:141], v[126:129], v[50:53], 0
	v_add_co_u32_e32 v126, vcc, s64, v2
	s_nop 1
	v_addc_co_u32_e32 v127, vcc, 0, v3, vcc
	v_add_co_u32_e32 v146, vcc, s65, v2
	s_waitcnt lgkmcnt(0)
	v_mfma_f32_16x16x32_bf16 v[154:157], v[142:145], v[38:41], v[134:137]
	v_addc_co_u32_e32 v147, vcc, 0, v3, vcc
	s_nop 1
	v_add_co_u32_e32 v134, vcc, s67, v2
	v_mfma_f32_16x16x32_bf16 v[150:153], v[130:133], v[46:49], 0
	s_nop 0
	v_addc_co_u32_e32 v135, vcc, 0, v3, vcc
	v_add_co_u32_e32 v2, vcc, s68, v2
	v_mfma_f32_16x16x32_bf16 v[204:207], v[130:133], v[50:53], 0
	global_load_dwordx4 v[126:129], v[126:127], off offset:128
	s_nop 0
	global_load_dwordx4 v[130:133], v[146:147], off offset:128
	ds_read_b128 v[208:211], v148 offset:6144
	v_addc_co_u32_e32 v3, vcc, 0, v3, vcc
	v_mfma_f32_16x16x32_bf16 v[146:149], v[142:145], v[42:45], v[138:141]
	global_load_dwordx4 v[134:137], v[134:135], off offset:128
	s_nop 1
	global_load_dwordx4 v[138:141], v[2:3], off offset:128
	v_max3_f32 v2, v170, v171, v172
	v_add_f32_e32 v3, 0x41000000, v190
	v_max3_f32 v2, v2, v173, v166
	s_waitcnt lgkmcnt(0)
	v_mfma_f32_16x16x32_bf16 v[150:153], v[208:211], v[38:41], v[150:153]
	v_max3_f32 v2, v2, v167, v168
	v_max3_f32 v2, v2, v169, v169
	v_mfma_f32_16x16x32_bf16 v[142:145], v[208:211], v[42:45], v[204:207]
	v_mul_f32_e32 v2, 0x3e38aa3b, v2
	v_cmp_gt_f32_e32 vcc, v2, v3
	s_cbranch_vccz .LBB0_558
	ds_swizzle_b32 v3, v2 offset:swizzle(SWAP,16)
	v_max_f32_e32 v2, v2, v2
	v_mov_b32_e32 v185, v191
	s_waitcnt lgkmcnt(0)
	v_max_f32_e32 v3, v3, v3
	v_max_f32_e32 v2, v2, v3
	ds_bpermute_b32 v3, v196, v2
	s_waitcnt lgkmcnt(0)
	v_max3_f32 v184, v190, v2, v3
	v_sub_f32_e32 v2, v190, v184
	v_exp_f32_e32 v2, v2
	v_mov_b32_e32 v190, v184
	v_mul_f32_e32 v0, v0, v2
	v_pk_mul_f32 v[116:117], v[116:117], v[2:3] op_sel_hi:[1,0]
	v_pk_mul_f32 v[114:115], v[114:115], v[2:3] op_sel_hi:[1,0]
	v_pk_mul_f32 v[108:109], v[108:109], v[2:3] op_sel_hi:[1,0]
	v_pk_mul_f32 v[106:107], v[106:107], v[2:3] op_sel_hi:[1,0]
	v_pk_mul_f32 v[100:101], v[100:101], v[2:3] op_sel_hi:[1,0]
	v_pk_mul_f32 v[98:99], v[98:99], v[2:3] op_sel_hi:[1,0]
	v_pk_mul_f32 v[92:93], v[92:93], v[2:3] op_sel_hi:[1,0]
	v_pk_mul_f32 v[90:91], v[90:91], v[2:3] op_sel_hi:[1,0]
	v_pk_mul_f32 v[84:85], v[84:85], v[2:3] op_sel_hi:[1,0]
	v_pk_mul_f32 v[82:83], v[82:83], v[2:3] op_sel_hi:[1,0]
	v_pk_mul_f32 v[72:73], v[72:73], v[2:3] op_sel_hi:[1,0]
	v_pk_mul_f32 v[70:71], v[70:71], v[2:3] op_sel_hi:[1,0]
	v_pk_mul_f32 v[68:69], v[68:69], v[2:3] op_sel_hi:[1,0]
	v_pk_mul_f32 v[66:67], v[66:67], v[2:3] op_sel_hi:[1,0]
	v_pk_mul_f32 v[76:77], v[76:77], v[2:3] op_sel_hi:[1,0]
	v_pk_mul_f32 v[74:75], v[74:75], v[2:3] op_sel_hi:[1,0]
	s_branch .LBB0_559

.LBB0_559:
	v_max3_f32 v2, v158, v159, v160
	v_add_f32_e32 v3, 0x41000000, v185
	v_max3_f32 v2, v2, v161, v162
	v_max3_f32 v2, v2, v163, v164
	v_max3_f32 v2, v2, v165, v165
	v_mul_f32_e32 v2, 0x3e38aa3b, v2
	v_cmp_gt_f32_e32 vcc, v2, v3
	s_cbranch_vccz .LBB0_561
	ds_swizzle_b32 v3, v2 offset:swizzle(SWAP,16)
	v_max_f32_e32 v2, v2, v2
	v_mov_b32_e32 v179, v184
	s_waitcnt lgkmcnt(0)
	v_max_f32_e32 v3, v3, v3
	v_max_f32_e32 v2, v2, v3
	ds_bpermute_b32 v3, v196, v2
	s_waitcnt lgkmcnt(0)
	v_max3_f32 v189, v185, v2, v3
	v_sub_f32_e32 v2, v185, v189
	v_exp_f32_e32 v2, v2
	v_mov_b32_e32 v185, v189
	v_mul_f32_e32 v198, v198, v2
	v_pk_mul_f32 v[112:113], v[112:113], v[2:3] op_sel_hi:[1,0]
	v_pk_mul_f32 v[110:111], v[110:111], v[2:3] op_sel_hi:[1,0]
	v_pk_mul_f32 v[104:105], v[104:105], v[2:3] op_sel_hi:[1,0]
	v_pk_mul_f32 v[102:103], v[102:103], v[2:3] op_sel_hi:[1,0]
	v_pk_mul_f32 v[96:97], v[96:97], v[2:3] op_sel_hi:[1,0]
	v_pk_mul_f32 v[94:95], v[94:95], v[2:3] op_sel_hi:[1,0]
	v_pk_mul_f32 v[88:89], v[88:89], v[2:3] op_sel_hi:[1,0]
	v_pk_mul_f32 v[86:87], v[86:87], v[2:3] op_sel_hi:[1,0]
	v_pk_mul_f32 v[80:81], v[80:81], v[2:3] op_sel_hi:[1,0]
	v_pk_mul_f32 v[78:79], v[78:79], v[2:3] op_sel_hi:[1,0]
	v_pk_mul_f32 v[64:65], v[64:65], v[2:3] op_sel_hi:[1,0]
	v_pk_mul_f32 v[62:63], v[62:63], v[2:3] op_sel_hi:[1,0]
	v_pk_mul_f32 v[60:61], v[60:61], v[2:3] op_sel_hi:[1,0]
	v_pk_mul_f32 v[58:59], v[58:59], v[2:3] op_sel_hi:[1,0]
	v_pk_mul_f32 v[56:57], v[56:57], v[2:3] op_sel_hi:[1,0]
	v_pk_mul_f32 v[54:55], v[54:55], v[2:3] op_sel_hi:[1,0]
	s_branch .LBB0_562

.LBB0_562:
	v_mov_b64_e32 v[2:3], v[184:185]
	v_fma_f32 v170, v170, s72, -v190
	v_fma_f32 v171, v171, s72, -v190
	v_exp_f32_e32 v170, v170
	v_exp_f32_e32 v171, v171
	v_fma_f32 v172, v172, s72, -v190
	v_fma_f32 v173, v173, s72, -v190
	v_exp_f32_e32 v172, v172
	v_exp_f32_e32 v173, v173
	v_fma_f32 v166, v166, s72, -v190
	v_fma_f32 v167, v167, s72, -v190
	v_fma_f32 v168, v168, s72, -v190
	v_exp_f32_e32 v166, v166
	v_exp_f32_e32 v167, v167
	v_exp_f32_e32 v206, v168
	v_fma_f32 v168, v169, s72, -v190
	v_exp_f32_e32 v207, v168
	v_pk_add_f32 v[204:205], v[170:171], 0 op_sel_hi:[1,0]
	v_fma_f32 v158, v158, s72, -v185
	v_pk_add_f32 v[204:205], v[172:173], v[204:205]
	v_fma_f32 v159, v159, s72, -v185
	v_pk_add_f32 v[168:169], v[166:167], v[204:205]
	v_fma_f32 v160, v160, s72, -v185
	v_pk_add_f32 v[168:169], v[206:207], v[168:169]
	v_fma_f32 v161, v161, s72, -v185
	v_add_f32_e32 v168, v168, v169
	v_add_f32_e32 v0, v0, v168
	v_cvt_pk_bf16_f32 v168, v170, v171
	v_cvt_pk_bf16_f32 v170, v166, v167
	v_add_u32_e32 v166, s0, v200
	v_add_u32_e32 v167, v166, v199
	ds_read_b128 v[208:211], v167 offset:8192
	v_fma_f32 v162, v162, s72, -v185
	v_fma_f32 v163, v163, s72, -v185
	v_fma_f32 v164, v164, s72, -v185
	v_fma_f32 v165, v165, s72, -v185
	v_exp_f32_e32 v158, v158
	v_exp_f32_e32 v159, v159
	v_exp_f32_e32 v160, v160
	v_exp_f32_e32 v161, v161
	v_exp_f32_e32 v162, v162
	v_exp_f32_e32 v163, v163
	v_exp_f32_e32 v164, v164
	v_exp_f32_e32 v165, v165
	v_cvt_pk_bf16_f32 v169, v172, v173
	v_cvt_pk_bf16_f32 v171, v206, v207
	v_cvt_pk_bf16_f32 v204, v158, v159
	v_cvt_pk_bf16_f32 v205, v160, v161
	v_cvt_pk_bf16_f32 v206, v162, v163
	v_cvt_pk_bf16_f32 v207, v164, v165
	s_waitcnt lgkmcnt(0)
	v_mfma_f32_16x16x32_bf16 v[114:117], v[208:211], v[168:171], v[114:117]
	v_mfma_f32_16x16x32_bf16 v[110:113], v[208:211], v[204:207], v[110:113]
	ds_read_b128 v[208:211], v167 offset:10240
	s_waitcnt lgkmcnt(0)
	v_mfma_f32_16x16x32_bf16 v[106:109], v[208:211], v[168:171], v[106:109]
	v_mfma_f32_16x16x32_bf16 v[102:105], v[208:211], v[204:207], v[102:105]
	ds_read_b128 v[208:211], v167 offset:12288
	s_waitcnt lgkmcnt(0)
	v_mfma_f32_16x16x32_bf16 v[98:101], v[208:211], v[168:171], v[98:101]
	v_mfma_f32_16x16x32_bf16 v[94:97], v[208:211], v[204:207], v[94:97]
	ds_read_b128 v[208:211], v167 offset:14336
	s_waitcnt lgkmcnt(0)
	v_mfma_f32_16x16x32_bf16 v[90:93], v[208:211], v[168:171], v[90:93]
	v_mfma_f32_16x16x32_bf16 v[86:89], v[208:211], v[204:207], v[86:89]
	ds_read_b128 v[208:211], v167 offset:16384
	s_waitcnt lgkmcnt(0)
	v_mfma_f32_16x16x32_bf16 v[82:85], v[208:211], v[168:171], v[82:85]
	v_mfma_f32_16x16x32_bf16 v[78:81], v[208:211], v[204:207], v[78:81]
	ds_read_b128 v[208:211], v167 offset:18432
	s_waitcnt lgkmcnt(0)
	v_mfma_f32_16x16x32_bf16 v[70:73], v[208:211], v[168:171], v[70:73]
	v_mfma_f32_16x16x32_bf16 v[62:65], v[208:211], v[204:207], v[62:65]
	ds_read_b128 v[208:211], v167 offset:20480
	s_waitcnt lgkmcnt(0)
	v_mfma_f32_16x16x32_bf16 v[66:69], v[208:211], v[168:171], v[66:69]
	v_mfma_f32_16x16x32_bf16 v[58:61], v[208:211], v[204:207], v[58:61]
	ds_read_b128 v[208:211], v167 offset:22528
	v_max3_f32 v167, v154, v155, v156
	v_max3_f32 v167, v167, v157, v150
	s_waitcnt lgkmcnt(0)
	v_mfma_f32_16x16x32_bf16 v[74:77], v[208:211], v[168:171], v[74:77]
	v_max3_f32 v167, v167, v151, v152
	v_add_f32_e32 v168, 0x41000000, v179
	v_max3_f32 v167, v167, v153, v153
	v_mfma_f32_16x16x32_bf16 v[54:57], v[208:211], v[204:207], v[54:57]
	v_mul_f32_e32 v167, 0x3e38aa3b, v167
	v_cmp_gt_f32_e32 vcc, v167, v168
	s_cbranch_vccz .LBB0_564
	ds_swizzle_b32 v2, v167 offset:swizzle(SWAP,16)
	v_max_f32_e32 v167, v167, v167
	v_mov_b32_e32 v185, v3
	s_waitcnt lgkmcnt(0)
	v_max_f32_e32 v2, v2, v2
	v_max_f32_e32 v2, v167, v2
	ds_bpermute_b32 v167, v196, v2
	s_waitcnt lgkmcnt(0)
	v_max3_f32 v2, v179, v2, v167
	v_sub_f32_e32 v167, v179, v2
	v_exp_f32_e32 v168, v167
	v_mov_b32_e32 v179, v2
	v_mul_f32_e32 v0, v0, v168
	v_pk_mul_f32 v[116:117], v[116:117], v[168:169] op_sel_hi:[1,0]
	v_pk_mul_f32 v[114:115], v[114:115], v[168:169] op_sel_hi:[1,0]
	v_pk_mul_f32 v[108:109], v[108:109], v[168:169] op_sel_hi:[1,0]
	v_pk_mul_f32 v[106:107], v[106:107], v[168:169] op_sel_hi:[1,0]
	v_pk_mul_f32 v[100:101], v[100:101], v[168:169] op_sel_hi:[1,0]
	v_pk_mul_f32 v[98:99], v[98:99], v[168:169] op_sel_hi:[1,0]
	v_pk_mul_f32 v[92:93], v[92:93], v[168:169] op_sel_hi:[1,0]
	v_pk_mul_f32 v[90:91], v[90:91], v[168:169] op_sel_hi:[1,0]
	v_pk_mul_f32 v[84:85], v[84:85], v[168:169] op_sel_hi:[1,0]
	v_pk_mul_f32 v[82:83], v[82:83], v[168:169] op_sel_hi:[1,0]
	v_pk_mul_f32 v[72:73], v[72:73], v[168:169] op_sel_hi:[1,0]
	v_pk_mul_f32 v[70:71], v[70:71], v[168:169] op_sel_hi:[1,0]
	v_pk_mul_f32 v[68:69], v[68:69], v[168:169] op_sel_hi:[1,0]
	v_pk_mul_f32 v[66:67], v[66:67], v[168:169] op_sel_hi:[1,0]
	v_pk_mul_f32 v[76:77], v[76:77], v[168:169] op_sel_hi:[1,0]
	v_pk_mul_f32 v[74:75], v[74:75], v[168:169] op_sel_hi:[1,0]
.LBB0_564:
	v_pk_add_f32 v[158:159], v[158:159], 0 op_sel_hi:[1,0]
	s_nop 0
	v_pk_add_f32 v[158:159], v[160:161], v[158:159]
	v_add_f32_e32 v160, 0x41000000, v185
	v_pk_add_f32 v[158:159], v[162:163], v[158:159]
	s_nop 0
	v_pk_add_f32 v[158:159], v[164:165], v[158:159]
	s_nop 0
	v_add_f32_e32 v158, v158, v159
	v_max3_f32 v159, v146, v147, v148
	v_add_f32_e32 v158, v198, v158
	v_max3_f32 v159, v159, v149, v142
	v_max3_f32 v159, v159, v143, v144
	v_max3_f32 v159, v159, v145, v145
	v_mul_f32_e32 v159, 0x3e38aa3b, v159
	v_cmp_gt_f32_e32 vcc, v159, v160
	s_cbranch_vccz .LBB0_555
	ds_swizzle_b32 v3, v159 offset:swizzle(SWAP,16)
	v_max_f32_e32 v159, v159, v159
	s_waitcnt lgkmcnt(0)
	v_max_f32_e32 v3, v3, v3
	v_max_f32_e32 v3, v159, v3
	ds_bpermute_b32 v159, v196, v3
	s_waitcnt lgkmcnt(0)
	v_max3_f32 v3, v185, v3, v159
	v_sub_f32_e32 v159, v185, v3
	v_exp_f32_e32 v160, v159
	v_mov_b32_e32 v185, v3
	v_mul_f32_e32 v158, v158, v160
	v_pk_mul_f32 v[112:113], v[112:113], v[160:161] op_sel_hi:[1,0]
	v_pk_mul_f32 v[110:111], v[110:111], v[160:161] op_sel_hi:[1,0]
	v_pk_mul_f32 v[104:105], v[104:105], v[160:161] op_sel_hi:[1,0]
	v_pk_mul_f32 v[102:103], v[102:103], v[160:161] op_sel_hi:[1,0]
	v_pk_mul_f32 v[96:97], v[96:97], v[160:161] op_sel_hi:[1,0]
	v_pk_mul_f32 v[94:95], v[94:95], v[160:161] op_sel_hi:[1,0]
	v_pk_mul_f32 v[88:89], v[88:89], v[160:161] op_sel_hi:[1,0]
	v_pk_mul_f32 v[86:87], v[86:87], v[160:161] op_sel_hi:[1,0]
	v_pk_mul_f32 v[80:81], v[80:81], v[160:161] op_sel_hi:[1,0]
	v_pk_mul_f32 v[78:79], v[78:79], v[160:161] op_sel_hi:[1,0]
	v_pk_mul_f32 v[64:65], v[64:65], v[160:161] op_sel_hi:[1,0]
	v_pk_mul_f32 v[62:63], v[62:63], v[160:161] op_sel_hi:[1,0]
	v_pk_mul_f32 v[60:61], v[60:61], v[160:161] op_sel_hi:[1,0]
	v_pk_mul_f32 v[58:59], v[58:59], v[160:161] op_sel_hi:[1,0]
	v_pk_mul_f32 v[56:57], v[56:57], v[160:161] op_sel_hi:[1,0]
	v_pk_mul_f32 v[54:55], v[54:55], v[160:161] op_sel_hi:[1,0]
	s_branch .LBB0_555
.LBB0_566:
	v_mfma_f32_16x16x32_bf16 v[8:11], v[30:33], v[20:23], v[8:11]
	s_waitcnt lgkmcnt(0)
	s_barrier
	v_mfma_f32_16x16x32_bf16 v[12:15], v[34:37], v[20:23], v[12:15]
	v_mfma_f32_16x16x32_bf16 v[22:25], v[30:33], v[26:29], v[4:7]
	s_nop 2
	v_add3_u32 v6, s0, v199, v200
	ds_read_b128 v[2:5], v6
	ds_read_b128 v[30:33], v6 offset:2048
	v_add3_u32 v7, s0, v197, v200
	ds_read_b128 v[118:121], v7
	v_mfma_f32_16x16x32_bf16 v[18:21], v[34:37], v[26:29], v[16:19]
	s_waitcnt lgkmcnt(2)
	v_mfma_f32_16x16x32_bf16 v[26:29], v[2:5], v[46:49], 0
	v_mfma_f32_16x16x32_bf16 v[2:5], v[2:5], v[50:53], 0
	s_waitcnt lgkmcnt(0)
	v_mfma_f32_16x16x32_bf16 v[130:133], v[118:121], v[38:41], v[26:29]
	v_mfma_f32_16x16x32_bf16 v[118:121], v[118:121], v[42:45], v[2:5]
	s_nop 4
	ds_read_b128 v[2:5], v7 offset:2048
	v_mfma_f32_16x16x32_bf16 v[34:37], v[30:33], v[46:49], 0
	v_mfma_f32_16x16x32_bf16 v[30:33], v[30:33], v[50:53], 0
	s_waitcnt lgkmcnt(0)
	v_mfma_f32_16x16x32_bf16 v[126:129], v[2:5], v[38:41], v[34:37]
	v_mfma_f32_16x16x32_bf16 v[122:125], v[2:5], v[42:45], v[30:33]
	ds_read_b128 v[2:5], v6 offset:4096
	s_nop 3
	ds_read_b128 v[30:33], v6 offset:6144
	s_waitcnt lgkmcnt(1)
	v_mfma_f32_16x16x32_bf16 v[26:29], v[2:5], v[46:49], 0
	v_max3_f32 v6, v130, v131, v132
	v_max3_f32 v6, v6, v133, v126
	v_mfma_f32_16x16x32_bf16 v[2:5], v[2:5], v[50:53], 0
	v_max3_f32 v6, v6, v127, v128
	v_max3_f32 v6, v6, v129, v129
	s_waitcnt lgkmcnt(0)
	v_mfma_f32_16x16x32_bf16 v[34:37], v[30:33], v[46:49], 0
	v_mul_f32_e32 v6, 0x3e38aa3b, v6
	v_mfma_f32_16x16x32_bf16 v[46:49], v[30:33], v[50:53], 0
	ds_read_b128 v[50:53], v7 offset:4096
	s_waitcnt lgkmcnt(0)
	v_mfma_f32_16x16x32_bf16 v[30:33], v[50:53], v[38:41], v[26:29]
	s_nop 2
	ds_read_b128 v[26:29], v7 offset:6144
	v_add_f32_e32 v7, 0x41000000, v190
	v_cmp_gt_f32_e32 vcc, v6, v7
	v_mfma_f32_16x16x32_bf16 v[2:5], v[50:53], v[42:45], v[2:5]
	s_waitcnt lgkmcnt(0)
	v_mfma_f32_16x16x32_bf16 v[34:37], v[26:29], v[38:41], v[34:37]
	v_mfma_f32_16x16x32_bf16 v[26:29], v[26:29], v[42:45], v[46:49]
	s_cbranch_vccz .LBB0_568
	ds_swizzle_b32 v7, v6 offset:swizzle(SWAP,16)
	v_max_f32_e32 v6, v6, v6
	v_mov_b32_e32 v185, v191
	s_waitcnt lgkmcnt(0)
	v_max_f32_e32 v7, v7, v7
	v_max_f32_e32 v6, v6, v7
	ds_bpermute_b32 v7, v196, v6
	s_waitcnt lgkmcnt(0)
	v_max3_f32 v6, v190, v6, v7
	v_sub_f32_e32 v7, v190, v6
	v_exp_f32_e32 v16, v7
	v_mov_b32_e32 v7, v191
	v_mov_b32_e32 v190, v6
	v_mul_f32_e32 v0, v0, v16
	v_pk_mul_f32 v[116:117], v[116:117], v[16:17] op_sel_hi:[1,0]
	v_pk_mul_f32 v[114:115], v[114:115], v[16:17] op_sel_hi:[1,0]
	v_pk_mul_f32 v[108:109], v[108:109], v[16:17] op_sel_hi:[1,0]
	v_pk_mul_f32 v[106:107], v[106:107], v[16:17] op_sel_hi:[1,0]
	v_pk_mul_f32 v[100:101], v[100:101], v[16:17] op_sel_hi:[1,0]
	v_pk_mul_f32 v[98:99], v[98:99], v[16:17] op_sel_hi:[1,0]
	v_pk_mul_f32 v[92:93], v[92:93], v[16:17] op_sel_hi:[1,0]
	v_pk_mul_f32 v[90:91], v[90:91], v[16:17] op_sel_hi:[1,0]
	v_pk_mul_f32 v[84:85], v[84:85], v[16:17] op_sel_hi:[1,0]
	v_pk_mul_f32 v[82:83], v[82:83], v[16:17] op_sel_hi:[1,0]
	v_pk_mul_f32 v[72:73], v[72:73], v[16:17] op_sel_hi:[1,0]
	v_pk_mul_f32 v[70:71], v[70:71], v[16:17] op_sel_hi:[1,0]
	v_pk_mul_f32 v[68:69], v[68:69], v[16:17] op_sel_hi:[1,0]
	v_pk_mul_f32 v[66:67], v[66:67], v[16:17] op_sel_hi:[1,0]
	v_pk_mul_f32 v[76:77], v[76:77], v[16:17] op_sel_hi:[1,0]
	v_pk_mul_f32 v[74:75], v[74:75], v[16:17] op_sel_hi:[1,0]
	s_branch .LBB0_569

.LBB0_569:
	v_max3_f32 v16, v118, v119, v120
	v_add_f32_e32 v17, 0x41000000, v185
	v_max3_f32 v16, v16, v121, v122
	v_max3_f32 v16, v16, v123, v124
	v_max3_f32 v16, v16, v125, v125
	v_mul_f32_e32 v16, 0x3e38aa3b, v16
	v_cmp_gt_f32_e32 vcc, v16, v17
	s_cbranch_vccz .LBB0_571
	ds_swizzle_b32 v7, v16 offset:swizzle(SWAP,16)
	v_max_f32_e32 v16, v16, v16
	s_waitcnt lgkmcnt(0)
	v_max_f32_e32 v7, v7, v7
	v_max_f32_e32 v7, v16, v7
	ds_bpermute_b32 v16, v196, v7
	s_waitcnt lgkmcnt(0)
	v_max3_f32 v7, v185, v7, v16
	v_sub_f32_e32 v16, v185, v7
	v_exp_f32_e32 v16, v16
	v_mov_b32_e32 v185, v7
	v_mul_f32_e32 v198, v198, v16
	v_pk_mul_f32 v[112:113], v[112:113], v[16:17] op_sel_hi:[1,0]
	v_pk_mul_f32 v[110:111], v[110:111], v[16:17] op_sel_hi:[1,0]
	v_pk_mul_f32 v[104:105], v[104:105], v[16:17] op_sel_hi:[1,0]
	v_pk_mul_f32 v[102:103], v[102:103], v[16:17] op_sel_hi:[1,0]
	v_pk_mul_f32 v[96:97], v[96:97], v[16:17] op_sel_hi:[1,0]
	v_pk_mul_f32 v[94:95], v[94:95], v[16:17] op_sel_hi:[1,0]
	v_pk_mul_f32 v[88:89], v[88:89], v[16:17] op_sel_hi:[1,0]
	v_pk_mul_f32 v[86:87], v[86:87], v[16:17] op_sel_hi:[1,0]
	v_pk_mul_f32 v[80:81], v[80:81], v[16:17] op_sel_hi:[1,0]
	v_pk_mul_f32 v[78:79], v[78:79], v[16:17] op_sel_hi:[1,0]
	v_pk_mul_f32 v[64:65], v[64:65], v[16:17] op_sel_hi:[1,0]
	v_pk_mul_f32 v[62:63], v[62:63], v[16:17] op_sel_hi:[1,0]
	v_pk_mul_f32 v[60:61], v[60:61], v[16:17] op_sel_hi:[1,0]
	v_pk_mul_f32 v[58:59], v[58:59], v[16:17] op_sel_hi:[1,0]
	v_pk_mul_f32 v[56:57], v[56:57], v[16:17] op_sel_hi:[1,0]
	v_pk_mul_f32 v[54:55], v[54:55], v[16:17] op_sel_hi:[1,0]
	s_branch .LBB0_572

.LBB0_572:
	v_fma_f32 v16, v130, s72, -v190
	v_fma_f32 v17, v131, s72, -v190
	v_exp_f32_e32 v16, v16
	v_exp_f32_e32 v17, v17
	v_fma_f32 v38, v132, s72, -v190
	v_fma_f32 v39, v133, s72, -v190
	v_exp_f32_e32 v38, v38
	v_exp_f32_e32 v39, v39
	v_fma_f32 v42, v126, s72, -v190
	v_fma_f32 v43, v127, s72, -v190
	v_exp_f32_e32 v42, v42
	v_exp_f32_e32 v43, v43
	v_fma_f32 v44, v128, s72, -v190
	v_fma_f32 v45, v129, s72, -v190
	v_exp_f32_e32 v44, v44
	v_exp_f32_e32 v45, v45
	v_pk_add_f32 v[40:41], v[16:17], 0 op_sel_hi:[1,0]
	v_cvt_pk_bf16_f32 v129, v38, v39
	v_pk_add_f32 v[40:41], v[38:39], v[40:41]
	v_fma_f32 v38, v120, s72, -v185
	v_pk_add_f32 v[40:41], v[42:43], v[40:41]
	v_cvt_pk_bf16_f32 v128, v16, v17
	v_fma_f32 v16, v118, s72, -v185
	v_exp_f32_e32 v118, v38
	v_fma_f32 v38, v121, s72, -v185
	v_pk_add_f32 v[40:41], v[44:45], v[40:41]
	v_fma_f32 v17, v119, s72, -v185
	v_exp_f32_e32 v119, v38
	v_fma_f32 v38, v122, s72, -v185
	v_add_f32_e32 v40, v40, v41
	v_exp_f32_e32 v120, v38
	v_fma_f32 v38, v123, s72, -v185
	v_add_f32_e32 v126, v0, v40
	v_add_u32_e32 v0, s0, v200
	v_exp_f32_e32 v121, v38
	v_fma_f32 v38, v124, s72, -v185
	v_exp_f32_e32 v122, v38
	v_fma_f32 v38, v125, s72, -v185
	v_add_u32_e32 v124, v0, v199
	v_exp_f32_e32 v123, v38
	ds_read_b128 v[38:41], v124 offset:8192
	v_exp_f32_e32 v16, v16
	v_exp_f32_e32 v17, v17
	v_cvt_pk_bf16_f32 v130, v42, v43
	v_cvt_pk_bf16_f32 v131, v44, v45
	v_cvt_pk_bf16_f32 v133, v118, v119
	v_cvt_pk_bf16_f32 v132, v16, v17
	v_cvt_pk_bf16_f32 v134, v120, v121
	v_cvt_pk_bf16_f32 v135, v122, v123
	ds_read_b128 v[42:45], v124 offset:20480
	s_waitcnt lgkmcnt(1)
	v_mfma_f32_16x16x32_bf16 v[114:117], v[38:41], v[128:131], v[114:117]
	v_mfma_f32_16x16x32_bf16 v[110:113], v[38:41], v[132:135], v[110:113]
	ds_read_b128 v[38:41], v124 offset:10240
	s_waitcnt lgkmcnt(0)
	v_mfma_f32_16x16x32_bf16 v[106:109], v[38:41], v[128:131], v[106:109]
	v_mfma_f32_16x16x32_bf16 v[102:105], v[38:41], v[132:135], v[102:105]
	ds_read_b128 v[38:41], v124 offset:12288
	s_waitcnt lgkmcnt(0)
	v_mfma_f32_16x16x32_bf16 v[98:101], v[38:41], v[128:131], v[98:101]
	v_mfma_f32_16x16x32_bf16 v[94:97], v[38:41], v[132:135], v[94:97]
	ds_read_b128 v[38:41], v124 offset:14336
	s_waitcnt lgkmcnt(0)
	v_mfma_f32_16x16x32_bf16 v[90:93], v[38:41], v[128:131], v[90:93]
	v_mfma_f32_16x16x32_bf16 v[86:89], v[38:41], v[132:135], v[86:89]
	ds_read_b128 v[38:41], v124 offset:16384
	s_waitcnt lgkmcnt(0)
	v_mfma_f32_16x16x32_bf16 v[82:85], v[38:41], v[128:131], v[82:85]
	v_mfma_f32_16x16x32_bf16 v[78:81], v[38:41], v[132:135], v[78:81]
	ds_read_b128 v[38:41], v124 offset:18432
	s_waitcnt lgkmcnt(0)
	v_mfma_f32_16x16x32_bf16 v[50:53], v[38:41], v[132:135], v[62:65]
	s_nop 2
	ds_read_b128 v[62:65], v124 offset:22528
	v_mfma_f32_16x16x32_bf16 v[46:49], v[38:41], v[128:131], v[70:73]
	v_mfma_f32_16x16x32_bf16 v[38:41], v[42:45], v[128:131], v[66:69]
	v_mfma_f32_16x16x32_bf16 v[42:45], v[42:45], v[132:135], v[58:61]
	s_waitcnt lgkmcnt(0)
	v_mfma_f32_16x16x32_bf16 v[58:61], v[62:65], v[128:131], v[74:77]
	v_mfma_f32_16x16x32_bf16 v[54:57], v[62:65], v[132:135], v[54:57]
	v_max3_f32 v62, v30, v31, v32
	v_add_f32_e32 v63, 0x41000000, v6
	v_max3_f32 v62, v62, v33, v34
	v_max3_f32 v62, v62, v35, v36
	v_max3_f32 v62, v62, v37, v37
	v_mul_f32_e32 v62, 0x3e38aa3b, v62
	v_cmp_gt_f32_e32 vcc, v62, v63
	s_cbranch_vccz .LBB0_574
	ds_swizzle_b32 v63, v62 offset:swizzle(SWAP,16)
	v_max_f32_e32 v62, v62, v62
	v_mov_b32_e32 v185, v7
	s_waitcnt lgkmcnt(0)
	v_max_f32_e32 v63, v63, v63
	v_max_f32_e32 v62, v62, v63
	ds_bpermute_b32 v63, v196, v62
	s_waitcnt lgkmcnt(0)
	v_max3_f32 v62, v6, v62, v63
	v_sub_f32_e32 v6, v6, v62
	v_exp_f32_e32 v6, v6
	s_nop 0
	v_mul_f32_e32 v126, v126, v6
	v_pk_mul_f32 v[116:117], v[116:117], v[6:7] op_sel_hi:[1,0]
	v_pk_mul_f32 v[114:115], v[114:115], v[6:7] op_sel_hi:[1,0]
	v_pk_mul_f32 v[108:109], v[108:109], v[6:7] op_sel_hi:[1,0]
	v_pk_mul_f32 v[106:107], v[106:107], v[6:7] op_sel_hi:[1,0]
	v_pk_mul_f32 v[100:101], v[100:101], v[6:7] op_sel_hi:[1,0]
	v_pk_mul_f32 v[98:99], v[98:99], v[6:7] op_sel_hi:[1,0]
	v_pk_mul_f32 v[92:93], v[92:93], v[6:7] op_sel_hi:[1,0]
	v_pk_mul_f32 v[90:91], v[90:91], v[6:7] op_sel_hi:[1,0]
	v_pk_mul_f32 v[84:85], v[84:85], v[6:7] op_sel_hi:[1,0]
	v_pk_mul_f32 v[82:83], v[82:83], v[6:7] op_sel_hi:[1,0]
	v_pk_mul_f32 v[48:49], v[48:49], v[6:7] op_sel_hi:[1,0]
	v_pk_mul_f32 v[46:47], v[46:47], v[6:7] op_sel_hi:[1,0]
	v_pk_mul_f32 v[40:41], v[40:41], v[6:7] op_sel_hi:[1,0]
	v_pk_mul_f32 v[38:39], v[38:39], v[6:7] op_sel_hi:[1,0]
	v_pk_mul_f32 v[60:61], v[60:61], v[6:7] op_sel_hi:[1,0]
	v_pk_mul_f32 v[58:59], v[58:59], v[6:7] op_sel_hi:[1,0]
	v_mov_b32_e32 v6, v62
.LBB0_574:
	v_pk_add_f32 v[16:17], v[16:17], 0 op_sel_hi:[1,0]
	s_nop 0
	v_pk_add_f32 v[16:17], v[118:119], v[16:17]
	s_nop 0
	v_pk_add_f32 v[16:17], v[120:121], v[16:17]
	s_nop 0
	v_pk_add_f32 v[16:17], v[122:123], v[16:17]
	s_nop 0
	v_add_f32_e32 v7, v16, v17
	v_max3_f32 v16, v2, v3, v4
	v_add_f32_e32 v17, 0x41000000, v185
	v_max3_f32 v16, v16, v5, v26
	v_add_f32_e32 v7, v198, v7
	v_max3_f32 v16, v16, v27, v28
	v_max3_f32 v16, v16, v29, v29
	v_mul_f32_e32 v16, 0x3e38aa3b, v16
	v_cmp_gt_f32_e32 vcc, v16, v17
	s_cbranch_vccz .LBB0_576
	ds_swizzle_b32 v17, v16 offset:swizzle(SWAP,16)
	v_max_f32_e32 v16, v16, v16
	s_waitcnt lgkmcnt(0)
	v_max_f32_e32 v17, v17, v17
	v_max_f32_e32 v16, v16, v17
	ds_bpermute_b32 v17, v196, v16
	s_waitcnt lgkmcnt(0)
	v_max3_f32 v17, v185, v16, v17
	v_sub_f32_e32 v16, v185, v17
	v_exp_f32_e32 v16, v16
	v_mov_b32_e32 v185, v17
	v_mul_f32_e32 v7, v7, v16
	v_pk_mul_f32 v[112:113], v[112:113], v[16:17] op_sel_hi:[1,0]
	v_pk_mul_f32 v[110:111], v[110:111], v[16:17] op_sel_hi:[1,0]
	v_pk_mul_f32 v[104:105], v[104:105], v[16:17] op_sel_hi:[1,0]
	v_pk_mul_f32 v[102:103], v[102:103], v[16:17] op_sel_hi:[1,0]
	v_pk_mul_f32 v[96:97], v[96:97], v[16:17] op_sel_hi:[1,0]
	v_pk_mul_f32 v[94:95], v[94:95], v[16:17] op_sel_hi:[1,0]
	v_pk_mul_f32 v[88:89], v[88:89], v[16:17] op_sel_hi:[1,0]
	v_pk_mul_f32 v[86:87], v[86:87], v[16:17] op_sel_hi:[1,0]
	v_pk_mul_f32 v[80:81], v[80:81], v[16:17] op_sel_hi:[1,0]
	v_pk_mul_f32 v[78:79], v[78:79], v[16:17] op_sel_hi:[1,0]
	v_pk_mul_f32 v[52:53], v[52:53], v[16:17] op_sel_hi:[1,0]
	v_pk_mul_f32 v[50:51], v[50:51], v[16:17] op_sel_hi:[1,0]
	v_pk_mul_f32 v[44:45], v[44:45], v[16:17] op_sel_hi:[1,0]
	v_pk_mul_f32 v[42:43], v[42:43], v[16:17] op_sel_hi:[1,0]
	v_pk_mul_f32 v[56:57], v[56:57], v[16:17] op_sel_hi:[1,0]
	v_pk_mul_f32 v[54:55], v[54:55], v[16:17] op_sel_hi:[1,0]

.LBB0_584:
	s_bitcmp1_b32 s0, 0
	s_cselect_b32 s0, 0x6000, 0
	s_add_i32 s28, s0, 0
	s_add_i32 s19, s19, 64
	s_add_i32 s0, s42, 0x1000
	s_and_b64 s[26:27], s[26:27], exec
	s_cselect_b32 s42, s19, s0
	s_lshl_b32 s100, s44, 14
	s_add_u32 s100, s14, s100
	s_addc_u32 s101, s15, 0
	global_load_dwordx4 v[84:87], v150, s[100:101]
	global_load_dwordx4 v[88:91], v151, s[100:101]
	s_lshl_b32 s100, s42, 1
	s_add_u32 s100, s22, s100
	s_addc_u32 s101, s23, 0
	global_load_dwordx4 v[92:95], v142, s[100:101]
	global_load_dwordx4 v[104:107], v148, s[100:101]
	v_add3_u32 v2, s28, v159, v160
	global_load_dwordx4 v[96:99], v144, s[100:101]
	ds_read_b128 v[108:111], v2
	ds_read_b128 v[116:119], v2 offset:2048
	global_load_dwordx4 v[100:103], v146, s[100:101]
	v_add3_u32 v3, s28, v157, v160
	ds_read_b128 v[124:127], v3
	ds_read_b128 v[170:173], v3 offset:4096
	s_waitcnt vmcnt(9) lgkmcnt(3)
	v_mfma_f32_16x16x32_bf16 v[112:115], v[108:111], v[12:15], 0
	s_waitcnt vmcnt(7)
	v_mfma_f32_16x16x32_bf16 v[108:111], v[108:111], v[16:19], 0
	s_waitcnt lgkmcnt(1)
	v_mfma_f32_16x16x32_bf16 v[136:139], v[124:127], v[4:7], v[112:115]
	s_waitcnt vmcnt(6)
	v_mfma_f32_16x16x32_bf16 v[124:127], v[124:127], v[8:11], v[108:111]
	s_nop 3
	ds_read_b128 v[108:111], v3 offset:2048
	v_mfma_f32_16x16x32_bf16 v[120:123], v[116:119], v[12:15], 0
	v_mfma_f32_16x16x32_bf16 v[116:119], v[116:119], v[16:19], 0
	s_waitcnt lgkmcnt(0)
	v_mfma_f32_16x16x32_bf16 v[132:135], v[108:111], v[4:7], v[120:123]
	v_mfma_f32_16x16x32_bf16 v[128:131], v[108:111], v[8:11], v[116:119]
	ds_read_b128 v[108:111], v2 offset:4096
	s_nop 3
	ds_read_b128 v[116:119], v2 offset:6144
	s_waitcnt lgkmcnt(1)
	v_mfma_f32_16x16x32_bf16 v[112:115], v[108:111], v[12:15], 0
	v_max3_f32 v2, v136, v137, v138
	v_max3_f32 v2, v2, v139, v132
	s_waitcnt lgkmcnt(0)
	v_mfma_f32_16x16x32_bf16 v[120:123], v[116:119], v[12:15], 0
	v_max3_f32 v2, v2, v133, v134
	v_max3_f32 v2, v2, v135, v135
	v_mfma_f32_16x16x32_bf16 v[166:169], v[116:119], v[16:19], 0
	v_mul_f32_e32 v2, 0x3e38aa3b, v2
	v_mfma_f32_16x16x32_bf16 v[116:119], v[170:173], v[4:7], v[112:115]
	s_nop 2
	ds_read_b128 v[112:115], v3 offset:6144
	v_mfma_f32_16x16x32_bf16 v[108:111], v[108:111], v[16:19], 0
	v_add_f32_e32 v3, 0x41000000, v152
	v_cmp_gt_f32_e32 vcc, v2, v3
	v_mfma_f32_16x16x32_bf16 v[108:111], v[170:173], v[8:11], v[108:111]
	s_waitcnt lgkmcnt(0)
	v_mfma_f32_16x16x32_bf16 v[120:123], v[112:115], v[4:7], v[120:123]
	v_mfma_f32_16x16x32_bf16 v[112:115], v[112:115], v[8:11], v[166:169]
	s_cbranch_vccz .LBB0_586
	ds_swizzle_b32 v3, v2 offset:swizzle(SWAP,16)
	v_max_f32_e32 v2, v2, v2
	s_waitcnt lgkmcnt(0)
	v_max_f32_e32 v3, v3, v3
	v_max_f32_e32 v2, v2, v3
	ds_bpermute_b32 v3, v156, v2
	s_waitcnt lgkmcnt(0)
	v_max3_f32 v2, v152, v2, v3
	v_sub_f32_e32 v3, v152, v2
	v_exp_f32_e32 v152, v3
	v_mov_b32_e32 v3, v153
	v_mul_f32_e32 v0, v0, v152
	v_pk_mul_f32 v[82:83], v[82:83], v[152:153] op_sel_hi:[1,0]
	v_pk_mul_f32 v[80:81], v[80:81], v[152:153] op_sel_hi:[1,0]
	v_pk_mul_f32 v[74:75], v[74:75], v[152:153] op_sel_hi:[1,0]
	v_pk_mul_f32 v[72:73], v[72:73], v[152:153] op_sel_hi:[1,0]
	v_pk_mul_f32 v[66:67], v[66:67], v[152:153] op_sel_hi:[1,0]
	v_pk_mul_f32 v[64:65], v[64:65], v[152:153] op_sel_hi:[1,0]
	v_pk_mul_f32 v[58:59], v[58:59], v[152:153] op_sel_hi:[1,0]
	v_pk_mul_f32 v[56:57], v[56:57], v[152:153] op_sel_hi:[1,0]
	v_pk_mul_f32 v[50:51], v[50:51], v[152:153] op_sel_hi:[1,0]
	v_pk_mul_f32 v[48:49], v[48:49], v[152:153] op_sel_hi:[1,0]
	v_pk_mul_f32 v[42:43], v[42:43], v[152:153] op_sel_hi:[1,0]
	v_pk_mul_f32 v[40:41], v[40:41], v[152:153] op_sel_hi:[1,0]
	v_pk_mul_f32 v[38:39], v[38:39], v[152:153] op_sel_hi:[1,0]
	v_pk_mul_f32 v[36:37], v[36:37], v[152:153] op_sel_hi:[1,0]
	v_pk_mul_f32 v[30:31], v[30:31], v[152:153] op_sel_hi:[1,0]
	v_pk_mul_f32 v[28:29], v[28:29], v[152:153] op_sel_hi:[1,0]
	v_mov_b32_e32 v152, v2
	s_branch .LBB0_587

.LBB0_587:
	v_max3_f32 v153, v124, v125, v126
	v_add_f32_e32 v154, 0x41000000, v3
	v_max3_f32 v153, v153, v127, v128
	v_max3_f32 v153, v153, v129, v130
	v_max3_f32 v153, v153, v131, v131
	v_mul_f32_e32 v153, 0x3e38aa3b, v153
	v_cmp_gt_f32_e32 vcc, v153, v154
	s_cbranch_vccz .LBB0_589
	ds_swizzle_b32 v154, v153 offset:swizzle(SWAP,16)
	v_max_f32_e32 v153, v153, v153
	v_mov_b32_e32 v165, v2
	s_waitcnt lgkmcnt(0)
	v_max_f32_e32 v154, v154, v154
	v_max_f32_e32 v153, v153, v154
	ds_bpermute_b32 v154, v156, v153
	s_waitcnt lgkmcnt(0)
	v_max3_f32 v153, v3, v153, v154
	v_sub_f32_e32 v3, v3, v153
	v_exp_f32_e32 v154, v3
	v_mov_b32_e32 v3, v153
	v_mul_f32_e32 v158, v158, v154
	v_pk_mul_f32 v[78:79], v[78:79], v[154:155] op_sel_hi:[1,0]
	v_pk_mul_f32 v[76:77], v[76:77], v[154:155] op_sel_hi:[1,0]
	v_pk_mul_f32 v[70:71], v[70:71], v[154:155] op_sel_hi:[1,0]
	v_pk_mul_f32 v[68:69], v[68:69], v[154:155] op_sel_hi:[1,0]
	v_pk_mul_f32 v[62:63], v[62:63], v[154:155] op_sel_hi:[1,0]
	v_pk_mul_f32 v[60:61], v[60:61], v[154:155] op_sel_hi:[1,0]
	v_pk_mul_f32 v[54:55], v[54:55], v[154:155] op_sel_hi:[1,0]
	v_pk_mul_f32 v[52:53], v[52:53], v[154:155] op_sel_hi:[1,0]
	v_pk_mul_f32 v[46:47], v[46:47], v[154:155] op_sel_hi:[1,0]
	v_pk_mul_f32 v[44:45], v[44:45], v[154:155] op_sel_hi:[1,0]
	v_pk_mul_f32 v[34:35], v[34:35], v[154:155] op_sel_hi:[1,0]
	v_pk_mul_f32 v[32:33], v[32:33], v[154:155] op_sel_hi:[1,0]
	v_pk_mul_f32 v[26:27], v[26:27], v[154:155] op_sel_hi:[1,0]
	v_pk_mul_f32 v[24:25], v[24:25], v[154:155] op_sel_hi:[1,0]
	v_pk_mul_f32 v[22:23], v[22:23], v[154:155] op_sel_hi:[1,0]
	v_pk_mul_f32 v[20:21], v[20:21], v[154:155] op_sel_hi:[1,0]
	s_branch .LBB0_590

.LBB0_590:
	v_mov_b64_e32 v[154:155], v[2:3]
	v_pk_fma_f32 v[136:137], v[136:137], s[98:99], v[152:153] op_sel_hi:[1,1,0] neg_lo:[0,0,1] neg_hi:[0,0,1]
	v_pk_fma_f32 v[138:139], v[138:139], s[98:99], v[152:153] op_sel_hi:[1,1,0] neg_lo:[0,0,1] neg_hi:[0,0,1]
	v_pk_fma_f32 v[132:133], v[132:133], s[98:99], v[152:153] op_sel_hi:[1,1,0] neg_lo:[0,0,1] neg_hi:[0,0,1]
	v_pk_fma_f32 v[134:135], v[134:135], s[98:99], v[152:153] op_sel_hi:[1,1,0] neg_lo:[0,0,1] neg_hi:[0,0,1]
	v_exp_f32_e32 v136, v136
	v_exp_f32_e32 v137, v137
	v_exp_f32_e32 v138, v138
	v_exp_f32_e32 v139, v139
	v_exp_f32_e32 v168, v132
	v_exp_f32_e32 v169, v133
	v_exp_f32_e32 v170, v134
	v_exp_f32_e32 v171, v135
	v_pk_add_f32 v[166:167], v[136:137], 0 op_sel_hi:[1,0]
	v_cvt_pk_bf16_f32 v134, v168, v169
	v_pk_add_f32 v[166:167], v[138:139], v[166:167]
	v_fma_f32 v124, v124, s72, -v3
	v_fma_f32 v125, v125, s72, -v3
	v_pk_add_f32 v[132:133], v[168:169], v[166:167]
	v_fma_f32 v126, v126, s72, -v3
	v_fma_f32 v127, v127, s72, -v3
	v_pk_add_f32 v[132:133], v[170:171], v[132:133]
	v_fma_f32 v128, v128, s72, -v3
	v_fma_f32 v129, v129, s72, -v3
	v_add_f32_e32 v2, v132, v133
	v_add_f32_e32 v0, v0, v2
	v_add_u32_e32 v2, s28, v160
	v_add_u32_e32 v152, v2, v159
	ds_read_b128 v[166:169], v152 offset:8192
	v_fma_f32 v130, v130, s72, -v3
	v_fma_f32 v131, v131, s72, -v3
	v_exp_f32_e32 v124, v124
	v_exp_f32_e32 v125, v125
	v_exp_f32_e32 v126, v126
	v_exp_f32_e32 v127, v127
	v_exp_f32_e32 v128, v128
	v_exp_f32_e32 v129, v129
	v_exp_f32_e32 v130, v130
	v_exp_f32_e32 v131, v131
	v_cvt_pk_bf16_f32 v132, v136, v137
	v_cvt_pk_bf16_f32 v133, v138, v139
	v_cvt_pk_bf16_f32 v135, v170, v171
	ds_read_b128 v[170:173], v152 offset:10240
	v_cvt_pk_bf16_f32 v136, v124, v125
	v_cvt_pk_bf16_f32 v137, v126, v127
	v_cvt_pk_bf16_f32 v138, v128, v129
	v_cvt_pk_bf16_f32 v139, v130, v131
	v_pk_add_f32 v[124:125], v[124:125], 0 op_sel_hi:[1,0]
	s_nop 0
	v_pk_add_f32 v[124:125], v[126:127], v[124:125]
	s_nop 0
	v_pk_add_f32 v[124:125], v[128:129], v[124:125]
	s_nop 0
	v_pk_add_f32 v[124:125], v[130:131], v[124:125]
	s_nop 0
	v_add_f32_e32 v124, v124, v125
	ds_read_b128 v[126:129], v152 offset:12288
	s_waitcnt lgkmcnt(2)
	v_mfma_f32_16x16x32_bf16 v[80:83], v[166:169], v[132:135], v[80:83]
	v_mfma_f32_16x16x32_bf16 v[76:79], v[166:169], v[136:139], v[76:79]
	ds_read_b128 v[166:169], v152 offset:14336
	s_waitcnt lgkmcnt(2)
	v_mfma_f32_16x16x32_bf16 v[72:75], v[170:173], v[132:135], v[72:75]
	v_mfma_f32_16x16x32_bf16 v[68:71], v[170:173], v[136:139], v[68:71]
	ds_read_b128 v[170:173], v152 offset:16384
	s_waitcnt lgkmcnt(2)
	v_mfma_f32_16x16x32_bf16 v[64:67], v[126:129], v[132:135], v[64:67]
	v_mfma_f32_16x16x32_bf16 v[60:63], v[126:129], v[136:139], v[60:63]
	ds_read_b128 v[126:129], v152 offset:18432
	s_waitcnt lgkmcnt(2)
	v_mfma_f32_16x16x32_bf16 v[56:59], v[166:169], v[132:135], v[56:59]
	v_mfma_f32_16x16x32_bf16 v[52:55], v[166:169], v[136:139], v[52:55]
	ds_read_b128 v[166:169], v152 offset:20480
	s_waitcnt lgkmcnt(2)
	v_mfma_f32_16x16x32_bf16 v[48:51], v[170:173], v[132:135], v[48:51]
	v_mfma_f32_16x16x32_bf16 v[44:47], v[170:173], v[136:139], v[44:47]
	ds_read_b128 v[170:173], v152 offset:22528
	s_waitcnt lgkmcnt(2)
	v_mfma_f32_16x16x32_bf16 v[40:43], v[126:129], v[132:135], v[40:43]
	v_mfma_f32_16x16x32_bf16 v[32:35], v[126:129], v[136:139], v[32:35]
	s_waitcnt lgkmcnt(1)
	v_mfma_f32_16x16x32_bf16 v[36:39], v[166:169], v[132:135], v[36:39]
	v_mfma_f32_16x16x32_bf16 v[24:27], v[166:169], v[136:139], v[24:27]
	s_waitcnt lgkmcnt(0)
	v_mfma_f32_16x16x32_bf16 v[28:31], v[170:173], v[132:135], v[28:31]
	v_max3_f32 v132, v116, v117, v118
	v_add_f32_e32 v133, 0x41000000, v165
	v_max3_f32 v132, v132, v119, v120
	v_mfma_f32_16x16x32_bf16 v[20:23], v[170:173], v[136:139], v[20:23]
	v_max3_f32 v132, v132, v121, v122
	v_max3_f32 v132, v132, v123, v123
	v_mul_f32_e32 v132, 0x3e38aa3b, v132
	v_cmp_gt_f32_e32 vcc, v132, v133
	s_cbranch_vccz .LBB0_592
	ds_swizzle_b32 v3, v132 offset:swizzle(SWAP,16)
	v_max_f32_e32 v132, v132, v132
	s_waitcnt lgkmcnt(0)
	v_max_f32_e32 v3, v3, v3
	v_max_f32_e32 v3, v132, v3
	ds_bpermute_b32 v132, v156, v3
	s_waitcnt lgkmcnt(0)
	v_max3_f32 v154, v165, v3, v132
	v_sub_f32_e32 v3, v165, v154
	v_exp_f32_e32 v132, v3
	v_mov_b32_e32 v3, v155
	v_mov_b32_e32 v165, v154
	v_mul_f32_e32 v0, v0, v132
	v_pk_mul_f32 v[82:83], v[82:83], v[132:133] op_sel_hi:[1,0]
	v_pk_mul_f32 v[80:81], v[80:81], v[132:133] op_sel_hi:[1,0]
	v_pk_mul_f32 v[74:75], v[74:75], v[132:133] op_sel_hi:[1,0]
	v_pk_mul_f32 v[72:73], v[72:73], v[132:133] op_sel_hi:[1,0]
	v_pk_mul_f32 v[66:67], v[66:67], v[132:133] op_sel_hi:[1,0]
	v_pk_mul_f32 v[64:65], v[64:65], v[132:133] op_sel_hi:[1,0]
	v_pk_mul_f32 v[58:59], v[58:59], v[132:133] op_sel_hi:[1,0]
	v_pk_mul_f32 v[56:57], v[56:57], v[132:133] op_sel_hi:[1,0]
	v_pk_mul_f32 v[50:51], v[50:51], v[132:133] op_sel_hi:[1,0]
	v_pk_mul_f32 v[48:49], v[48:49], v[132:133] op_sel_hi:[1,0]
	v_pk_mul_f32 v[42:43], v[42:43], v[132:133] op_sel_hi:[1,0]
	v_pk_mul_f32 v[40:41], v[40:41], v[132:133] op_sel_hi:[1,0]
	v_pk_mul_f32 v[38:39], v[38:39], v[132:133] op_sel_hi:[1,0]
	v_pk_mul_f32 v[36:37], v[36:37], v[132:133] op_sel_hi:[1,0]
	v_pk_mul_f32 v[30:31], v[30:31], v[132:133] op_sel_hi:[1,0]
	v_pk_mul_f32 v[28:29], v[28:29], v[132:133] op_sel_hi:[1,0]
.LBB0_592:
	v_add_f32_e32 v126, 0x41000000, v3
	v_max3_f32 v125, v108, v109, v110
	v_add_f32_e32 v124, v158, v124
	v_max3_f32 v125, v125, v111, v112
	v_max3_f32 v125, v125, v113, v114
	v_max3_f32 v125, v125, v115, v115
	v_mul_f32_e32 v125, 0x3e38aa3b, v125
	v_cmp_gt_f32_e32 vcc, v125, v126
	s_cbranch_vccz .LBB0_594
	ds_swizzle_b32 v126, v125 offset:swizzle(SWAP,16)
	v_max_f32_e32 v125, v125, v125
	s_waitcnt lgkmcnt(0)
	v_max_f32_e32 v126, v126, v126
	v_max_f32_e32 v125, v125, v126
	ds_bpermute_b32 v126, v156, v125
	s_waitcnt lgkmcnt(0)
	v_max3_f32 v155, v3, v125, v126
	v_sub_f32_e32 v3, v3, v155
	v_exp_f32_e32 v126, v3
	v_mov_b32_e32 v3, v155
	v_mul_f32_e32 v124, v124, v126
	v_pk_mul_f32 v[78:79], v[78:79], v[126:127] op_sel_hi:[1,0]
	v_pk_mul_f32 v[76:77], v[76:77], v[126:127] op_sel_hi:[1,0]
	v_pk_mul_f32 v[70:71], v[70:71], v[126:127] op_sel_hi:[1,0]
	v_pk_mul_f32 v[68:69], v[68:69], v[126:127] op_sel_hi:[1,0]
	v_pk_mul_f32 v[62:63], v[62:63], v[126:127] op_sel_hi:[1,0]
	v_pk_mul_f32 v[60:61], v[60:61], v[126:127] op_sel_hi:[1,0]
	v_pk_mul_f32 v[54:55], v[54:55], v[126:127] op_sel_hi:[1,0]
	v_pk_mul_f32 v[52:53], v[52:53], v[126:127] op_sel_hi:[1,0]
	v_pk_mul_f32 v[46:47], v[46:47], v[126:127] op_sel_hi:[1,0]
	v_pk_mul_f32 v[44:45], v[44:45], v[126:127] op_sel_hi:[1,0]
	v_pk_mul_f32 v[34:35], v[34:35], v[126:127] op_sel_hi:[1,0]
	v_pk_mul_f32 v[32:33], v[32:33], v[126:127] op_sel_hi:[1,0]
	v_pk_mul_f32 v[26:27], v[26:27], v[126:127] op_sel_hi:[1,0]
	v_pk_mul_f32 v[24:25], v[24:25], v[126:127] op_sel_hi:[1,0]
	v_pk_mul_f32 v[22:23], v[22:23], v[126:127] op_sel_hi:[1,0]
	v_pk_mul_f32 v[20:21], v[20:21], v[126:127] op_sel_hi:[1,0]

.LBB0_596:
	v_add3_u32 v2, s0, v159, v160
	s_waitcnt lgkmcnt(0)
	s_barrier
	ds_read_b128 v[84:87], v2
	ds_read_b128 v[92:95], v2 offset:2048
	v_add3_u32 v116, s0, v157, v160
	ds_read_b128 v[100:103], v116
	s_waitcnt lgkmcnt(2)
	v_mfma_f32_16x16x32_bf16 v[88:91], v[84:87], v[12:15], 0
	v_mfma_f32_16x16x32_bf16 v[84:87], v[84:87], v[16:19], 0
	s_waitcnt lgkmcnt(0)
	v_mfma_f32_16x16x32_bf16 v[112:115], v[100:103], v[4:7], v[88:91]
	v_mfma_f32_16x16x32_bf16 v[100:103], v[100:103], v[8:11], v[84:87]
	s_nop 4
	ds_read_b128 v[84:87], v116 offset:2048
	v_mfma_f32_16x16x32_bf16 v[96:99], v[92:95], v[12:15], 0
	v_mfma_f32_16x16x32_bf16 v[92:95], v[92:95], v[16:19], 0
	s_waitcnt lgkmcnt(0)
	v_mfma_f32_16x16x32_bf16 v[108:111], v[84:87], v[4:7], v[96:99]
	v_mfma_f32_16x16x32_bf16 v[104:107], v[84:87], v[8:11], v[92:95]
	ds_read_b128 v[84:87], v2 offset:4096
	s_nop 3
	ds_read_b128 v[92:95], v2 offset:6144
	s_waitcnt lgkmcnt(1)
	v_mfma_f32_16x16x32_bf16 v[88:91], v[84:87], v[12:15], 0
	v_max3_f32 v2, v112, v113, v114
	v_max3_f32 v2, v2, v115, v108
	v_mfma_f32_16x16x32_bf16 v[84:87], v[84:87], v[16:19], 0
	v_max3_f32 v2, v2, v109, v110
	v_max3_f32 v2, v2, v111, v111
	s_waitcnt lgkmcnt(0)
	v_mfma_f32_16x16x32_bf16 v[12:15], v[92:95], v[12:15], 0
	v_mul_f32_e32 v2, 0x3e38aa3b, v2
	v_mfma_f32_16x16x32_bf16 v[16:19], v[92:95], v[16:19], 0
	ds_read_b128 v[92:95], v116 offset:4096
	s_waitcnt lgkmcnt(0)
	v_mfma_f32_16x16x32_bf16 v[96:99], v[92:95], v[4:7], v[88:91]
	v_mfma_f32_16x16x32_bf16 v[88:91], v[92:95], v[8:11], v[84:87]
	s_nop 2
	ds_read_b128 v[84:87], v116 offset:6144
	s_waitcnt lgkmcnt(0)
	v_mfma_f32_16x16x32_bf16 v[92:95], v[84:87], v[4:7], v[12:15]
	v_add_f32_e32 v4, 0x41000000, v152
	v_cmp_gt_f32_e32 vcc, v2, v4
	v_mfma_f32_16x16x32_bf16 v[84:87], v[84:87], v[8:11], v[16:19]
	s_cbranch_vccz .LBB0_598
	ds_swizzle_b32 v3, v2 offset:swizzle(SWAP,16)
	v_max_f32_e32 v2, v2, v2
	v_mov_b32_e32 v117, v153
	s_waitcnt lgkmcnt(0)
	v_max_f32_e32 v3, v3, v3
	v_max_f32_e32 v2, v2, v3
	ds_bpermute_b32 v3, v156, v2
	s_waitcnt lgkmcnt(0)
	v_max3_f32 v116, v152, v2, v3
	v_sub_f32_e32 v2, v152, v116
	v_exp_f32_e32 v2, v2
	v_mov_b32_e32 v152, v116
	v_mul_f32_e32 v0, v0, v2
	v_pk_mul_f32 v[82:83], v[82:83], v[2:3] op_sel_hi:[1,0]
	v_pk_mul_f32 v[80:81], v[80:81], v[2:3] op_sel_hi:[1,0]
	v_pk_mul_f32 v[74:75], v[74:75], v[2:3] op_sel_hi:[1,0]
	v_pk_mul_f32 v[72:73], v[72:73], v[2:3] op_sel_hi:[1,0]
	v_pk_mul_f32 v[66:67], v[66:67], v[2:3] op_sel_hi:[1,0]
	v_pk_mul_f32 v[64:65], v[64:65], v[2:3] op_sel_hi:[1,0]
	v_pk_mul_f32 v[58:59], v[58:59], v[2:3] op_sel_hi:[1,0]
	v_pk_mul_f32 v[56:57], v[56:57], v[2:3] op_sel_hi:[1,0]
	v_pk_mul_f32 v[50:51], v[50:51], v[2:3] op_sel_hi:[1,0]
	v_pk_mul_f32 v[48:49], v[48:49], v[2:3] op_sel_hi:[1,0]
	v_pk_mul_f32 v[42:43], v[42:43], v[2:3] op_sel_hi:[1,0]
	v_pk_mul_f32 v[40:41], v[40:41], v[2:3] op_sel_hi:[1,0]
	v_pk_mul_f32 v[38:39], v[38:39], v[2:3] op_sel_hi:[1,0]
	v_pk_mul_f32 v[36:37], v[36:37], v[2:3] op_sel_hi:[1,0]
	v_pk_mul_f32 v[30:31], v[30:31], v[2:3] op_sel_hi:[1,0]
	v_pk_mul_f32 v[28:29], v[28:29], v[2:3] op_sel_hi:[1,0]
	v_mov_b32_e32 v3, v153
	s_branch .LBB0_599

.LBB0_599:
	v_max3_f32 v2, v100, v101, v102
	v_add_f32_e32 v4, 0x41000000, v3
	v_max3_f32 v2, v2, v103, v104
	v_max3_f32 v2, v2, v105, v106
	v_max3_f32 v2, v2, v107, v107
	v_mul_f32_e32 v2, 0x3e38aa3b, v2
	v_cmp_gt_f32_e32 vcc, v2, v4
	s_cbranch_vccz .LBB0_601
	ds_swizzle_b32 v4, v2 offset:swizzle(SWAP,16)
	v_max_f32_e32 v2, v2, v2
	s_waitcnt lgkmcnt(0)
	v_max_f32_e32 v4, v4, v4
	v_max_f32_e32 v2, v2, v4
	ds_bpermute_b32 v4, v156, v2
	s_waitcnt lgkmcnt(0)
	v_max3_f32 v117, v3, v2, v4
	v_sub_f32_e32 v2, v3, v117
	v_exp_f32_e32 v2, v2
	s_nop 0
	v_mul_f32_e32 v158, v158, v2
	v_pk_mul_f32 v[78:79], v[78:79], v[2:3] op_sel_hi:[1,0]
	v_pk_mul_f32 v[76:77], v[76:77], v[2:3] op_sel_hi:[1,0]
	v_pk_mul_f32 v[70:71], v[70:71], v[2:3] op_sel_hi:[1,0]
	v_pk_mul_f32 v[68:69], v[68:69], v[2:3] op_sel_hi:[1,0]
	v_pk_mul_f32 v[62:63], v[62:63], v[2:3] op_sel_hi:[1,0]
	v_pk_mul_f32 v[60:61], v[60:61], v[2:3] op_sel_hi:[1,0]
	v_pk_mul_f32 v[54:55], v[54:55], v[2:3] op_sel_hi:[1,0]
	v_pk_mul_f32 v[52:53], v[52:53], v[2:3] op_sel_hi:[1,0]
	v_pk_mul_f32 v[46:47], v[46:47], v[2:3] op_sel_hi:[1,0]
	v_pk_mul_f32 v[44:45], v[44:45], v[2:3] op_sel_hi:[1,0]
	v_pk_mul_f32 v[34:35], v[34:35], v[2:3] op_sel_hi:[1,0]
	v_pk_mul_f32 v[32:33], v[32:33], v[2:3] op_sel_hi:[1,0]
	v_pk_mul_f32 v[26:27], v[26:27], v[2:3] op_sel_hi:[1,0]
	v_pk_mul_f32 v[24:25], v[24:25], v[2:3] op_sel_hi:[1,0]
	v_pk_mul_f32 v[22:23], v[22:23], v[2:3] op_sel_hi:[1,0]
	v_pk_mul_f32 v[20:21], v[20:21], v[2:3] op_sel_hi:[1,0]
	v_mov_b32_e32 v3, v117
	s_branch .LBB0_602

.LBB0_602:
	v_fma_f32 v2, v112, s72, -v152
	v_exp_f32_e32 v4, v2
	v_fma_f32 v2, v113, s72, -v152
	v_exp_f32_e32 v5, v2
	v_fma_f32 v2, v114, s72, -v152
	v_exp_f32_e32 v6, v2
	v_fma_f32 v2, v115, s72, -v152
	v_exp_f32_e32 v7, v2
	v_fma_f32 v2, v108, s72, -v152
	v_exp_f32_e32 v10, v2
	v_fma_f32 v2, v109, s72, -v152
	v_exp_f32_e32 v11, v2
	v_fma_f32 v2, v110, s72, -v152
	v_exp_f32_e32 v16, v2
	v_fma_f32 v2, v111, s72, -v152
	v_pk_add_f32 v[8:9], v[4:5], 0 op_sel_hi:[1,0]
	v_exp_f32_e32 v17, v2
	v_cvt_pk_bf16_f32 v12, v4, v5
	v_fma_f32 v4, v100, s72, -v3
	v_exp_f32_e32 v100, v4
	v_fma_f32 v4, v101, s72, -v3
	v_pk_add_f32 v[8:9], v[6:7], v[8:9]
	v_exp_f32_e32 v101, v4
	v_fma_f32 v4, v102, s72, -v3
	v_pk_add_f32 v[8:9], v[10:11], v[8:9]
	v_exp_f32_e32 v102, v4
	v_fma_f32 v4, v103, s72, -v3
	v_pk_add_f32 v[8:9], v[16:17], v[8:9]
	v_exp_f32_e32 v103, v4
	v_fma_f32 v4, v104, s72, -v3
	v_add_f32_e32 v2, v8, v9
	v_exp_f32_e32 v104, v4
	v_fma_f32 v4, v105, s72, -v3
	v_add_f32_e32 v2, v0, v2
	v_add_u32_e32 v0, s0, v160
	v_exp_f32_e32 v105, v4
	v_fma_f32 v4, v106, s72, -v3
	v_exp_f32_e32 v106, v4
	v_fma_f32 v4, v107, s72, -v3
	v_add_u32_e32 v108, v0, v159
	v_cvt_pk_bf16_f32 v13, v6, v7
	v_exp_f32_e32 v107, v4
	ds_read_b128 v[4:7], v108 offset:8192
	v_cvt_pk_bf16_f32 v14, v10, v11
	v_cvt_pk_bf16_f32 v15, v16, v17
	v_cvt_pk_bf16_f32 v16, v100, v101
	v_cvt_pk_bf16_f32 v17, v102, v103
	v_cvt_pk_bf16_f32 v18, v104, v105
	v_cvt_pk_bf16_f32 v19, v106, v107
	s_waitcnt lgkmcnt(0)
	v_mfma_f32_16x16x32_bf16 v[80:83], v[4:7], v[12:15], v[80:83]
	v_mfma_f32_16x16x32_bf16 v[76:79], v[4:7], v[16:19], v[76:79]
	ds_read_b128 v[4:7], v108 offset:10240
	s_waitcnt lgkmcnt(0)
	v_mfma_f32_16x16x32_bf16 v[72:75], v[4:7], v[12:15], v[72:75]
	v_mfma_f32_16x16x32_bf16 v[68:71], v[4:7], v[16:19], v[68:71]
	ds_read_b128 v[4:7], v108 offset:12288
	s_waitcnt lgkmcnt(0)
	v_mfma_f32_16x16x32_bf16 v[64:67], v[4:7], v[12:15], v[64:67]
	v_mfma_f32_16x16x32_bf16 v[60:63], v[4:7], v[16:19], v[60:63]
	ds_read_b128 v[4:7], v108 offset:14336
	s_waitcnt lgkmcnt(0)
	v_mfma_f32_16x16x32_bf16 v[56:59], v[4:7], v[12:15], v[56:59]
	v_mfma_f32_16x16x32_bf16 v[52:55], v[4:7], v[16:19], v[52:55]
	ds_read_b128 v[4:7], v108 offset:16384
	s_waitcnt lgkmcnt(0)
	v_mfma_f32_16x16x32_bf16 v[48:51], v[4:7], v[12:15], v[48:51]
	v_mfma_f32_16x16x32_bf16 v[44:47], v[4:7], v[16:19], v[44:47]
	ds_read_b128 v[4:7], v108 offset:18432
	s_waitcnt lgkmcnt(0)
	v_mfma_f32_16x16x32_bf16 v[40:43], v[4:7], v[12:15], v[40:43]
	v_mfma_f32_16x16x32_bf16 v[32:35], v[4:7], v[16:19], v[32:35]
	ds_read_b128 v[4:7], v108 offset:20480
	s_waitcnt lgkmcnt(0)
	v_mfma_f32_16x16x32_bf16 v[8:11], v[4:7], v[12:15], v[36:39]
	v_mfma_f32_16x16x32_bf16 v[4:7], v[4:7], v[16:19], v[24:27]
	s_nop 2
	ds_read_b128 v[24:27], v108 offset:22528
	s_waitcnt lgkmcnt(0)
	v_mfma_f32_16x16x32_bf16 v[16:19], v[24:27], v[16:19], v[20:23]
	v_max3_f32 v20, v96, v97, v98
	s_nop 2
	v_add_f32_e32 v21, 0x41000000, v116
	v_max3_f32 v20, v20, v99, v92
	v_mfma_f32_16x16x32_bf16 v[12:15], v[24:27], v[12:15], v[28:31]
	v_max3_f32 v20, v20, v93, v94
	v_max3_f32 v20, v20, v95, v95
	v_mul_f32_e32 v20, 0x3e38aa3b, v20
	v_cmp_gt_f32_e32 vcc, v20, v21
	s_cbranch_vccz .LBB0_604
	ds_swizzle_b32 v3, v20 offset:swizzle(SWAP,16)
	v_max_f32_e32 v20, v20, v20
	s_waitcnt lgkmcnt(0)
	v_max_f32_e32 v3, v3, v3
	v_max_f32_e32 v3, v20, v3
	ds_bpermute_b32 v20, v156, v3
	s_waitcnt lgkmcnt(0)
	v_max3_f32 v21, v116, v3, v20
	v_sub_f32_e32 v3, v116, v21
	v_exp_f32_e32 v20, v3
	v_mov_b32_e32 v3, v117
	v_mov_b32_e32 v116, v21
	v_mul_f32_e32 v2, v2, v20
	v_pk_mul_f32 v[82:83], v[82:83], v[20:21] op_sel_hi:[1,0]
	v_pk_mul_f32 v[80:81], v[80:81], v[20:21] op_sel_hi:[1,0]
	v_pk_mul_f32 v[74:75], v[74:75], v[20:21] op_sel_hi:[1,0]
	v_pk_mul_f32 v[72:73], v[72:73], v[20:21] op_sel_hi:[1,0]
	v_pk_mul_f32 v[66:67], v[66:67], v[20:21] op_sel_hi:[1,0]
	v_pk_mul_f32 v[64:65], v[64:65], v[20:21] op_sel_hi:[1,0]
	v_pk_mul_f32 v[58:59], v[58:59], v[20:21] op_sel_hi:[1,0]
	v_pk_mul_f32 v[56:57], v[56:57], v[20:21] op_sel_hi:[1,0]
	v_pk_mul_f32 v[50:51], v[50:51], v[20:21] op_sel_hi:[1,0]
	v_pk_mul_f32 v[48:49], v[48:49], v[20:21] op_sel_hi:[1,0]
	v_pk_mul_f32 v[42:43], v[42:43], v[20:21] op_sel_hi:[1,0]
	v_pk_mul_f32 v[40:41], v[40:41], v[20:21] op_sel_hi:[1,0]
	v_pk_mul_f32 v[10:11], v[10:11], v[20:21] op_sel_hi:[1,0]
	v_pk_mul_f32 v[8:9], v[8:9], v[20:21] op_sel_hi:[1,0]
	v_pk_mul_f32 v[14:15], v[14:15], v[20:21] op_sel_hi:[1,0]
	v_pk_mul_f32 v[12:13], v[12:13], v[20:21] op_sel_hi:[1,0]
.LBB0_604:
	v_pk_add_f32 v[20:21], v[100:101], 0 op_sel_hi:[1,0]
	s_nop 0
	v_pk_add_f32 v[20:21], v[102:103], v[20:21]
	s_nop 0
	v_pk_add_f32 v[20:21], v[104:105], v[20:21]
	s_nop 0
	v_pk_add_f32 v[20:21], v[106:107], v[20:21]
	s_nop 0
	v_add_f32_e32 v20, v20, v21
	v_add_f32_e32 v24, v158, v20
	v_max3_f32 v20, v88, v89, v90
	v_add_f32_e32 v21, 0x41000000, v3
	v_max3_f32 v20, v20, v91, v84
	v_max3_f32 v20, v20, v85, v86
	v_max3_f32 v20, v20, v87, v87
	v_mul_f32_e32 v20, 0x3e38aa3b, v20
	v_cmp_gt_f32_e32 vcc, v20, v21
	s_cbranch_vccz .LBB0_606
	ds_swizzle_b32 v21, v20 offset:swizzle(SWAP,16)
	v_max_f32_e32 v20, v20, v20
	s_waitcnt lgkmcnt(0)
	v_max_f32_e32 v21, v21, v21
	v_max_f32_e32 v20, v20, v21
	ds_bpermute_b32 v21, v156, v20
	s_waitcnt lgkmcnt(0)
	v_max3_f32 v21, v3, v20, v21
	v_sub_f32_e32 v3, v3, v21
	v_exp_f32_e32 v20, v3
	v_mov_b32_e32 v3, v21
	v_mul_f32_e32 v24, v24, v20
	v_pk_mul_f32 v[78:79], v[78:79], v[20:21] op_sel_hi:[1,0]
	v_pk_mul_f32 v[76:77], v[76:77], v[20:21] op_sel_hi:[1,0]
	v_pk_mul_f32 v[70:71], v[70:71], v[20:21] op_sel_hi:[1,0]
	v_pk_mul_f32 v[68:69], v[68:69], v[20:21] op_sel_hi:[1,0]
	v_pk_mul_f32 v[62:63], v[62:63], v[20:21] op_sel_hi:[1,0]
	v_pk_mul_f32 v[60:61], v[60:61], v[20:21] op_sel_hi:[1,0]
	v_pk_mul_f32 v[54:55], v[54:55], v[20:21] op_sel_hi:[1,0]
	v_pk_mul_f32 v[52:53], v[52:53], v[20:21] op_sel_hi:[1,0]
	v_pk_mul_f32 v[46:47], v[46:47], v[20:21] op_sel_hi:[1,0]
	v_pk_mul_f32 v[44:45], v[44:45], v[20:21] op_sel_hi:[1,0]
	v_pk_mul_f32 v[34:35], v[34:35], v[20:21] op_sel_hi:[1,0]
	v_pk_mul_f32 v[32:33], v[32:33], v[20:21] op_sel_hi:[1,0]
	v_pk_mul_f32 v[6:7], v[6:7], v[20:21] op_sel_hi:[1,0]
	v_pk_mul_f32 v[4:5], v[4:5], v[20:21] op_sel_hi:[1,0]
	v_pk_mul_f32 v[18:19], v[18:19], v[20:21] op_sel_hi:[1,0]
	v_pk_mul_f32 v[16:17], v[16:17], v[20:21] op_sel_hi:[1,0]

.LBB0_611:
	s_bitcmp1_b32 s0, 0
	s_cselect_b32 s0, 0x6000, 0
	s_add_i32 s24, s0, 0
	s_add_i32 s19, s19, 64
	s_add_i32 s0, s27, 0x1000
	s_and_b64 s[22:23], s[22:23], exec
	s_cselect_b32 s42, s19, s0
	s_lshl_b32 vcc_lo, s26, 14
	s_add_u32 vcc_lo, s14, vcc_lo
	s_addc_u32 vcc_hi, s15, 0
	global_load_dwordx4 v[118:121], v192, vcc offset:128
	global_load_dwordx4 v[122:125], v193, vcc offset:128
	s_lshl_b32 vcc_lo, s42, 1
	s_add_u32 vcc_lo, s100, vcc_lo
	s_addc_u32 vcc_hi, s101, 0
	global_load_dwordx4 v[126:129], v184, vcc
	global_load_dwordx4 v[138:141], v190, vcc
	v_add3_u32 v2, s24, v205, v206
	global_load_dwordx4 v[130:133], v186, vcc
	ds_read_b128 v[142:145], v2
	ds_read_b128 v[150:153], v2 offset:2048
	global_load_dwordx4 v[134:137], v188, vcc
	v_add3_u32 v3, s24, v203, v206
	ds_read_b128 v[158:161], v3
	ds_read_b128 v[234:237], v3 offset:4096
	s_waitcnt lgkmcnt(3)
	v_mfma_f32_16x16x32_bf16 v[146:149], v[142:145], v[46:49], 0
	v_mfma_f32_16x16x32_bf16 v[142:145], v[142:145], v[50:53], 0
	s_waitcnt lgkmcnt(1)
	v_mfma_f32_16x16x32_bf16 v[170:173], v[158:161], v[38:41], v[146:149]
	v_mfma_f32_16x16x32_bf16 v[158:161], v[158:161], v[42:45], v[142:145]
	s_nop 4
	ds_read_b128 v[142:145], v3 offset:2048
	v_mfma_f32_16x16x32_bf16 v[154:157], v[150:153], v[46:49], 0
	v_mfma_f32_16x16x32_bf16 v[150:153], v[150:153], v[50:53], 0
	s_waitcnt lgkmcnt(0)
	v_mfma_f32_16x16x32_bf16 v[166:169], v[142:145], v[38:41], v[154:157]
	v_mfma_f32_16x16x32_bf16 v[162:165], v[142:145], v[42:45], v[150:153]
	ds_read_b128 v[142:145], v2 offset:4096
	s_nop 3
	ds_read_b128 v[150:153], v2 offset:6144
	s_waitcnt lgkmcnt(1)
	v_mfma_f32_16x16x32_bf16 v[146:149], v[142:145], v[46:49], 0
	v_max3_f32 v2, v170, v171, v172
	v_max3_f32 v2, v2, v173, v166
	s_waitcnt lgkmcnt(0)
	v_mfma_f32_16x16x32_bf16 v[154:157], v[150:153], v[46:49], 0
	v_max3_f32 v2, v2, v167, v168
	v_max3_f32 v2, v2, v169, v169
	v_mfma_f32_16x16x32_bf16 v[226:229], v[150:153], v[50:53], 0
	v_mul_f32_e32 v2, 0x3e38aa3b, v2
	v_mfma_f32_16x16x32_bf16 v[150:153], v[234:237], v[38:41], v[146:149]
	s_nop 2
	ds_read_b128 v[146:149], v3 offset:6144
	v_mfma_f32_16x16x32_bf16 v[142:145], v[142:145], v[50:53], 0
	v_add_f32_e32 v3, 0x41000000, v196
	v_cmp_gt_f32_e32 vcc, v2, v3
	v_mfma_f32_16x16x32_bf16 v[142:145], v[234:237], v[42:45], v[142:145]
	s_waitcnt lgkmcnt(0)
	v_mfma_f32_16x16x32_bf16 v[154:157], v[146:149], v[38:41], v[154:157]
	v_mfma_f32_16x16x32_bf16 v[146:149], v[146:149], v[42:45], v[226:229]
	s_cbranch_vccz .LBB0_613
	ds_swizzle_b32 v3, v2 offset:swizzle(SWAP,16)
	v_max_f32_e32 v2, v2, v2
	v_mov_b32_e32 v195, v197
	s_waitcnt lgkmcnt(0)
	v_max_f32_e32 v3, v3, v3
	v_max_f32_e32 v2, v2, v3
	ds_bpermute_b32 v3, v202, v2
	s_waitcnt lgkmcnt(0)
	v_max3_f32 v194, v196, v2, v3
	v_sub_f32_e32 v2, v196, v194
	v_exp_f32_e32 v2, v2
	v_mov_b32_e32 v196, v194
	v_mul_f32_e32 v0, v0, v2
	v_pk_mul_f32 v[116:117], v[116:117], v[2:3] op_sel_hi:[1,0]
	v_pk_mul_f32 v[114:115], v[114:115], v[2:3] op_sel_hi:[1,0]
	v_pk_mul_f32 v[108:109], v[108:109], v[2:3] op_sel_hi:[1,0]
	v_pk_mul_f32 v[106:107], v[106:107], v[2:3] op_sel_hi:[1,0]
	v_pk_mul_f32 v[100:101], v[100:101], v[2:3] op_sel_hi:[1,0]
	v_pk_mul_f32 v[98:99], v[98:99], v[2:3] op_sel_hi:[1,0]
	v_pk_mul_f32 v[92:93], v[92:93], v[2:3] op_sel_hi:[1,0]
	v_pk_mul_f32 v[90:91], v[90:91], v[2:3] op_sel_hi:[1,0]
	v_pk_mul_f32 v[84:85], v[84:85], v[2:3] op_sel_hi:[1,0]
	v_pk_mul_f32 v[82:83], v[82:83], v[2:3] op_sel_hi:[1,0]
	v_pk_mul_f32 v[76:77], v[76:77], v[2:3] op_sel_hi:[1,0]
	v_pk_mul_f32 v[74:75], v[74:75], v[2:3] op_sel_hi:[1,0]
	v_pk_mul_f32 v[72:73], v[72:73], v[2:3] op_sel_hi:[1,0]
	v_pk_mul_f32 v[70:71], v[70:71], v[2:3] op_sel_hi:[1,0]
	v_pk_mul_f32 v[64:65], v[64:65], v[2:3] op_sel_hi:[1,0]
	v_pk_mul_f32 v[62:63], v[62:63], v[2:3] op_sel_hi:[1,0]
	s_branch .LBB0_614

.LBB0_614:
	v_max3_f32 v2, v158, v159, v160
	v_add_f32_e32 v3, 0x41000000, v195
	v_max3_f32 v2, v2, v161, v162
	v_max3_f32 v2, v2, v163, v164
	v_max3_f32 v2, v2, v165, v165
	v_mul_f32_e32 v2, 0x3e38aa3b, v2
	v_cmp_gt_f32_e32 vcc, v2, v3
	s_cbranch_vccz .LBB0_616
	ds_swizzle_b32 v3, v2 offset:swizzle(SWAP,16)
	v_max_f32_e32 v2, v2, v2
	v_mov_b32_e32 v179, v194
	s_waitcnt lgkmcnt(0)
	v_max_f32_e32 v3, v3, v3
	v_max_f32_e32 v2, v2, v3
	ds_bpermute_b32 v3, v202, v2
	s_waitcnt lgkmcnt(0)
	v_max3_f32 v197, v195, v2, v3
	v_sub_f32_e32 v2, v195, v197
	v_exp_f32_e32 v2, v2
	v_mov_b32_e32 v195, v197
	v_mul_f32_e32 v204, v204, v2
	v_pk_mul_f32 v[112:113], v[112:113], v[2:3] op_sel_hi:[1,0]
	v_pk_mul_f32 v[110:111], v[110:111], v[2:3] op_sel_hi:[1,0]
	v_pk_mul_f32 v[104:105], v[104:105], v[2:3] op_sel_hi:[1,0]
	v_pk_mul_f32 v[102:103], v[102:103], v[2:3] op_sel_hi:[1,0]
	v_pk_mul_f32 v[96:97], v[96:97], v[2:3] op_sel_hi:[1,0]
	v_pk_mul_f32 v[94:95], v[94:95], v[2:3] op_sel_hi:[1,0]
	v_pk_mul_f32 v[88:89], v[88:89], v[2:3] op_sel_hi:[1,0]
	v_pk_mul_f32 v[86:87], v[86:87], v[2:3] op_sel_hi:[1,0]
	v_pk_mul_f32 v[80:81], v[80:81], v[2:3] op_sel_hi:[1,0]
	v_pk_mul_f32 v[78:79], v[78:79], v[2:3] op_sel_hi:[1,0]
	v_pk_mul_f32 v[68:69], v[68:69], v[2:3] op_sel_hi:[1,0]
	v_pk_mul_f32 v[66:67], v[66:67], v[2:3] op_sel_hi:[1,0]
	v_pk_mul_f32 v[60:61], v[60:61], v[2:3] op_sel_hi:[1,0]
	v_pk_mul_f32 v[58:59], v[58:59], v[2:3] op_sel_hi:[1,0]
	v_pk_mul_f32 v[56:57], v[56:57], v[2:3] op_sel_hi:[1,0]
	v_pk_mul_f32 v[54:55], v[54:55], v[2:3] op_sel_hi:[1,0]
	s_branch .LBB0_617

.LBB0_617:
	v_mov_b64_e32 v[2:3], v[194:195]
	v_pk_fma_f32 v[170:171], v[170:171], s[98:99], v[196:197] op_sel_hi:[1,1,0] neg_lo:[0,0,1] neg_hi:[0,0,1]
	v_pk_fma_f32 v[172:173], v[172:173], s[98:99], v[196:197] op_sel_hi:[1,1,0] neg_lo:[0,0,1] neg_hi:[0,0,1]
	v_pk_fma_f32 v[166:167], v[166:167], s[98:99], v[196:197] op_sel_hi:[1,1,0] neg_lo:[0,0,1] neg_hi:[0,0,1]
	v_pk_fma_f32 v[168:169], v[168:169], s[98:99], v[196:197] op_sel_hi:[1,1,0] neg_lo:[0,0,1] neg_hi:[0,0,1]
	v_exp_f32_e32 v170, v170
	v_exp_f32_e32 v171, v171
	v_exp_f32_e32 v172, v172
	v_exp_f32_e32 v173, v173
	v_exp_f32_e32 v166, v166
	v_exp_f32_e32 v167, v167
	v_exp_f32_e32 v214, v168
	v_exp_f32_e32 v215, v169
	v_pk_add_f32 v[212:213], v[170:171], 0 op_sel_hi:[1,0]
	v_fma_f32 v158, v158, s72, -v195
	v_fma_f32 v159, v159, s72, -v195
	v_pk_add_f32 v[212:213], v[172:173], v[212:213]
	v_fma_f32 v160, v160, s72, -v195
	v_fma_f32 v161, v161, s72, -v195
	v_pk_add_f32 v[168:169], v[166:167], v[212:213]
	v_fma_f32 v162, v162, s72, -v195
	v_fma_f32 v163, v163, s72, -v195
	v_pk_add_f32 v[168:169], v[214:215], v[168:169]
	v_fma_f32 v164, v164, s72, -v195
	v_fma_f32 v165, v165, s72, -v195
	v_add_f32_e32 v168, v168, v169
	v_add_f32_e32 v0, v0, v168
	v_cvt_pk_bf16_f32 v168, v170, v171
	v_cvt_pk_bf16_f32 v170, v166, v167
	v_add_u32_e32 v166, s24, v206
	v_add_u32_e32 v167, v166, v205
	ds_read_b128 v[234:237], v167 offset:8192
	v_exp_f32_e32 v158, v158
	v_exp_f32_e32 v159, v159
	v_exp_f32_e32 v160, v160
	v_exp_f32_e32 v161, v161
	v_exp_f32_e32 v162, v162
	v_exp_f32_e32 v163, v163
	v_exp_f32_e32 v164, v164
	v_exp_f32_e32 v165, v165
	v_cvt_pk_bf16_f32 v169, v172, v173
	v_cvt_pk_bf16_f32 v171, v214, v215
	ds_read_b128 v[212:215], v167 offset:10240
	v_cvt_pk_bf16_f32 v226, v158, v159
	v_cvt_pk_bf16_f32 v227, v160, v161
	v_cvt_pk_bf16_f32 v228, v162, v163
	v_cvt_pk_bf16_f32 v229, v164, v165
	v_pk_add_f32 v[158:159], v[158:159], 0 op_sel_hi:[1,0]
	s_nop 0
	v_pk_add_f32 v[158:159], v[160:161], v[158:159]
	s_nop 0
	v_pk_add_f32 v[158:159], v[162:163], v[158:159]
	s_nop 0
	v_pk_add_f32 v[158:159], v[164:165], v[158:159]
	s_nop 0
	v_add_f32_e32 v158, v158, v159
	ds_read_b128 v[160:163], v167 offset:12288
	s_waitcnt lgkmcnt(2)
	v_mfma_f32_16x16x32_bf16 v[114:117], v[234:237], v[168:171], v[114:117]
	v_mfma_f32_16x16x32_bf16 v[110:113], v[234:237], v[226:229], v[110:113]
	ds_read_b128 v[234:237], v167 offset:14336
	s_waitcnt lgkmcnt(2)
	v_mfma_f32_16x16x32_bf16 v[106:109], v[212:215], v[168:171], v[106:109]
	v_mfma_f32_16x16x32_bf16 v[102:105], v[212:215], v[226:229], v[102:105]
	ds_read_b128 v[212:215], v167 offset:16384
	s_waitcnt lgkmcnt(2)
	v_mfma_f32_16x16x32_bf16 v[98:101], v[160:163], v[168:171], v[98:101]
	v_mfma_f32_16x16x32_bf16 v[94:97], v[160:163], v[226:229], v[94:97]
	ds_read_b128 v[160:163], v167 offset:18432
	s_waitcnt lgkmcnt(2)
	v_mfma_f32_16x16x32_bf16 v[90:93], v[234:237], v[168:171], v[90:93]
	v_mfma_f32_16x16x32_bf16 v[86:89], v[234:237], v[226:229], v[86:89]
	ds_read_b128 v[234:237], v167 offset:20480
	s_waitcnt lgkmcnt(2)
	v_mfma_f32_16x16x32_bf16 v[82:85], v[212:215], v[168:171], v[82:85]
	v_mfma_f32_16x16x32_bf16 v[78:81], v[212:215], v[226:229], v[78:81]
	ds_read_b128 v[212:215], v167 offset:22528
	s_waitcnt lgkmcnt(2)
	v_mfma_f32_16x16x32_bf16 v[74:77], v[160:163], v[168:171], v[74:77]
	v_mfma_f32_16x16x32_bf16 v[66:69], v[160:163], v[226:229], v[66:69]
	s_waitcnt lgkmcnt(1)
	v_mfma_f32_16x16x32_bf16 v[70:73], v[234:237], v[168:171], v[70:73]
	v_mfma_f32_16x16x32_bf16 v[58:61], v[234:237], v[226:229], v[58:61]
	v_max3_f32 v167, v150, v151, v152
	v_max3_f32 v167, v167, v153, v154
	s_waitcnt lgkmcnt(0)
	v_mfma_f32_16x16x32_bf16 v[62:65], v[212:215], v[168:171], v[62:65]
	v_max3_f32 v167, v167, v155, v156
	v_add_f32_e32 v168, 0x41000000, v179
	v_max3_f32 v167, v167, v157, v157
	v_mfma_f32_16x16x32_bf16 v[54:57], v[212:215], v[226:229], v[54:57]
	v_mul_f32_e32 v167, 0x3e38aa3b, v167
	v_cmp_gt_f32_e32 vcc, v167, v168
	s_cbranch_vccz .LBB0_619
	ds_swizzle_b32 v2, v167 offset:swizzle(SWAP,16)
	v_max_f32_e32 v167, v167, v167
	v_mov_b32_e32 v195, v3
	s_waitcnt lgkmcnt(0)
	v_max_f32_e32 v2, v2, v2
	v_max_f32_e32 v2, v167, v2
	ds_bpermute_b32 v167, v202, v2
	s_waitcnt lgkmcnt(0)
	v_max3_f32 v2, v179, v2, v167
	v_sub_f32_e32 v167, v179, v2
	v_exp_f32_e32 v168, v167
	v_mov_b32_e32 v179, v2
	v_mul_f32_e32 v0, v0, v168
	v_pk_mul_f32 v[116:117], v[116:117], v[168:169] op_sel_hi:[1,0]
	v_pk_mul_f32 v[114:115], v[114:115], v[168:169] op_sel_hi:[1,0]
	v_pk_mul_f32 v[108:109], v[108:109], v[168:169] op_sel_hi:[1,0]
	v_pk_mul_f32 v[106:107], v[106:107], v[168:169] op_sel_hi:[1,0]
	v_pk_mul_f32 v[100:101], v[100:101], v[168:169] op_sel_hi:[1,0]
	v_pk_mul_f32 v[98:99], v[98:99], v[168:169] op_sel_hi:[1,0]
	v_pk_mul_f32 v[92:93], v[92:93], v[168:169] op_sel_hi:[1,0]
	v_pk_mul_f32 v[90:91], v[90:91], v[168:169] op_sel_hi:[1,0]
	v_pk_mul_f32 v[84:85], v[84:85], v[168:169] op_sel_hi:[1,0]
	v_pk_mul_f32 v[82:83], v[82:83], v[168:169] op_sel_hi:[1,0]
	v_pk_mul_f32 v[76:77], v[76:77], v[168:169] op_sel_hi:[1,0]
	v_pk_mul_f32 v[74:75], v[74:75], v[168:169] op_sel_hi:[1,0]
	v_pk_mul_f32 v[72:73], v[72:73], v[168:169] op_sel_hi:[1,0]
	v_pk_mul_f32 v[70:71], v[70:71], v[168:169] op_sel_hi:[1,0]
	v_pk_mul_f32 v[64:65], v[64:65], v[168:169] op_sel_hi:[1,0]
	v_pk_mul_f32 v[62:63], v[62:63], v[168:169] op_sel_hi:[1,0]
.LBB0_619:
	v_add_f32_e32 v160, 0x41000000, v195
	v_max3_f32 v159, v142, v143, v144
	v_add_f32_e32 v158, v204, v158
	v_max3_f32 v159, v159, v145, v146
	v_max3_f32 v159, v159, v147, v148
	v_max3_f32 v159, v159, v149, v149
	v_mul_f32_e32 v159, 0x3e38aa3b, v159
	v_cmp_gt_f32_e32 vcc, v159, v160
	s_cbranch_vccz .LBB0_621
	ds_swizzle_b32 v3, v159 offset:swizzle(SWAP,16)
	v_max_f32_e32 v159, v159, v159
	s_waitcnt lgkmcnt(0)
	v_max_f32_e32 v3, v3, v3
	v_max_f32_e32 v3, v159, v3
	ds_bpermute_b32 v159, v202, v3
	s_waitcnt lgkmcnt(0)
	v_max3_f32 v3, v195, v3, v159
	v_sub_f32_e32 v159, v195, v3
	v_exp_f32_e32 v160, v159
	v_mov_b32_e32 v195, v3
	v_mul_f32_e32 v158, v158, v160
	v_pk_mul_f32 v[112:113], v[112:113], v[160:161] op_sel_hi:[1,0]
	v_pk_mul_f32 v[110:111], v[110:111], v[160:161] op_sel_hi:[1,0]
	v_pk_mul_f32 v[104:105], v[104:105], v[160:161] op_sel_hi:[1,0]
	v_pk_mul_f32 v[102:103], v[102:103], v[160:161] op_sel_hi:[1,0]
	v_pk_mul_f32 v[96:97], v[96:97], v[160:161] op_sel_hi:[1,0]
	v_pk_mul_f32 v[94:95], v[94:95], v[160:161] op_sel_hi:[1,0]
	v_pk_mul_f32 v[88:89], v[88:89], v[160:161] op_sel_hi:[1,0]
	v_pk_mul_f32 v[86:87], v[86:87], v[160:161] op_sel_hi:[1,0]
	v_pk_mul_f32 v[80:81], v[80:81], v[160:161] op_sel_hi:[1,0]
	v_pk_mul_f32 v[78:79], v[78:79], v[160:161] op_sel_hi:[1,0]
	v_pk_mul_f32 v[68:69], v[68:69], v[160:161] op_sel_hi:[1,0]
	v_pk_mul_f32 v[66:67], v[66:67], v[160:161] op_sel_hi:[1,0]
	v_pk_mul_f32 v[60:61], v[60:61], v[160:161] op_sel_hi:[1,0]
	v_pk_mul_f32 v[58:59], v[58:59], v[160:161] op_sel_hi:[1,0]
	v_pk_mul_f32 v[56:57], v[56:57], v[160:161] op_sel_hi:[1,0]
	v_pk_mul_f32 v[54:55], v[54:55], v[160:161] op_sel_hi:[1,0]

.LBB0_623:
	v_mfma_f32_16x16x32_bf16 v[8:11], v[30:33], v[20:23], v[8:11]
	s_waitcnt lgkmcnt(0)
	s_barrier
	v_mfma_f32_16x16x32_bf16 v[12:15], v[34:37], v[20:23], v[12:15]
	v_mfma_f32_16x16x32_bf16 v[22:25], v[30:33], v[26:29], v[4:7]
	s_nop 2
	v_add3_u32 v6, s0, v205, v206
	ds_read_b128 v[2:5], v6
	ds_read_b128 v[30:33], v6 offset:2048
	v_add3_u32 v7, s0, v203, v206
	ds_read_b128 v[118:121], v7
	v_mfma_f32_16x16x32_bf16 v[18:21], v[34:37], v[26:29], v[16:19]
	s_waitcnt lgkmcnt(2)
	v_mfma_f32_16x16x32_bf16 v[26:29], v[2:5], v[46:49], 0
	v_mfma_f32_16x16x32_bf16 v[2:5], v[2:5], v[50:53], 0
	s_waitcnt lgkmcnt(0)
	v_mfma_f32_16x16x32_bf16 v[130:133], v[118:121], v[38:41], v[26:29]
	v_mfma_f32_16x16x32_bf16 v[118:121], v[118:121], v[42:45], v[2:5]
	s_nop 4
	ds_read_b128 v[2:5], v7 offset:2048
	v_mfma_f32_16x16x32_bf16 v[34:37], v[30:33], v[46:49], 0
	v_mfma_f32_16x16x32_bf16 v[30:33], v[30:33], v[50:53], 0
	s_waitcnt lgkmcnt(0)
	v_mfma_f32_16x16x32_bf16 v[126:129], v[2:5], v[38:41], v[34:37]
	v_mfma_f32_16x16x32_bf16 v[122:125], v[2:5], v[42:45], v[30:33]
	ds_read_b128 v[2:5], v6 offset:4096
	s_nop 3
	ds_read_b128 v[30:33], v6 offset:6144
	s_waitcnt lgkmcnt(1)
	v_mfma_f32_16x16x32_bf16 v[26:29], v[2:5], v[46:49], 0
	v_max3_f32 v6, v130, v131, v132
	v_max3_f32 v6, v6, v133, v126
	v_mfma_f32_16x16x32_bf16 v[2:5], v[2:5], v[50:53], 0
	v_max3_f32 v6, v6, v127, v128
	v_max3_f32 v6, v6, v129, v129
	s_waitcnt lgkmcnt(0)
	v_mfma_f32_16x16x32_bf16 v[34:37], v[30:33], v[46:49], 0
	v_mul_f32_e32 v6, 0x3e38aa3b, v6
	v_mfma_f32_16x16x32_bf16 v[46:49], v[30:33], v[50:53], 0
	ds_read_b128 v[50:53], v7 offset:4096
	s_waitcnt lgkmcnt(0)
	v_mfma_f32_16x16x32_bf16 v[30:33], v[50:53], v[38:41], v[26:29]
	s_nop 2
	ds_read_b128 v[26:29], v7 offset:6144
	v_add_f32_e32 v7, 0x41000000, v196
	v_cmp_gt_f32_e32 vcc, v6, v7
	v_mfma_f32_16x16x32_bf16 v[2:5], v[50:53], v[42:45], v[2:5]
	s_waitcnt lgkmcnt(0)
	v_mfma_f32_16x16x32_bf16 v[34:37], v[26:29], v[38:41], v[34:37]
	v_mfma_f32_16x16x32_bf16 v[26:29], v[26:29], v[42:45], v[46:49]
	s_cbranch_vccz .LBB0_625
	ds_swizzle_b32 v7, v6 offset:swizzle(SWAP,16)
	v_max_f32_e32 v6, v6, v6
	v_mov_b32_e32 v195, v197
	s_waitcnt lgkmcnt(0)
	v_max_f32_e32 v7, v7, v7
	v_max_f32_e32 v6, v6, v7
	ds_bpermute_b32 v7, v202, v6
	s_waitcnt lgkmcnt(0)
	v_max3_f32 v6, v196, v6, v7
	v_sub_f32_e32 v7, v196, v6
	v_exp_f32_e32 v16, v7
	v_mov_b32_e32 v7, v197
	v_mov_b32_e32 v196, v6
	v_mul_f32_e32 v0, v0, v16
	v_pk_mul_f32 v[116:117], v[116:117], v[16:17] op_sel_hi:[1,0]
	v_pk_mul_f32 v[114:115], v[114:115], v[16:17] op_sel_hi:[1,0]
	v_pk_mul_f32 v[108:109], v[108:109], v[16:17] op_sel_hi:[1,0]
	v_pk_mul_f32 v[106:107], v[106:107], v[16:17] op_sel_hi:[1,0]
	v_pk_mul_f32 v[100:101], v[100:101], v[16:17] op_sel_hi:[1,0]
	v_pk_mul_f32 v[98:99], v[98:99], v[16:17] op_sel_hi:[1,0]
	v_pk_mul_f32 v[92:93], v[92:93], v[16:17] op_sel_hi:[1,0]
	v_pk_mul_f32 v[90:91], v[90:91], v[16:17] op_sel_hi:[1,0]
	v_pk_mul_f32 v[84:85], v[84:85], v[16:17] op_sel_hi:[1,0]
	v_pk_mul_f32 v[82:83], v[82:83], v[16:17] op_sel_hi:[1,0]
	v_pk_mul_f32 v[76:77], v[76:77], v[16:17] op_sel_hi:[1,0]
	v_pk_mul_f32 v[74:75], v[74:75], v[16:17] op_sel_hi:[1,0]
	v_pk_mul_f32 v[72:73], v[72:73], v[16:17] op_sel_hi:[1,0]
	v_pk_mul_f32 v[70:71], v[70:71], v[16:17] op_sel_hi:[1,0]
	v_pk_mul_f32 v[64:65], v[64:65], v[16:17] op_sel_hi:[1,0]
	v_pk_mul_f32 v[62:63], v[62:63], v[16:17] op_sel_hi:[1,0]
	s_branch .LBB0_626

.LBB0_626:
	v_max3_f32 v16, v118, v119, v120
	v_add_f32_e32 v17, 0x41000000, v195
	v_max3_f32 v16, v16, v121, v122
	v_max3_f32 v16, v16, v123, v124
	v_max3_f32 v16, v16, v125, v125
	v_mul_f32_e32 v16, 0x3e38aa3b, v16
	v_cmp_gt_f32_e32 vcc, v16, v17
	s_cbranch_vccz .LBB0_628
	ds_swizzle_b32 v7, v16 offset:swizzle(SWAP,16)
	v_max_f32_e32 v16, v16, v16
	s_waitcnt lgkmcnt(0)
	v_max_f32_e32 v7, v7, v7
	v_max_f32_e32 v7, v16, v7
	ds_bpermute_b32 v16, v202, v7
	s_waitcnt lgkmcnt(0)
	v_max3_f32 v7, v195, v7, v16
	v_sub_f32_e32 v16, v195, v7
	v_exp_f32_e32 v16, v16
	v_mov_b32_e32 v195, v7
	v_mul_f32_e32 v204, v204, v16
	v_pk_mul_f32 v[112:113], v[112:113], v[16:17] op_sel_hi:[1,0]
	v_pk_mul_f32 v[110:111], v[110:111], v[16:17] op_sel_hi:[1,0]
	v_pk_mul_f32 v[104:105], v[104:105], v[16:17] op_sel_hi:[1,0]
	v_pk_mul_f32 v[102:103], v[102:103], v[16:17] op_sel_hi:[1,0]
	v_pk_mul_f32 v[96:97], v[96:97], v[16:17] op_sel_hi:[1,0]
	v_pk_mul_f32 v[94:95], v[94:95], v[16:17] op_sel_hi:[1,0]
	v_pk_mul_f32 v[88:89], v[88:89], v[16:17] op_sel_hi:[1,0]
	v_pk_mul_f32 v[86:87], v[86:87], v[16:17] op_sel_hi:[1,0]
	v_pk_mul_f32 v[80:81], v[80:81], v[16:17] op_sel_hi:[1,0]
	v_pk_mul_f32 v[78:79], v[78:79], v[16:17] op_sel_hi:[1,0]
	v_pk_mul_f32 v[68:69], v[68:69], v[16:17] op_sel_hi:[1,0]
	v_pk_mul_f32 v[66:67], v[66:67], v[16:17] op_sel_hi:[1,0]
	v_pk_mul_f32 v[60:61], v[60:61], v[16:17] op_sel_hi:[1,0]
	v_pk_mul_f32 v[58:59], v[58:59], v[16:17] op_sel_hi:[1,0]
	v_pk_mul_f32 v[56:57], v[56:57], v[16:17] op_sel_hi:[1,0]
	v_pk_mul_f32 v[54:55], v[54:55], v[16:17] op_sel_hi:[1,0]
	s_branch .LBB0_629

.LBB0_629:
	v_fma_f32 v16, v130, s72, -v196
	v_fma_f32 v17, v131, s72, -v196
	v_exp_f32_e32 v16, v16
	v_exp_f32_e32 v17, v17
	v_fma_f32 v38, v132, s72, -v196
	v_fma_f32 v39, v133, s72, -v196
	v_exp_f32_e32 v38, v38
	v_exp_f32_e32 v39, v39
	v_fma_f32 v42, v126, s72, -v196
	v_fma_f32 v43, v127, s72, -v196
	v_exp_f32_e32 v42, v42
	v_exp_f32_e32 v43, v43
	v_fma_f32 v44, v128, s72, -v196
	v_fma_f32 v45, v129, s72, -v196
	v_exp_f32_e32 v44, v44
	v_exp_f32_e32 v45, v45
	v_pk_add_f32 v[40:41], v[16:17], 0 op_sel_hi:[1,0]
	v_cvt_pk_bf16_f32 v129, v38, v39
	v_pk_add_f32 v[40:41], v[38:39], v[40:41]
	v_fma_f32 v38, v120, s72, -v195
	v_pk_add_f32 v[40:41], v[42:43], v[40:41]
	v_cvt_pk_bf16_f32 v128, v16, v17
	v_fma_f32 v16, v118, s72, -v195
	v_exp_f32_e32 v118, v38
	v_fma_f32 v38, v121, s72, -v195
	v_pk_add_f32 v[40:41], v[44:45], v[40:41]
	v_fma_f32 v17, v119, s72, -v195
	v_exp_f32_e32 v119, v38
	v_fma_f32 v38, v122, s72, -v195
	v_add_f32_e32 v40, v40, v41
	v_exp_f32_e32 v120, v38
	v_fma_f32 v38, v123, s72, -v195
	v_add_f32_e32 v126, v0, v40
	v_add_u32_e32 v0, s0, v206
	v_exp_f32_e32 v121, v38
	v_fma_f32 v38, v124, s72, -v195
	v_exp_f32_e32 v122, v38
	v_fma_f32 v38, v125, s72, -v195
	v_add_u32_e32 v124, v0, v205
	v_exp_f32_e32 v123, v38
	ds_read_b128 v[38:41], v124 offset:8192
	v_exp_f32_e32 v16, v16
	v_exp_f32_e32 v17, v17
	v_cvt_pk_bf16_f32 v130, v42, v43
	v_cvt_pk_bf16_f32 v131, v44, v45
	v_cvt_pk_bf16_f32 v133, v118, v119
	v_cvt_pk_bf16_f32 v132, v16, v17
	v_cvt_pk_bf16_f32 v134, v120, v121
	v_cvt_pk_bf16_f32 v135, v122, v123
	ds_read_b128 v[42:45], v124 offset:20480
	s_waitcnt lgkmcnt(1)
	v_mfma_f32_16x16x32_bf16 v[114:117], v[38:41], v[128:131], v[114:117]
	v_mfma_f32_16x16x32_bf16 v[110:113], v[38:41], v[132:135], v[110:113]
	ds_read_b128 v[38:41], v124 offset:10240
	s_waitcnt lgkmcnt(0)
	v_mfma_f32_16x16x32_bf16 v[106:109], v[38:41], v[128:131], v[106:109]
	v_mfma_f32_16x16x32_bf16 v[102:105], v[38:41], v[132:135], v[102:105]
	ds_read_b128 v[38:41], v124 offset:12288
	s_waitcnt lgkmcnt(0)
	v_mfma_f32_16x16x32_bf16 v[98:101], v[38:41], v[128:131], v[98:101]
	v_mfma_f32_16x16x32_bf16 v[94:97], v[38:41], v[132:135], v[94:97]
	ds_read_b128 v[38:41], v124 offset:14336
	s_waitcnt lgkmcnt(0)
	v_mfma_f32_16x16x32_bf16 v[90:93], v[38:41], v[128:131], v[90:93]
	v_mfma_f32_16x16x32_bf16 v[86:89], v[38:41], v[132:135], v[86:89]
	ds_read_b128 v[38:41], v124 offset:16384
	s_waitcnt lgkmcnt(0)
	v_mfma_f32_16x16x32_bf16 v[82:85], v[38:41], v[128:131], v[82:85]
	v_mfma_f32_16x16x32_bf16 v[78:81], v[38:41], v[132:135], v[78:81]
	ds_read_b128 v[38:41], v124 offset:18432
	s_waitcnt lgkmcnt(0)
	v_mfma_f32_16x16x32_bf16 v[50:53], v[38:41], v[132:135], v[66:69]
	s_nop 2
	ds_read_b128 v[66:69], v124 offset:22528
	v_mfma_f32_16x16x32_bf16 v[46:49], v[38:41], v[128:131], v[74:77]
	v_mfma_f32_16x16x32_bf16 v[38:41], v[42:45], v[128:131], v[70:73]
	v_mfma_f32_16x16x32_bf16 v[42:45], v[42:45], v[132:135], v[58:61]
	s_waitcnt lgkmcnt(0)
	v_mfma_f32_16x16x32_bf16 v[58:61], v[66:69], v[128:131], v[62:65]
	v_max3_f32 v62, v30, v31, v32
	v_max3_f32 v62, v62, v33, v34
	v_mfma_f32_16x16x32_bf16 v[54:57], v[66:69], v[132:135], v[54:57]
	v_max3_f32 v62, v62, v35, v36
	v_add_f32_e32 v63, 0x41000000, v6
	v_max3_f32 v62, v62, v37, v37
	v_mul_f32_e32 v62, 0x3e38aa3b, v62
	v_cmp_gt_f32_e32 vcc, v62, v63
	s_cbranch_vccz .LBB0_631
	ds_swizzle_b32 v63, v62 offset:swizzle(SWAP,16)
	v_max_f32_e32 v62, v62, v62
	v_mov_b32_e32 v195, v7
	s_waitcnt lgkmcnt(0)
	v_max_f32_e32 v63, v63, v63
	v_max_f32_e32 v62, v62, v63
	ds_bpermute_b32 v63, v202, v62
	s_waitcnt lgkmcnt(0)
	v_max3_f32 v62, v6, v62, v63
	v_sub_f32_e32 v6, v6, v62
	v_exp_f32_e32 v6, v6
	s_nop 0
	v_mul_f32_e32 v126, v126, v6
	v_pk_mul_f32 v[116:117], v[116:117], v[6:7] op_sel_hi:[1,0]
	v_pk_mul_f32 v[114:115], v[114:115], v[6:7] op_sel_hi:[1,0]
	v_pk_mul_f32 v[108:109], v[108:109], v[6:7] op_sel_hi:[1,0]
	v_pk_mul_f32 v[106:107], v[106:107], v[6:7] op_sel_hi:[1,0]
	v_pk_mul_f32 v[100:101], v[100:101], v[6:7] op_sel_hi:[1,0]
	v_pk_mul_f32 v[98:99], v[98:99], v[6:7] op_sel_hi:[1,0]
	v_pk_mul_f32 v[92:93], v[92:93], v[6:7] op_sel_hi:[1,0]
	v_pk_mul_f32 v[90:91], v[90:91], v[6:7] op_sel_hi:[1,0]
	v_pk_mul_f32 v[84:85], v[84:85], v[6:7] op_sel_hi:[1,0]
	v_pk_mul_f32 v[82:83], v[82:83], v[6:7] op_sel_hi:[1,0]
	v_pk_mul_f32 v[48:49], v[48:49], v[6:7] op_sel_hi:[1,0]
	v_pk_mul_f32 v[46:47], v[46:47], v[6:7] op_sel_hi:[1,0]
	v_pk_mul_f32 v[40:41], v[40:41], v[6:7] op_sel_hi:[1,0]
	v_pk_mul_f32 v[38:39], v[38:39], v[6:7] op_sel_hi:[1,0]
	v_pk_mul_f32 v[60:61], v[60:61], v[6:7] op_sel_hi:[1,0]
	v_pk_mul_f32 v[58:59], v[58:59], v[6:7] op_sel_hi:[1,0]
	v_mov_b32_e32 v6, v62
.LBB0_631:
	v_pk_add_f32 v[16:17], v[16:17], 0 op_sel_hi:[1,0]
	s_nop 0
	v_pk_add_f32 v[16:17], v[118:119], v[16:17]
	s_nop 0
	v_pk_add_f32 v[16:17], v[120:121], v[16:17]
	s_nop 0
	v_pk_add_f32 v[16:17], v[122:123], v[16:17]
	s_nop 0
	v_add_f32_e32 v7, v16, v17
	v_max3_f32 v16, v2, v3, v4
	v_add_f32_e32 v17, 0x41000000, v195
	v_max3_f32 v16, v16, v5, v26
	v_add_f32_e32 v7, v204, v7
	v_max3_f32 v16, v16, v27, v28
	v_max3_f32 v16, v16, v29, v29
	v_mul_f32_e32 v16, 0x3e38aa3b, v16
	v_cmp_gt_f32_e32 vcc, v16, v17
	s_cbranch_vccz .LBB0_512
	ds_swizzle_b32 v17, v16 offset:swizzle(SWAP,16)
	v_max_f32_e32 v16, v16, v16
	s_waitcnt lgkmcnt(0)
	v_max_f32_e32 v17, v17, v17
	v_max_f32_e32 v16, v16, v17
	ds_bpermute_b32 v17, v202, v16
	s_waitcnt lgkmcnt(0)
	v_max3_f32 v17, v195, v16, v17
	v_sub_f32_e32 v16, v195, v17
	v_exp_f32_e32 v16, v16
	v_mov_b32_e32 v195, v17
	v_mul_f32_e32 v7, v7, v16
	v_pk_mul_f32 v[112:113], v[112:113], v[16:17] op_sel_hi:[1,0]
	v_pk_mul_f32 v[110:111], v[110:111], v[16:17] op_sel_hi:[1,0]
	v_pk_mul_f32 v[104:105], v[104:105], v[16:17] op_sel_hi:[1,0]
	v_pk_mul_f32 v[102:103], v[102:103], v[16:17] op_sel_hi:[1,0]
	v_pk_mul_f32 v[96:97], v[96:97], v[16:17] op_sel_hi:[1,0]
	v_pk_mul_f32 v[94:95], v[94:95], v[16:17] op_sel_hi:[1,0]
	v_pk_mul_f32 v[88:89], v[88:89], v[16:17] op_sel_hi:[1,0]
	v_pk_mul_f32 v[86:87], v[86:87], v[16:17] op_sel_hi:[1,0]
	v_pk_mul_f32 v[80:81], v[80:81], v[16:17] op_sel_hi:[1,0]
	v_pk_mul_f32 v[78:79], v[78:79], v[16:17] op_sel_hi:[1,0]
	v_pk_mul_f32 v[52:53], v[52:53], v[16:17] op_sel_hi:[1,0]
	v_pk_mul_f32 v[50:51], v[50:51], v[16:17] op_sel_hi:[1,0]
	v_pk_mul_f32 v[44:45], v[44:45], v[16:17] op_sel_hi:[1,0]
	v_pk_mul_f32 v[42:43], v[42:43], v[16:17] op_sel_hi:[1,0]
	v_pk_mul_f32 v[56:57], v[56:57], v[16:17] op_sel_hi:[1,0]
	v_pk_mul_f32 v[54:55], v[54:55], v[16:17] op_sel_hi:[1,0]
	s_branch .LBB0_512
